# MFMA issue order within each 16-MFMA block rearranged so consecutive MFMAs share one operand (all fp8 GEMM loops)
# speedup vs baseline: 1.0054x; 1.0054x over previous
.LBB0_197:
	s_ashr_i32 s47, s46, 31
	ds_read_b128 v[18:21], v190
	ds_read_b128 v[22:25], v190 offset:1024
	ds_read_b128 v[26:29], v190 offset:2048
	ds_read_b128 v[30:33], v190 offset:3072
	ds_read_b128 v[2:5], v190 offset:16384
	ds_read_b128 v[6:9], v190 offset:17408
	ds_read_b128 v[10:13], v190 offset:18432
	ds_read_b128 v[14:17], v190 offset:19456
	s_lshl_b64 s[8:9], s[46:47], 20
	s_add_u32 s48, s22, s8
	s_addc_u32 s49, s23, s9
	s_and_b64 s[8:9], s[2:3], exec
	s_cselect_b32 s47, s49, s73
	s_cselect_b32 s70, s48, s72
	s_ashr_i32 s45, s44, 31
	s_lshl_b64 s[8:9], s[44:45], 20
	s_add_u32 s50, s27, s8
	s_addc_u32 s51, s68, s9
	s_and_b64 s[8:9], s[2:3], exec
	s_cselect_b32 s45, s51, s55
	s_cselect_b32 s71, s50, s54
	s_add_u32 s8, s72, 0x80080
	s_addc_u32 s9, s73, 0
	s_mov_b32 m0, s92
	v_lshl_add_u64 v[216:217], s[8:9], 0, v[164:165]
	ds_read_b128 v[180:183], v191
	ds_read_b128 v[184:187], v191 offset:1024
	ds_read_b128 v[192:195], v191 offset:2048
	ds_read_b128 v[196:199], v191 offset:3072
	ds_read_b128 v[200:203], v191 offset:4096
	ds_read_b128 v[204:207], v191 offset:5120
	ds_read_b128 v[208:211], v191 offset:6144
	ds_read_b128 v[212:215], v191 offset:7168
	global_load_lds_dwordx4 v[216:217], off
	v_lshl_add_u64 v[216:217], s[8:9], 0, v[168:169]
	s_mov_b32 m0, s93
	s_nop 0
	global_load_lds_dwordx4 v[216:217], off
	s_waitcnt vmcnt(8)
	s_waitcnt lgkmcnt(0)
	s_barrier
	s_setprio 1
	s_waitcnt lgkmcnt(0)
	v_mfma_scale_f32_16x16x128_f8f6f4 v[158:161], v[18:25], v[180:187], 0, v189, v189 op_sel_hi:[0,0,0]
	v_mfma_scale_f32_16x16x128_f8f6f4 v[154:157], v[26:33], v[180:187], 0, v189, v189 op_sel_hi:[0,0,0]
	v_mfma_scale_f32_16x16x128_f8f6f4 v[146:149], v[26:33], v[192:199], 0, v189, v189 op_sel_hi:[0,0,0]
	v_mfma_scale_f32_16x16x128_f8f6f4 v[150:153], v[18:25], v[192:199], 0, v189, v189 op_sel_hi:[0,0,0]
	v_mfma_scale_f32_16x16x128_f8f6f4 v[142:145], v[18:25], v[200:207], 0, v189, v189 op_sel_hi:[0,0,0]
	v_mfma_scale_f32_16x16x128_f8f6f4 v[138:141], v[26:33], v[200:207], 0, v189, v189 op_sel_hi:[0,0,0]
	v_mfma_scale_f32_16x16x128_f8f6f4 v[130:133], v[26:33], v[208:215], 0, v189, v189 op_sel_hi:[0,0,0]
	v_mfma_scale_f32_16x16x128_f8f6f4 v[134:137], v[18:25], v[208:215], 0, v189, v189 op_sel_hi:[0,0,0]
	s_setprio 0
	s_setprio 1
	v_mfma_scale_f32_16x16x128_f8f6f4 v[102:105], v[2:9], v[208:215], 0, v189, v189 op_sel_hi:[0,0,0]
	v_mfma_scale_f32_16x16x128_f8f6f4 v[98:101], v[10:17], v[208:215], 0, v189, v189 op_sel_hi:[0,0,0]
	v_mfma_scale_f32_16x16x128_f8f6f4 v[106:109], v[10:17], v[200:207], 0, v189, v189 op_sel_hi:[0,0,0]
	v_mfma_scale_f32_16x16x128_f8f6f4 v[110:113], v[2:9], v[200:207], 0, v189, v189 op_sel_hi:[0,0,0]
	v_mfma_scale_f32_16x16x128_f8f6f4 v[118:121], v[2:9], v[192:199], 0, v189, v189 op_sel_hi:[0,0,0]
	v_mfma_scale_f32_16x16x128_f8f6f4 v[114:117], v[10:17], v[192:199], 0, v189, v189 op_sel_hi:[0,0,0]
	v_mfma_scale_f32_16x16x128_f8f6f4 v[122:125], v[10:17], v[180:187], 0, v189, v189 op_sel_hi:[0,0,0]
	v_mfma_scale_f32_16x16x128_f8f6f4 v[126:129], v[2:9], v[180:187], 0, v189, v189 op_sel_hi:[0,0,0]
	s_setprio 0
	s_barrier
	v_lshl_add_u64 v[180:181], s[54:55], 0, v[166:167]
	s_mov_b32 m0, s77
	v_lshl_add_u64 v[182:183], v[180:181], 0, s[16:17]
	ds_read_b128 v[192:195], v191 offset:16384
	ds_read_b128 v[196:199], v191 offset:17408
	ds_read_b128 v[200:203], v191 offset:18432
	ds_read_b128 v[204:207], v191 offset:19456
	ds_read_b128 v[208:211], v191 offset:20480
	ds_read_b128 v[212:215], v191 offset:21504
	ds_read_b128 v[216:219], v191 offset:22528
	ds_read_b128 v[220:223], v191 offset:23552
	global_load_lds_dwordx4 v[182:183], off
	v_lshl_add_u64 v[182:183], s[54:55], 0, v[170:171]
	s_add_u32 s8, s54, 0x80100
	v_lshl_add_u64 v[184:185], v[182:183], 0, s[16:17]
	s_mov_b32 m0, s78
	s_addc_u32 s9, s55, 0
	global_load_lds_dwordx4 v[184:185], off
	v_lshl_add_u64 v[184:185], s[8:9], 0, v[166:167]
	s_mov_b32 m0, s79
	s_nop 0
	global_load_lds_dwordx4 v[184:185], off
	v_lshl_add_u64 v[184:185], s[8:9], 0, v[170:171]
	s_mov_b32 m0, s80
	s_nop 0
	global_load_lds_dwordx4 v[184:185], off
	v_lshl_add_u64 v[184:185], s[72:73], 0, v[164:165]
	v_lshl_add_u64 v[186:187], v[184:185], 0, s[16:17]
	s_mov_b32 m0, s53
	s_nop 0
	global_load_lds_dwordx4 v[186:187], off
	v_lshl_add_u64 v[186:187], s[72:73], 0, v[168:169]
	v_lshl_add_u64 v[224:225], v[186:187], 0, s[16:17]
	s_mov_b32 m0, s81
	s_nop 0
	global_load_lds_dwordx4 v[224:225], off
	s_waitcnt vmcnt(8)
	s_waitcnt lgkmcnt(0)
	s_barrier
	s_setprio 1
	s_waitcnt lgkmcnt(0)
	v_mfma_scale_f32_16x16x128_f8f6f4 v[94:97], v[18:25], v[192:199], 0, v189, v189 op_sel_hi:[0,0,0]
	v_mfma_scale_f32_16x16x128_f8f6f4 v[90:93], v[26:33], v[192:199], 0, v189, v189 op_sel_hi:[0,0,0]
	v_mfma_scale_f32_16x16x128_f8f6f4 v[82:85], v[26:33], v[200:207], 0, v189, v189 op_sel_hi:[0,0,0]
	v_mfma_scale_f32_16x16x128_f8f6f4 v[86:89], v[18:25], v[200:207], 0, v189, v189 op_sel_hi:[0,0,0]
	v_mfma_scale_f32_16x16x128_f8f6f4 v[78:81], v[18:25], v[208:215], 0, v189, v189 op_sel_hi:[0,0,0]
	v_mfma_scale_f32_16x16x128_f8f6f4 v[74:77], v[26:33], v[208:215], 0, v189, v189 op_sel_hi:[0,0,0]
	v_mfma_scale_f32_16x16x128_f8f6f4 v[66:69], v[26:33], v[216:223], 0, v189, v189 op_sel_hi:[0,0,0]
	v_mfma_scale_f32_16x16x128_f8f6f4 v[70:73], v[18:25], v[216:223], 0, v189, v189 op_sel_hi:[0,0,0]
	s_setprio 0
	s_setprio 1
	v_mfma_scale_f32_16x16x128_f8f6f4 v[38:41], v[2:9], v[216:223], 0, v189, v189 op_sel_hi:[0,0,0]
	v_mfma_scale_f32_16x16x128_f8f6f4 v[34:37], v[10:17], v[216:223], 0, v189, v189 op_sel_hi:[0,0,0]
	v_mfma_scale_f32_16x16x128_f8f6f4 v[42:45], v[10:17], v[208:215], 0, v189, v189 op_sel_hi:[0,0,0]
	v_mfma_scale_f32_16x16x128_f8f6f4 v[46:49], v[2:9], v[208:215], 0, v189, v189 op_sel_hi:[0,0,0]
	v_mfma_scale_f32_16x16x128_f8f6f4 v[54:57], v[2:9], v[200:207], 0, v189, v189 op_sel_hi:[0,0,0]
	v_mfma_scale_f32_16x16x128_f8f6f4 v[50:53], v[10:17], v[200:207], 0, v189, v189 op_sel_hi:[0,0,0]
	v_mfma_scale_f32_16x16x128_f8f6f4 v[58:61], v[10:17], v[192:199], 0, v189, v189 op_sel_hi:[0,0,0]
	v_mfma_scale_f32_16x16x128_f8f6f4 v[62:65], v[2:9], v[192:199], 0, v189, v189 op_sel_hi:[0,0,0]
	s_setprio 0
	s_barrier
	ds_read_b128 v[18:21], v190 offset:32768
	ds_read_b128 v[22:25], v190 offset:33792
	ds_read_b128 v[26:29], v190 offset:34816
	ds_read_b128 v[30:33], v190 offset:35840
	ds_read_b128 v[2:5], v190 offset:49152
	ds_read_b128 v[6:9], v190 offset:50176
	ds_read_b128 v[10:13], v190 offset:51200
	ds_read_b128 v[14:17], v190 offset:52224
	s_add_u32 s8, s72, 0x80100
	s_addc_u32 s9, s73, 0
	s_mov_b32 m0, s82
	v_lshl_add_u64 v[224:225], s[8:9], 0, v[164:165]
	ds_read_b128 v[192:195], v191 offset:32768
	ds_read_b128 v[196:199], v191 offset:33792
	ds_read_b128 v[200:203], v191 offset:34816
	ds_read_b128 v[204:207], v191 offset:35840
	ds_read_b128 v[208:211], v191 offset:36864
	ds_read_b128 v[212:215], v191 offset:37888
	ds_read_b128 v[216:219], v191 offset:38912
	ds_read_b128 v[220:223], v191 offset:39936
	global_load_lds_dwordx4 v[224:225], off
	v_lshl_add_u64 v[224:225], s[8:9], 0, v[168:169]
	s_mov_b32 m0, s83
	s_nop 0
	global_load_lds_dwordx4 v[224:225], off
	s_waitcnt vmcnt(8)
	s_waitcnt lgkmcnt(0)
	s_barrier
	s_setprio 1
	s_waitcnt lgkmcnt(0)
	v_mfma_scale_f32_16x16x128_f8f6f4 v[158:161], v[18:25], v[192:199], v[158:161], v189, v189 op_sel_hi:[0,0,0]
	v_mfma_scale_f32_16x16x128_f8f6f4 v[154:157], v[26:33], v[192:199], v[154:157], v189, v189 op_sel_hi:[0,0,0]
	v_mfma_scale_f32_16x16x128_f8f6f4 v[146:149], v[26:33], v[200:207], v[146:149], v189, v189 op_sel_hi:[0,0,0]
	v_mfma_scale_f32_16x16x128_f8f6f4 v[150:153], v[18:25], v[200:207], v[150:153], v189, v189 op_sel_hi:[0,0,0]
	v_mfma_scale_f32_16x16x128_f8f6f4 v[142:145], v[18:25], v[208:215], v[142:145], v189, v189 op_sel_hi:[0,0,0]
	v_mfma_scale_f32_16x16x128_f8f6f4 v[138:141], v[26:33], v[208:215], v[138:141], v189, v189 op_sel_hi:[0,0,0]
	v_mfma_scale_f32_16x16x128_f8f6f4 v[130:133], v[26:33], v[216:223], v[130:133], v189, v189 op_sel_hi:[0,0,0]
	v_mfma_scale_f32_16x16x128_f8f6f4 v[134:137], v[18:25], v[216:223], v[134:137], v189, v189 op_sel_hi:[0,0,0]
	s_setprio 0
	s_setprio 1
	v_mfma_scale_f32_16x16x128_f8f6f4 v[102:105], v[2:9], v[216:223], v[102:105], v189, v189 op_sel_hi:[0,0,0]
	v_mfma_scale_f32_16x16x128_f8f6f4 v[98:101], v[10:17], v[216:223], v[98:101], v189, v189 op_sel_hi:[0,0,0]
	v_mfma_scale_f32_16x16x128_f8f6f4 v[106:109], v[10:17], v[208:215], v[106:109], v189, v189 op_sel_hi:[0,0,0]
	v_mfma_scale_f32_16x16x128_f8f6f4 v[110:113], v[2:9], v[208:215], v[110:113], v189, v189 op_sel_hi:[0,0,0]
	v_mfma_scale_f32_16x16x128_f8f6f4 v[118:121], v[2:9], v[200:207], v[118:121], v189, v189 op_sel_hi:[0,0,0]
	v_mfma_scale_f32_16x16x128_f8f6f4 v[114:117], v[10:17], v[200:207], v[114:117], v189, v189 op_sel_hi:[0,0,0]
	v_mfma_scale_f32_16x16x128_f8f6f4 v[122:125], v[10:17], v[192:199], v[122:125], v189, v189 op_sel_hi:[0,0,0]
	v_mfma_scale_f32_16x16x128_f8f6f4 v[126:129], v[2:9], v[192:199], v[126:129], v189, v189 op_sel_hi:[0,0,0]
	s_setprio 0
	s_barrier
	s_mov_b32 m0, s86
	v_lshl_add_u64 v[180:181], v[180:181], 0, s[20:21]
	s_add_u32 s8, s54, 0x80180
	ds_read_b128 v[192:195], v191 offset:49152
	ds_read_b128 v[196:199], v191 offset:50176
	ds_read_b128 v[200:203], v191 offset:51200
	ds_read_b128 v[204:207], v191 offset:52224
	ds_read_b128 v[208:211], v191 offset:53248
	ds_read_b128 v[212:215], v191 offset:54272
	ds_read_b128 v[216:219], v191 offset:55296
	ds_read_b128 v[220:223], v191 offset:56320
	global_load_lds_dwordx4 v[180:181], off
	v_lshl_add_u64 v[180:181], v[182:183], 0, s[20:21]
	s_mov_b32 m0, s87
	s_addc_u32 s9, s55, 0
	global_load_lds_dwordx4 v[180:181], off
	v_lshl_add_u64 v[180:181], s[8:9], 0, v[166:167]
	s_mov_b32 m0, s90
	s_nop 0
	global_load_lds_dwordx4 v[180:181], off
	v_lshl_add_u64 v[180:181], s[8:9], 0, v[170:171]
	s_mov_b32 m0, s91
	s_nop 0
	global_load_lds_dwordx4 v[180:181], off
	v_lshl_add_u64 v[180:181], v[184:185], 0, s[20:21]
	s_mov_b32 m0, s88
	s_nop 0
	global_load_lds_dwordx4 v[180:181], off
	v_lshl_add_u64 v[180:181], v[186:187], 0, s[20:21]
	s_mov_b32 m0, s89
	s_nop 0
	global_load_lds_dwordx4 v[180:181], off
	s_waitcnt vmcnt(8)
	s_waitcnt lgkmcnt(0)
	s_barrier
	s_setprio 1
	s_waitcnt lgkmcnt(0)
	v_mfma_scale_f32_16x16x128_f8f6f4 v[94:97], v[18:25], v[192:199], v[94:97], v189, v189 op_sel_hi:[0,0,0]
	v_mfma_scale_f32_16x16x128_f8f6f4 v[90:93], v[26:33], v[192:199], v[90:93], v189, v189 op_sel_hi:[0,0,0]
	v_mfma_scale_f32_16x16x128_f8f6f4 v[82:85], v[26:33], v[200:207], v[82:85], v189, v189 op_sel_hi:[0,0,0]
	v_mfma_scale_f32_16x16x128_f8f6f4 v[86:89], v[18:25], v[200:207], v[86:89], v189, v189 op_sel_hi:[0,0,0]
	v_mfma_scale_f32_16x16x128_f8f6f4 v[78:81], v[18:25], v[208:215], v[78:81], v189, v189 op_sel_hi:[0,0,0]
	v_mfma_scale_f32_16x16x128_f8f6f4 v[74:77], v[26:33], v[208:215], v[74:77], v189, v189 op_sel_hi:[0,0,0]
	v_mfma_scale_f32_16x16x128_f8f6f4 v[66:69], v[26:33], v[216:223], v[66:69], v189, v189 op_sel_hi:[0,0,0]
	v_mfma_scale_f32_16x16x128_f8f6f4 v[70:73], v[18:25], v[216:223], v[70:73], v189, v189 op_sel_hi:[0,0,0]
	s_setprio 0
	s_setprio 1
	v_mfma_scale_f32_16x16x128_f8f6f4 v[38:41], v[2:9], v[216:223], v[38:41], v189, v189 op_sel_hi:[0,0,0]
	v_mfma_scale_f32_16x16x128_f8f6f4 v[34:37], v[10:17], v[216:223], v[34:37], v189, v189 op_sel_hi:[0,0,0]
	v_mfma_scale_f32_16x16x128_f8f6f4 v[42:45], v[10:17], v[208:215], v[42:45], v189, v189 op_sel_hi:[0,0,0]
	v_mfma_scale_f32_16x16x128_f8f6f4 v[46:49], v[2:9], v[208:215], v[46:49], v189, v189 op_sel_hi:[0,0,0]
	v_mfma_scale_f32_16x16x128_f8f6f4 v[54:57], v[2:9], v[200:207], v[54:57], v189, v189 op_sel_hi:[0,0,0]
	v_mfma_scale_f32_16x16x128_f8f6f4 v[50:53], v[10:17], v[200:207], v[50:53], v189, v189 op_sel_hi:[0,0,0]
	v_mfma_scale_f32_16x16x128_f8f6f4 v[58:61], v[10:17], v[192:199], v[58:61], v189, v189 op_sel_hi:[0,0,0]
	v_mfma_scale_f32_16x16x128_f8f6f4 v[62:65], v[2:9], v[192:199], v[62:65], v189, v189 op_sel_hi:[0,0,0]
	s_setprio 0
	s_barrier
	s_add_u32 s72, s72, 0x80180
	s_addc_u32 s73, s73, 0
	s_add_u32 s8, s54, 0x200
	s_addc_u32 s9, s55, 0
	s_mov_b32 s62, 0
.LBB0_198:
	ds_read_b128 v[2:5], v190
	ds_read_b128 v[6:9], v190 offset:1024
	ds_read_b128 v[18:21], v190 offset:2048
	ds_read_b128 v[22:25], v190 offset:3072
	ds_read_b128 v[26:29], v190 offset:16384
	ds_read_b128 v[30:33], v190 offset:17408
	ds_read_b128 v[180:183], v190 offset:18432
	ds_read_b128 v[184:187], v190 offset:19456
	s_add_u32 s54, s72, 0xfff80080
	s_addc_u32 s55, s73, -1
	s_cmp_eq_u32 s62, 28
	s_cselect_b32 s75, s47, s55
	s_cselect_b32 s74, s70, s54
	s_cselect_b32 s55, s45, s9
	s_cselect_b32 s54, s71, s8
	s_mov_b32 m0, s92
	v_lshl_add_u64 v[216:217], s[72:73], 0, v[172:173]
	ds_read_b128 v[10:13], v191
	ds_read_b128 v[14:17], v191 offset:1024
	ds_read_b128 v[192:195], v191 offset:2048
	ds_read_b128 v[196:199], v191 offset:3072
	ds_read_b128 v[200:203], v191 offset:4096
	ds_read_b128 v[204:207], v191 offset:5120
	ds_read_b128 v[208:211], v191 offset:6144
	ds_read_b128 v[212:215], v191 offset:7168
	global_load_lds_dwordx4 v[216:217], off
	v_lshl_add_u64 v[216:217], s[72:73], 0, v[174:175]
	s_mov_b32 m0, s93
	s_nop 0
	global_load_lds_dwordx4 v[216:217], off
	s_waitcnt vmcnt(8)
	s_waitcnt lgkmcnt(0)
	s_barrier
	s_setprio 1
	s_waitcnt lgkmcnt(0)
	v_mfma_scale_f32_16x16x128_f8f6f4 v[158:161], v[2:9], v[10:17], v[158:161], v189, v189 op_sel_hi:[0,0,0]
	v_mfma_scale_f32_16x16x128_f8f6f4 v[154:157], v[18:25], v[10:17], v[154:157], v189, v189 op_sel_hi:[0,0,0]
	v_mfma_scale_f32_16x16x128_f8f6f4 v[146:149], v[18:25], v[192:199], v[146:149], v189, v189 op_sel_hi:[0,0,0]
	v_mfma_scale_f32_16x16x128_f8f6f4 v[150:153], v[2:9], v[192:199], v[150:153], v189, v189 op_sel_hi:[0,0,0]
	v_mfma_scale_f32_16x16x128_f8f6f4 v[142:145], v[2:9], v[200:207], v[142:145], v189, v189 op_sel_hi:[0,0,0]
	v_mfma_scale_f32_16x16x128_f8f6f4 v[138:141], v[18:25], v[200:207], v[138:141], v189, v189 op_sel_hi:[0,0,0]
	v_mfma_scale_f32_16x16x128_f8f6f4 v[130:133], v[18:25], v[208:215], v[130:133], v189, v189 op_sel_hi:[0,0,0]
	v_mfma_scale_f32_16x16x128_f8f6f4 v[134:137], v[2:9], v[208:215], v[134:137], v189, v189 op_sel_hi:[0,0,0]
	s_setprio 0
	s_setprio 1
	v_mfma_scale_f32_16x16x128_f8f6f4 v[102:105], v[26:33], v[208:215], v[102:105], v189, v189 op_sel_hi:[0,0,0]
	v_mfma_scale_f32_16x16x128_f8f6f4 v[98:101], v[180:187], v[208:215], v[98:101], v189, v189 op_sel_hi:[0,0,0]
	v_mfma_scale_f32_16x16x128_f8f6f4 v[106:109], v[180:187], v[200:207], v[106:109], v189, v189 op_sel_hi:[0,0,0]
	v_mfma_scale_f32_16x16x128_f8f6f4 v[110:113], v[26:33], v[200:207], v[110:113], v189, v189 op_sel_hi:[0,0,0]
	v_mfma_scale_f32_16x16x128_f8f6f4 v[118:121], v[26:33], v[192:199], v[118:121], v189, v189 op_sel_hi:[0,0,0]
	v_mfma_scale_f32_16x16x128_f8f6f4 v[114:117], v[180:187], v[192:199], v[114:117], v189, v189 op_sel_hi:[0,0,0]
	v_mfma_scale_f32_16x16x128_f8f6f4 v[122:125], v[180:187], v[10:17], v[122:125], v189, v189 op_sel_hi:[0,0,0]
	v_mfma_scale_f32_16x16x128_f8f6f4 v[126:129], v[26:33], v[10:17], v[126:129], v189, v189 op_sel_hi:[0,0,0]
	s_setprio 0
	s_barrier
	s_mov_b32 m0, s77
	v_lshl_add_u64 v[10:11], s[54:55], 0, v[166:167]
	s_add_u32 vcc_lo, s54, 0x80000
	ds_read_b128 v[192:195], v191 offset:16384
	ds_read_b128 v[196:199], v191 offset:17408
	ds_read_b128 v[200:203], v191 offset:18432
	ds_read_b128 v[204:207], v191 offset:19456
	ds_read_b128 v[208:211], v191 offset:20480
	ds_read_b128 v[212:215], v191 offset:21504
	ds_read_b128 v[216:219], v191 offset:22528
	ds_read_b128 v[220:223], v191 offset:23552
	global_load_lds_dwordx4 v[10:11], off
	v_lshl_add_u64 v[12:13], s[54:55], 0, v[170:171]
	s_mov_b32 m0, s78
	s_addc_u32 vcc_hi, s55, 0
	global_load_lds_dwordx4 v[12:13], off
	v_lshl_add_u64 v[14:15], vcc, 0, v[166:167]
	s_mov_b32 m0, s79
	v_lshl_add_u64 v[16:17], s[74:75], 0, v[168:169]
	global_load_lds_dwordx4 v[14:15], off
	v_lshl_add_u64 v[14:15], vcc, 0, v[170:171]
	s_mov_b32 m0, s80
	s_nop 0
	global_load_lds_dwordx4 v[14:15], off
	v_lshl_add_u64 v[14:15], s[74:75], 0, v[164:165]
	s_mov_b32 m0, s53
	s_nop 0
	global_load_lds_dwordx4 v[14:15], off
	s_mov_b32 m0, s81
	s_nop 0
	global_load_lds_dwordx4 v[16:17], off
	s_waitcnt vmcnt(8)
	s_waitcnt lgkmcnt(0)
	s_barrier
	s_setprio 1
	s_waitcnt lgkmcnt(0)
	v_mfma_scale_f32_16x16x128_f8f6f4 v[94:97], v[2:9], v[192:199], v[94:97], v189, v189 op_sel_hi:[0,0,0]
	v_mfma_scale_f32_16x16x128_f8f6f4 v[90:93], v[18:25], v[192:199], v[90:93], v189, v189 op_sel_hi:[0,0,0]
	v_mfma_scale_f32_16x16x128_f8f6f4 v[82:85], v[18:25], v[200:207], v[82:85], v189, v189 op_sel_hi:[0,0,0]
	v_mfma_scale_f32_16x16x128_f8f6f4 v[86:89], v[2:9], v[200:207], v[86:89], v189, v189 op_sel_hi:[0,0,0]
	v_mfma_scale_f32_16x16x128_f8f6f4 v[78:81], v[2:9], v[208:215], v[78:81], v189, v189 op_sel_hi:[0,0,0]
	v_mfma_scale_f32_16x16x128_f8f6f4 v[74:77], v[18:25], v[208:215], v[74:77], v189, v189 op_sel_hi:[0,0,0]
	v_mfma_scale_f32_16x16x128_f8f6f4 v[66:69], v[18:25], v[216:223], v[66:69], v189, v189 op_sel_hi:[0,0,0]
	v_mfma_scale_f32_16x16x128_f8f6f4 v[70:73], v[2:9], v[216:223], v[70:73], v189, v189 op_sel_hi:[0,0,0]
	s_setprio 0
	s_setprio 1
	v_mfma_scale_f32_16x16x128_f8f6f4 v[38:41], v[26:33], v[216:223], v[38:41], v189, v189 op_sel_hi:[0,0,0]
	v_mfma_scale_f32_16x16x128_f8f6f4 v[34:37], v[180:187], v[216:223], v[34:37], v189, v189 op_sel_hi:[0,0,0]
	v_mfma_scale_f32_16x16x128_f8f6f4 v[42:45], v[180:187], v[208:215], v[42:45], v189, v189 op_sel_hi:[0,0,0]
	v_mfma_scale_f32_16x16x128_f8f6f4 v[46:49], v[26:33], v[208:215], v[46:49], v189, v189 op_sel_hi:[0,0,0]
	v_mfma_scale_f32_16x16x128_f8f6f4 v[54:57], v[26:33], v[200:207], v[54:57], v189, v189 op_sel_hi:[0,0,0]
	v_mfma_scale_f32_16x16x128_f8f6f4 v[50:53], v[180:187], v[200:207], v[50:53], v189, v189 op_sel_hi:[0,0,0]
	v_mfma_scale_f32_16x16x128_f8f6f4 v[58:61], v[180:187], v[192:199], v[58:61], v189, v189 op_sel_hi:[0,0,0]
	v_mfma_scale_f32_16x16x128_f8f6f4 v[62:65], v[26:33], v[192:199], v[62:65], v189, v189 op_sel_hi:[0,0,0]
	s_setprio 0
	s_barrier
	ds_read_b128 v[18:21], v190 offset:32768
	ds_read_b128 v[22:25], v190 offset:33792
	ds_read_b128 v[26:29], v190 offset:34816
	ds_read_b128 v[30:33], v190 offset:35840
	ds_read_b128 v[2:5], v190 offset:49152
	ds_read_b128 v[6:9], v190 offset:50176
	ds_read_b128 v[180:183], v190 offset:51200
	ds_read_b128 v[184:187], v190 offset:52224
	s_add_u32 s74, s74, 0x80000
	s_addc_u32 s75, s75, 0
	s_mov_b32 m0, s82
	v_lshl_add_u64 v[224:225], s[74:75], 0, v[164:165]
	ds_read_b128 v[192:195], v191 offset:32768
	ds_read_b128 v[196:199], v191 offset:33792
	ds_read_b128 v[200:203], v191 offset:34816
	ds_read_b128 v[204:207], v191 offset:35840
	ds_read_b128 v[208:211], v191 offset:36864
	ds_read_b128 v[212:215], v191 offset:37888
	ds_read_b128 v[216:219], v191 offset:38912
	ds_read_b128 v[220:223], v191 offset:39936
	global_load_lds_dwordx4 v[224:225], off
	v_lshl_add_u64 v[224:225], s[74:75], 0, v[168:169]
	s_mov_b32 m0, s83
	s_nop 0
	global_load_lds_dwordx4 v[224:225], off
	s_waitcnt vmcnt(8)
	s_waitcnt lgkmcnt(0)
	s_barrier
	s_setprio 1
	s_waitcnt lgkmcnt(0)
	v_mfma_scale_f32_16x16x128_f8f6f4 v[158:161], v[18:25], v[192:199], v[158:161], v189, v189 op_sel_hi:[0,0,0]
	v_mfma_scale_f32_16x16x128_f8f6f4 v[154:157], v[26:33], v[192:199], v[154:157], v189, v189 op_sel_hi:[0,0,0]
	v_mfma_scale_f32_16x16x128_f8f6f4 v[146:149], v[26:33], v[200:207], v[146:149], v189, v189 op_sel_hi:[0,0,0]
	v_mfma_scale_f32_16x16x128_f8f6f4 v[150:153], v[18:25], v[200:207], v[150:153], v189, v189 op_sel_hi:[0,0,0]
	v_mfma_scale_f32_16x16x128_f8f6f4 v[142:145], v[18:25], v[208:215], v[142:145], v189, v189 op_sel_hi:[0,0,0]
	v_mfma_scale_f32_16x16x128_f8f6f4 v[138:141], v[26:33], v[208:215], v[138:141], v189, v189 op_sel_hi:[0,0,0]
	v_mfma_scale_f32_16x16x128_f8f6f4 v[130:133], v[26:33], v[216:223], v[130:133], v189, v189 op_sel_hi:[0,0,0]
	v_mfma_scale_f32_16x16x128_f8f6f4 v[134:137], v[18:25], v[216:223], v[134:137], v189, v189 op_sel_hi:[0,0,0]
	s_setprio 0
	s_setprio 1
	v_mfma_scale_f32_16x16x128_f8f6f4 v[102:105], v[2:9], v[216:223], v[102:105], v189, v189 op_sel_hi:[0,0,0]
	v_mfma_scale_f32_16x16x128_f8f6f4 v[98:101], v[180:187], v[216:223], v[98:101], v189, v189 op_sel_hi:[0,0,0]
	v_mfma_scale_f32_16x16x128_f8f6f4 v[106:109], v[180:187], v[208:215], v[106:109], v189, v189 op_sel_hi:[0,0,0]
	v_mfma_scale_f32_16x16x128_f8f6f4 v[110:113], v[2:9], v[208:215], v[110:113], v189, v189 op_sel_hi:[0,0,0]
	v_mfma_scale_f32_16x16x128_f8f6f4 v[118:121], v[2:9], v[200:207], v[118:121], v189, v189 op_sel_hi:[0,0,0]
	v_mfma_scale_f32_16x16x128_f8f6f4 v[114:117], v[180:187], v[200:207], v[114:117], v189, v189 op_sel_hi:[0,0,0]
	v_mfma_scale_f32_16x16x128_f8f6f4 v[122:125], v[180:187], v[192:199], v[122:125], v189, v189 op_sel_hi:[0,0,0]
	v_mfma_scale_f32_16x16x128_f8f6f4 v[126:129], v[2:9], v[192:199], v[126:129], v189, v189 op_sel_hi:[0,0,0]
	s_setprio 0
	s_barrier
	s_mov_b32 m0, s86
	v_lshl_add_u64 v[10:11], v[10:11], 0, s[4:5]
	s_add_u32 s54, s54, 0x80080
	ds_read_b128 v[192:195], v191 offset:49152
	ds_read_b128 v[196:199], v191 offset:50176
	ds_read_b128 v[200:203], v191 offset:51200
	ds_read_b128 v[204:207], v191 offset:52224
	ds_read_b128 v[208:211], v191 offset:53248
	ds_read_b128 v[212:215], v191 offset:54272
	ds_read_b128 v[216:219], v191 offset:55296
	ds_read_b128 v[220:223], v191 offset:56320
	global_load_lds_dwordx4 v[10:11], off
	v_lshl_add_u64 v[10:11], v[12:13], 0, s[4:5]
	s_mov_b32 m0, s87
	s_addc_u32 s55, s55, 0
	global_load_lds_dwordx4 v[10:11], off
	v_lshl_add_u64 v[10:11], s[54:55], 0, v[166:167]
	s_mov_b32 m0, s90
	s_nop 0
	global_load_lds_dwordx4 v[10:11], off
	v_lshl_add_u64 v[10:11], s[54:55], 0, v[170:171]
	s_mov_b32 m0, s91
	s_nop 0
	global_load_lds_dwordx4 v[10:11], off
	v_lshl_add_u64 v[10:11], v[14:15], 0, s[4:5]
	s_mov_b32 m0, s88
	s_nop 0
	global_load_lds_dwordx4 v[10:11], off
	v_lshl_add_u64 v[10:11], v[16:17], 0, s[4:5]
	s_mov_b32 m0, s89
	s_nop 0
	global_load_lds_dwordx4 v[10:11], off
	s_waitcnt vmcnt(8)
	s_waitcnt lgkmcnt(0)
	s_barrier
	s_setprio 1
	s_waitcnt lgkmcnt(0)
	v_mfma_scale_f32_16x16x128_f8f6f4 v[94:97], v[18:25], v[192:199], v[94:97], v189, v189 op_sel_hi:[0,0,0]
	v_mfma_scale_f32_16x16x128_f8f6f4 v[90:93], v[26:33], v[192:199], v[90:93], v189, v189 op_sel_hi:[0,0,0]
	v_mfma_scale_f32_16x16x128_f8f6f4 v[82:85], v[26:33], v[200:207], v[82:85], v189, v189 op_sel_hi:[0,0,0]
	v_mfma_scale_f32_16x16x128_f8f6f4 v[86:89], v[18:25], v[200:207], v[86:89], v189, v189 op_sel_hi:[0,0,0]
	v_mfma_scale_f32_16x16x128_f8f6f4 v[78:81], v[18:25], v[208:215], v[78:81], v189, v189 op_sel_hi:[0,0,0]
	v_mfma_scale_f32_16x16x128_f8f6f4 v[74:77], v[26:33], v[208:215], v[74:77], v189, v189 op_sel_hi:[0,0,0]
	v_mfma_scale_f32_16x16x128_f8f6f4 v[66:69], v[26:33], v[216:223], v[66:69], v189, v189 op_sel_hi:[0,0,0]
	v_mfma_scale_f32_16x16x128_f8f6f4 v[70:73], v[18:25], v[216:223], v[70:73], v189, v189 op_sel_hi:[0,0,0]
	s_setprio 0
	s_setprio 1
	v_mfma_scale_f32_16x16x128_f8f6f4 v[38:41], v[2:9], v[216:223], v[38:41], v189, v189 op_sel_hi:[0,0,0]
	v_mfma_scale_f32_16x16x128_f8f6f4 v[34:37], v[180:187], v[216:223], v[34:37], v189, v189 op_sel_hi:[0,0,0]
	v_mfma_scale_f32_16x16x128_f8f6f4 v[42:45], v[180:187], v[208:215], v[42:45], v189, v189 op_sel_hi:[0,0,0]
	v_mfma_scale_f32_16x16x128_f8f6f4 v[46:49], v[2:9], v[208:215], v[46:49], v189, v189 op_sel_hi:[0,0,0]
	v_mfma_scale_f32_16x16x128_f8f6f4 v[54:57], v[2:9], v[200:207], v[54:57], v189, v189 op_sel_hi:[0,0,0]
	v_mfma_scale_f32_16x16x128_f8f6f4 v[50:53], v[180:187], v[200:207], v[50:53], v189, v189 op_sel_hi:[0,0,0]
	v_mfma_scale_f32_16x16x128_f8f6f4 v[58:61], v[180:187], v[192:199], v[58:61], v189, v189 op_sel_hi:[0,0,0]
	v_mfma_scale_f32_16x16x128_f8f6f4 v[62:65], v[2:9], v[192:199], v[62:65], v189, v189 op_sel_hi:[0,0,0]
	s_setprio 0
	s_barrier
	s_add_i32 s62, s62, 2
	s_add_u32 s72, s72, 0x100
	s_addc_u32 s73, s73, 0
	s_add_u32 s8, s8, 0x100
	s_addc_u32 s9, s9, 0
	s_cmp_gt_u32 s62, 29
	s_cbranch_scc0 .LBB0_198
	s_and_b64 vcc, exec, s[6:7]
	s_cbranch_vccz .LBB0_201
	s_barrier

.LBB0_208:
	s_ashr_i32 s2, s4, 31
	s_ashr_i32 s0, s4, 3
	s_lshr_b32 s2, s2, 27
	s_add_i32 s2, s0, s2
	s_and_b32 s8, s2, 0x1ffffe0
	s_lshl_b32 s2, s2, 3
	s_sub_i32 s0, s0, s8
	s_and_b32 s1, s16, 64
	s_and_b32 s3, s6, 0xc0
	s_and_b32 s2, s2, 0xffffff00
	s_lshl_b32 s8, s0, 7
	s_or_b32 s0, s2, s3
	s_or_b32 s2, s8, s1
	s_mul_i32 s1, s2, 0x2b00
	s_ashr_i32 s3, s1, 31
	s_add_u32 s27, s35, s1
	s_addc_u32 s33, s61, s3
	s_ashr_i32 s1, s0, 31
	s_lshl_b64 s[8:9], s[0:1], 14
	s_add_u32 s8, s56, s8
	s_addc_u32 s9, s57, s9
	s_ashr_i32 s3, s2, 31
	s_lshl_b64 s[2:3], s[2:3], 2
	s_add_u32 s2, s8, s2
	s_addc_u32 s3, s9, s3
	s_add_u32 s8, s2, 0x8000
	s_addc_u32 s9, s3, 0
	global_load_dword v31, v20, s[2:3] nt
	global_load_dword v72, v20, s[2:3] offset:128 nt
	global_load_dword v34, v20, s[8:9] nt
	global_load_dword v73, v20, s[8:9] offset:128 nt
	s_add_u32 s8, s2, 0x10000
	s_addc_u32 s9, s3, 0
	global_load_dword v35, v20, s[8:9] nt
	global_load_dword v74, v20, s[8:9] offset:128 nt
	s_add_u32 s8, s2, 0x18000
	s_addc_u32 s9, s3, 0
	global_load_dword v36, v20, s[8:9] nt
	global_load_dword v75, v20, s[8:9] offset:128 nt
	s_add_u32 s8, s2, 0x20000
	s_addc_u32 s9, s3, 0
	global_load_dword v37, v20, s[8:9] nt
	global_load_dword v76, v20, s[8:9] offset:128 nt
	s_add_u32 s8, s2, 0x28000
	s_addc_u32 s9, s3, 0
	global_load_dword v38, v20, s[8:9] nt
	global_load_dword v77, v20, s[8:9] offset:128 nt
	s_add_u32 s8, s2, 0x30000
	s_addc_u32 s9, s3, 0
	global_load_dword v39, v20, s[8:9] nt
	global_load_dword v78, v20, s[8:9] offset:128 nt
	s_add_u32 s8, s2, 0x38000
	s_addc_u32 s9, s3, 0
	global_load_dword v40, v20, s[8:9] nt
	global_load_dword v79, v20, s[8:9] offset:128 nt
	s_add_u32 s8, s2, 0x40000
	s_addc_u32 s9, s3, 0
	global_load_dword v32, v20, s[8:9] nt
	global_load_dword v80, v20, s[8:9] offset:128 nt
	s_add_u32 s8, s2, 0x48000
	s_addc_u32 s9, s3, 0
	global_load_dword v33, v20, s[8:9] nt
	global_load_dword v81, v20, s[8:9] offset:128 nt
	s_add_u32 s8, s2, 0x50000
	s_addc_u32 s9, s3, 0
	global_load_dword v41, v20, s[8:9] nt
	global_load_dword v82, v20, s[8:9] offset:128 nt
	s_add_u32 s8, s2, 0x58000
	s_addc_u32 s9, s3, 0
	global_load_dword v42, v20, s[8:9] nt
	global_load_dword v83, v20, s[8:9] offset:128 nt
	s_add_u32 s8, s2, 0x60000
	s_addc_u32 s9, s3, 0
	global_load_dword v43, v20, s[8:9] nt
	global_load_dword v84, v20, s[8:9] offset:128 nt
	s_add_u32 s8, s2, 0x68000
	s_addc_u32 s9, s3, 0
	global_load_dword v44, v20, s[8:9] nt
	global_load_dword v85, v20, s[8:9] offset:128 nt
	s_add_u32 s8, s2, 0x70000
	s_addc_u32 s9, s3, 0
	global_load_dword v45, v20, s[8:9] nt
	global_load_dword v86, v20, s[8:9] offset:128 nt
	s_add_u32 s8, s2, 0x78000
	s_addc_u32 s9, s3, 0
	global_load_dword v46, v20, s[8:9] nt
	global_load_dword v87, v20, s[8:9] offset:128 nt
	s_add_u32 s8, s2, 0x80000
	s_addc_u32 s9, s3, 0
	global_load_dword v47, v20, s[8:9] nt
	global_load_dword v88, v20, s[8:9] offset:128 nt
	s_add_u32 s8, s2, 0x88000
	s_addc_u32 s9, s3, 0
	global_load_dword v48, v20, s[8:9] nt
	global_load_dword v89, v20, s[8:9] offset:128 nt
	s_add_u32 s8, s2, 0x90000
	s_addc_u32 s9, s3, 0
	global_load_dword v49, v20, s[8:9] nt
	global_load_dword v90, v20, s[8:9] offset:128 nt
	s_add_u32 s8, s2, 0x98000
	s_addc_u32 s9, s3, 0
	global_load_dword v50, v20, s[8:9] nt
	global_load_dword v91, v20, s[8:9] offset:128 nt
	s_add_u32 s8, s2, 0xa0000
	s_addc_u32 s9, s3, 0
	global_load_dword v51, v20, s[8:9] nt
	global_load_dword v92, v20, s[8:9] offset:128 nt
	s_add_u32 s8, s2, 0xa8000
	s_addc_u32 s9, s3, 0
	global_load_dword v52, v20, s[8:9] nt
	global_load_dword v93, v20, s[8:9] offset:128 nt
	s_add_u32 s8, s2, 0xb0000
	s_addc_u32 s9, s3, 0
	global_load_dword v53, v20, s[8:9] nt
	global_load_dword v94, v20, s[8:9] offset:128 nt
	s_add_u32 s8, s2, 0xb8000
	s_addc_u32 s9, s3, 0
	global_load_dword v54, v20, s[8:9] nt
	global_load_dword v95, v20, s[8:9] offset:128 nt
	s_add_u32 s8, s2, 0xc0000
	s_addc_u32 s9, s3, 0
	global_load_dword v55, v20, s[8:9] nt
	global_load_dword v96, v20, s[8:9] offset:128 nt
	s_add_u32 s8, s2, 0xc8000
	s_addc_u32 s9, s3, 0
	global_load_dword v56, v20, s[8:9] nt
	global_load_dword v97, v20, s[8:9] offset:128 nt
	s_add_u32 s8, s2, 0xd0000
	s_addc_u32 s9, s3, 0
	global_load_dword v57, v20, s[8:9] nt
	global_load_dword v98, v20, s[8:9] offset:128 nt
	s_add_u32 s8, s2, 0xd8000
	s_addc_u32 s9, s3, 0
	global_load_dword v58, v20, s[8:9] nt
	global_load_dword v99, v20, s[8:9] offset:128 nt
	s_add_u32 s8, s2, 0xe0000
	s_addc_u32 s9, s3, 0
	global_load_dword v59, v20, s[8:9] nt
	global_load_dword v100, v20, s[8:9] offset:128 nt
	s_add_u32 s8, s2, 0xe8000
	s_addc_u32 s9, s3, 0
	global_load_dword v60, v20, s[8:9] nt
	global_load_dword v101, v20, s[8:9] offset:128 nt
	s_add_u32 s8, s2, 0xf0000
	s_addc_u32 s9, s3, 0
	s_add_u32 s2, s2, 0xf8000
	global_load_dword v61, v20, s[8:9] nt
	global_load_dword v102, v20, s[8:9] offset:128 nt
	s_addc_u32 s3, s3, 0
	global_load_dword v62, v20, s[2:3] nt
	global_load_dword v103, v20, s[2:3] offset:128 nt
	s_waitcnt vmcnt(0)
	s_add_u32 s0, s27, s0
	ds_write2_b32 v24, v32, v33 offset0:16 offset1:82
	ds_write2_b32 v24, v41, v42 offset0:148 offset1:214
	ds_write2_b32 v25, v43, v44 offset0:24 offset1:90
	ds_write2_b32 v25, v45, v46 offset0:156 offset1:222
	ds_write2_b32 v26, v47, v48 offset0:32 offset1:98
	ds_write2_b32 v26, v49, v50 offset0:164 offset1:230
	ds_write2_b32 v27, v51, v52 offset0:40 offset1:106
	ds_write2_b32 v27, v53, v54 offset0:172 offset1:238
	ds_write2_b32 v28, v55, v56 offset0:48 offset1:114
	ds_write2_b32 v28, v57, v58 offset0:180 offset1:246
	ds_write2_b32 v29, v59, v60 offset0:56 offset1:122
	ds_write2_b32 v29, v61, v62 offset0:188 offset1:254
	ds_write2_b32 v22, v31, v34 offset1:66
	ds_write2_b32 v22, v35, v36 offset0:132 offset1:198
	ds_write2_b32 v23, v37, v38 offset0:8 offset1:74
	ds_write2_b32 v23, v39, v40 offset0:140 offset1:206
	s_waitcnt lgkmcnt(0)
	ds_read2_b32 v[40:41], v21 offset1:16
	ds_read2_b32 v[42:43], v21 offset0:33 offset1:49
	ds_read2_b32 v[44:45], v21 offset0:66 offset1:82
	ds_read2_b32 v[46:47], v21 offset0:99 offset1:115
	ds_read2_b32 v[48:49], v21 offset0:132 offset1:148
	ds_read2_b32 v[50:51], v21 offset0:165 offset1:181
	ds_read2_b32 v[52:53], v21 offset0:198 offset1:214
	ds_read2_b32 v[54:55], v21 offset0:231 offset1:247
	ds_read2_b32 v[56:57], v30 offset0:8 offset1:24
	ds_read2_b32 v[58:59], v30 offset0:41 offset1:57
	ds_read2_b32 v[60:61], v30 offset0:74 offset1:90
	ds_read2_b32 v[62:63], v30 offset0:107 offset1:123
	ds_read2_b32 v[64:65], v30 offset0:140 offset1:156
	ds_read2_b32 v[66:67], v30 offset0:173 offset1:189
	ds_read2_b32 v[68:69], v30 offset0:206 offset1:222
	ds_read2_b32 v[70:71], v30 offset0:239 offset1:255
	s_addc_u32 s1, s33, s1
	v_mov_b32_e32 v2, 0
	v_mov_b32_e32 v3, 0
	v_mov_b32_e32 v4, 0
	v_mov_b32_e32 v5, 0
	v_lshl_add_u64 v[32:33], s[0:1], 0, v[162:163]
	v_mov_b32_e32 v10, 0
	v_mov_b32_e32 v11, 0
	v_mov_b32_e32 v12, 0
	v_mov_b32_e32 v13, 0
	v_lshl_add_u64 v[32:33], v[32:33], 0, v[18:19]
	s_waitcnt lgkmcnt(0)
	v_cvt_scalef32_pk_fp8_f32 v2, v40, v42, s20
	v_cvt_scalef32_pk_fp8_f32 v3, v48, v50, s20
	v_cvt_scalef32_pk_fp8_f32 v4, v56, v58, s20
	v_cvt_scalef32_pk_fp8_f32 v5, v64, v66, s20
	v_add_co_u32_e32 v34, vcc, s21, v32
	v_cvt_scalef32_pk_fp8_f32 v10, v41, v43, s20
	v_cvt_scalef32_pk_fp8_f32 v11, v49, v51, s20
	v_cvt_scalef32_pk_fp8_f32 v12, v57, v59, s20
	v_cvt_scalef32_pk_fp8_f32 v13, v65, v67, s20
	v_cvt_scalef32_pk_fp8_f32 v2, v44, v46, s20 op_sel:[0,0,0,1]
	v_cvt_scalef32_pk_fp8_f32 v3, v52, v54, s20 op_sel:[0,0,0,1]
	v_cvt_scalef32_pk_fp8_f32 v4, v60, v62, s20 op_sel:[0,0,0,1]
	v_cvt_scalef32_pk_fp8_f32 v5, v68, v70, s20 op_sel:[0,0,0,1]
	v_addc_co_u32_e32 v35, vcc, 0, v33, vcc
	v_cvt_scalef32_pk_fp8_f32 v10, v45, v47, s20 op_sel:[0,0,0,1]
	v_cvt_scalef32_pk_fp8_f32 v11, v53, v55, s20 op_sel:[0,0,0,1]
	v_cvt_scalef32_pk_fp8_f32 v12, v61, v63, s20 op_sel:[0,0,0,1]
	v_cvt_scalef32_pk_fp8_f32 v13, v69, v71, s20 op_sel:[0,0,0,1]
	global_store_dwordx4 v[32:33], v[2:5], off
	global_store_dwordx4 v[34:35], v[10:13], off
	s_waitcnt lgkmcnt(0)
	v_add_co_u32_e32 v36, vcc, s26, v32
	ds_write2_b32 v22, v72, v73 offset1:66
	ds_write2_b32 v22, v74, v75 offset0:132 offset1:198
	ds_write2_b32 v23, v76, v77 offset0:8 offset1:74
	ds_write2_b32 v23, v78, v79 offset0:140 offset1:206
	ds_write2_b32 v24, v80, v81 offset0:16 offset1:82
	ds_write2_b32 v24, v82, v83 offset0:148 offset1:214
	ds_write2_b32 v25, v84, v85 offset0:24 offset1:90
	ds_write2_b32 v25, v86, v87 offset0:156 offset1:222
	ds_write2_b32 v26, v88, v89 offset0:32 offset1:98
	ds_write2_b32 v26, v90, v91 offset0:164 offset1:230
	ds_write2_b32 v27, v92, v93 offset0:40 offset1:106
	ds_write2_b32 v27, v94, v95 offset0:172 offset1:238
	ds_write2_b32 v28, v96, v97 offset0:48 offset1:114
	ds_write2_b32 v28, v98, v99 offset0:180 offset1:246
	ds_write2_b32 v29, v100, v101 offset0:56 offset1:122
	ds_write2_b32 v29, v102, v103 offset0:188 offset1:254
	v_addc_co_u32_e32 v37, vcc, 0, v33, vcc
	s_waitcnt lgkmcnt(0)
	v_add_co_u32_e32 v38, vcc, 0x81000, v32
	v_mov_b32_e32 v6, 0
	s_nop 0
	v_addc_co_u32_e32 v39, vcc, 0, v33, vcc
	ds_read2_b32 v[2:3], v21 offset1:16
	ds_read2_b32 v[4:5], v21 offset0:33 offset1:49
	ds_read2_b32 v[10:11], v21 offset0:66 offset1:82
	ds_read2_b32 v[12:13], v21 offset0:99 offset1:115
	ds_read2_b32 v[32:33], v21 offset0:132 offset1:148
	ds_read2_b32 v[34:35], v21 offset0:165 offset1:181
	ds_read2_b32 v[40:41], v21 offset0:198 offset1:214
	ds_read2_b32 v[42:43], v21 offset0:231 offset1:247
	ds_read2_b32 v[44:45], v30 offset0:8 offset1:24
	ds_read2_b32 v[46:47], v30 offset0:41 offset1:57
	ds_read2_b32 v[48:49], v30 offset0:74 offset1:90
	ds_read2_b32 v[50:51], v30 offset0:107 offset1:123
	ds_read2_b32 v[52:53], v30 offset0:140 offset1:156
	ds_read2_b32 v[54:55], v30 offset0:173 offset1:189
	ds_read2_b32 v[56:57], v30 offset0:206 offset1:222
	ds_read2_b32 v[58:59], v30 offset0:239 offset1:255
	v_mov_b32_e32 v7, 0
	v_mov_b32_e32 v8, 0
	v_mov_b32_e32 v9, 0
	v_mov_b32_e32 v14, 0
	v_mov_b32_e32 v15, 0
	v_mov_b32_e32 v16, 0
	v_mov_b32_e32 v17, 0
	s_waitcnt lgkmcnt(0)
	v_cvt_scalef32_pk_fp8_f32 v6, v2, v4, s20
	v_cvt_scalef32_pk_fp8_f32 v7, v32, v34, s20
	v_cvt_scalef32_pk_fp8_f32 v8, v44, v46, s20
	v_cvt_scalef32_pk_fp8_f32 v9, v52, v54, s20
	v_cvt_scalef32_pk_fp8_f32 v14, v3, v5, s20
	v_cvt_scalef32_pk_fp8_f32 v15, v33, v35, s20
	v_cvt_scalef32_pk_fp8_f32 v16, v45, v47, s20
	v_cvt_scalef32_pk_fp8_f32 v17, v53, v55, s20
	v_cvt_scalef32_pk_fp8_f32 v6, v10, v12, s20 op_sel:[0,0,0,1]
	v_cvt_scalef32_pk_fp8_f32 v7, v40, v42, s20 op_sel:[0,0,0,1]
	v_cvt_scalef32_pk_fp8_f32 v8, v48, v50, s20 op_sel:[0,0,0,1]
	v_cvt_scalef32_pk_fp8_f32 v9, v56, v58, s20 op_sel:[0,0,0,1]
	v_cvt_scalef32_pk_fp8_f32 v14, v11, v13, s20 op_sel:[0,0,0,1]
	v_cvt_scalef32_pk_fp8_f32 v15, v41, v43, s20 op_sel:[0,0,0,1]
	v_cvt_scalef32_pk_fp8_f32 v16, v49, v51, s20 op_sel:[0,0,0,1]
	v_cvt_scalef32_pk_fp8_f32 v17, v57, v59, s20 op_sel:[0,0,0,1]
	global_store_dwordx4 v[36:37], v[6:9], off
	global_store_dwordx4 v[38:39], v[14:17], off
	s_waitcnt lgkmcnt(0)
	s_add_i32 s4, s4, s5
	s_add_i32 s6, s6, s7
	s_add_i32 s16, s16, s17
	s_cmpk_lt_i32 s4, 0x2b00
	s_cbranch_scc1 .LBB0_208

.LBB0_282:
	ds_read_b128 v[2:5], v187
	ds_read_b128 v[6:9], v187 offset:1024
	ds_read_b128 v[174:177], v187 offset:2048
	ds_read_b128 v[178:181], v187 offset:3072
	ds_read_b128 v[190:193], v187 offset:16384
	ds_read_b128 v[194:197], v187 offset:17408
	ds_read_b128 v[198:201], v187 offset:18432
	ds_read_b128 v[202:205], v187 offset:19456
	s_add_u32 s49, s52, 0x100
	s_addc_u32 s71, s53, 0
	s_and_b64 s[62:63], s[54:55], exec
	s_cselect_b32 s73, s1, s71
	s_cselect_b32 s72, s0, s49
	s_add_u32 s49, s50, 0x100
	s_addc_u32 s62, s51, 0
	s_and_b64 s[54:55], s[54:55], exec
	s_cselect_b32 s55, s5, s62
	s_cselect_b32 s54, s4, s49
	s_add_u32 s62, s52, 0x158080
	s_addc_u32 s63, s53, 0
	s_add_i32 s49, s33, 0xc000
	v_lshl_add_u64 v[182:183], s[62:63], 0, v[154:155]
	s_mov_b32 m0, s49
	s_add_i32 s71, s33, 0xe000
	ds_read_b128 v[206:209], v188
	ds_read_b128 v[210:213], v188 offset:1024
	ds_read_b128 v[214:217], v188 offset:2048
	ds_read_b128 v[218:221], v188 offset:3072
	ds_read_b128 v[222:225], v188 offset:4096
	ds_read_b128 v[226:229], v188 offset:5120
	ds_read_b128 v[230:233], v188 offset:6144
	ds_read_b128 v[234:237], v188 offset:7168
	global_load_lds_dwordx4 v[182:183], off
	v_lshl_add_u64 v[182:183], s[62:63], 0, v[158:159]
	s_mov_b32 m0, s71
	s_nop 0
	global_load_lds_dwordx4 v[182:183], off
	s_waitcnt vmcnt(8)
	s_waitcnt lgkmcnt(0)
	s_barrier
	s_setprio 1
	s_waitcnt lgkmcnt(0)
	v_mfma_scale_f32_16x16x128_f8f6f4 v[134:137], v[2:9], v[206:213], 0, v186, v186 op_sel_hi:[0,0,0]
	v_mfma_scale_f32_16x16x128_f8f6f4 v[130:133], v[174:181], v[206:213], 0, v186, v186 op_sel_hi:[0,0,0]
	v_mfma_scale_f32_16x16x128_f8f6f4 v[122:125], v[174:181], v[214:221], 0, v186, v186 op_sel_hi:[0,0,0]
	v_mfma_scale_f32_16x16x128_f8f6f4 v[126:129], v[2:9], v[214:221], 0, v186, v186 op_sel_hi:[0,0,0]
	v_mfma_scale_f32_16x16x128_f8f6f4 v[118:121], v[2:9], v[222:229], 0, v186, v186 op_sel_hi:[0,0,0]
	v_mfma_scale_f32_16x16x128_f8f6f4 v[114:117], v[174:181], v[222:229], 0, v186, v186 op_sel_hi:[0,0,0]
	v_mfma_scale_f32_16x16x128_f8f6f4 v[106:109], v[174:181], v[230:237], 0, v186, v186 op_sel_hi:[0,0,0]
	v_mfma_scale_f32_16x16x128_f8f6f4 v[110:113], v[2:9], v[230:237], 0, v186, v186 op_sel_hi:[0,0,0]
	s_setprio 0
	s_setprio 1
	v_mfma_scale_f32_16x16x128_f8f6f4 v[78:81], v[190:197], v[230:237], 0, v186, v186 op_sel_hi:[0,0,0]
	v_mfma_scale_f32_16x16x128_f8f6f4 v[74:77], v[198:205], v[230:237], 0, v186, v186 op_sel_hi:[0,0,0]
	v_mfma_scale_f32_16x16x128_f8f6f4 v[82:85], v[198:205], v[222:229], 0, v186, v186 op_sel_hi:[0,0,0]
	v_mfma_scale_f32_16x16x128_f8f6f4 v[86:89], v[190:197], v[222:229], 0, v186, v186 op_sel_hi:[0,0,0]
	v_mfma_scale_f32_16x16x128_f8f6f4 v[94:97], v[190:197], v[214:221], 0, v186, v186 op_sel_hi:[0,0,0]
	v_mfma_scale_f32_16x16x128_f8f6f4 v[90:93], v[198:205], v[214:221], 0, v186, v186 op_sel_hi:[0,0,0]
	v_mfma_scale_f32_16x16x128_f8f6f4 v[98:101], v[198:205], v[206:213], 0, v186, v186 op_sel_hi:[0,0,0]
	v_mfma_scale_f32_16x16x128_f8f6f4 v[102:105], v[190:197], v[206:213], 0, v186, v186 op_sel_hi:[0,0,0]
	s_setprio 0
	s_barrier
	s_mov_b32 m0, s47
	v_lshl_add_u64 v[182:183], s[54:55], 0, v[156:157]
	s_add_u32 s62, s54, 0x158000
	ds_read_b128 v[206:209], v188 offset:16384
	ds_read_b128 v[210:213], v188 offset:17408
	ds_read_b128 v[214:217], v188 offset:18432
	ds_read_b128 v[218:221], v188 offset:19456
	ds_read_b128 v[222:225], v188 offset:20480
	ds_read_b128 v[226:229], v188 offset:21504
	ds_read_b128 v[230:233], v188 offset:22528
	ds_read_b128 v[234:237], v188 offset:23552
	global_load_lds_dwordx4 v[182:183], off
	v_lshl_add_u64 v[238:239], s[54:55], 0, v[160:161]
	s_mov_b32 m0, s68
	s_addc_u32 s63, s55, 0
	global_load_lds_dwordx4 v[238:239], off
	v_lshl_add_u64 v[242:243], s[62:63], 0, v[156:157]
	s_mov_b32 m0, s69
	v_lshl_add_u64 v[244:245], s[72:73], 0, v[158:159]
	global_load_lds_dwordx4 v[242:243], off
	v_lshl_add_u64 v[242:243], s[62:63], 0, v[160:161]
	s_mov_b32 m0, s74
	s_nop 0
	global_load_lds_dwordx4 v[242:243], off
	v_lshl_add_u64 v[242:243], s[72:73], 0, v[154:155]
	s_mov_b32 m0, s33
	s_nop 0
	global_load_lds_dwordx4 v[242:243], off
	s_mov_b32 m0, s75
	s_nop 0
	global_load_lds_dwordx4 v[244:245], off
	s_waitcnt vmcnt(8)
	s_waitcnt lgkmcnt(0)
	s_barrier
	s_setprio 1
	s_waitcnt lgkmcnt(0)
	v_mfma_scale_f32_16x16x128_f8f6f4 v[70:73], v[2:9], v[206:213], 0, v186, v186 op_sel_hi:[0,0,0]
	v_mfma_scale_f32_16x16x128_f8f6f4 v[66:69], v[174:181], v[206:213], 0, v186, v186 op_sel_hi:[0,0,0]
	v_mfma_scale_f32_16x16x128_f8f6f4 v[58:61], v[174:181], v[214:221], 0, v186, v186 op_sel_hi:[0,0,0]
	v_mfma_scale_f32_16x16x128_f8f6f4 v[62:65], v[2:9], v[214:221], 0, v186, v186 op_sel_hi:[0,0,0]
	v_mfma_scale_f32_16x16x128_f8f6f4 v[54:57], v[2:9], v[222:229], 0, v186, v186 op_sel_hi:[0,0,0]
	v_mfma_scale_f32_16x16x128_f8f6f4 v[50:53], v[174:181], v[222:229], 0, v186, v186 op_sel_hi:[0,0,0]
	v_mfma_scale_f32_16x16x128_f8f6f4 v[42:45], v[174:181], v[230:237], 0, v186, v186 op_sel_hi:[0,0,0]
	v_mfma_scale_f32_16x16x128_f8f6f4 v[46:49], v[2:9], v[230:237], 0, v186, v186 op_sel_hi:[0,0,0]
	s_setprio 0
	s_setprio 1
	v_mfma_scale_f32_16x16x128_f8f6f4 v[14:17], v[190:197], v[230:237], 0, v186, v186 op_sel_hi:[0,0,0]
	v_mfma_scale_f32_16x16x128_f8f6f4 v[10:13], v[198:205], v[230:237], 0, v186, v186 op_sel_hi:[0,0,0]
	v_mfma_scale_f32_16x16x128_f8f6f4 v[18:21], v[198:205], v[222:229], 0, v186, v186 op_sel_hi:[0,0,0]
	v_mfma_scale_f32_16x16x128_f8f6f4 v[22:25], v[190:197], v[222:229], 0, v186, v186 op_sel_hi:[0,0,0]
	v_mfma_scale_f32_16x16x128_f8f6f4 v[30:33], v[190:197], v[214:221], 0, v186, v186 op_sel_hi:[0,0,0]
	v_mfma_scale_f32_16x16x128_f8f6f4 v[26:29], v[198:205], v[214:221], 0, v186, v186 op_sel_hi:[0,0,0]
	v_mfma_scale_f32_16x16x128_f8f6f4 v[34:37], v[198:205], v[206:213], 0, v186, v186 op_sel_hi:[0,0,0]
	v_mfma_scale_f32_16x16x128_f8f6f4 v[38:41], v[190:197], v[206:213], 0, v186, v186 op_sel_hi:[0,0,0]
	s_setprio 0
	s_barrier
	ds_read_b128 v[2:5], v187 offset:32768
	ds_read_b128 v[6:9], v187 offset:33792
	ds_read_b128 v[174:177], v187 offset:34816
	ds_read_b128 v[178:181], v187 offset:35840
	ds_read_b128 v[190:193], v187 offset:49152
	ds_read_b128 v[194:197], v187 offset:50176
	ds_read_b128 v[198:201], v187 offset:51200
	ds_read_b128 v[202:205], v187 offset:52224
	s_add_u32 s62, s72, 0x158000
	s_addc_u32 s63, s73, 0
	s_mov_b32 m0, s76
	v_lshl_add_u64 v[246:247], s[62:63], 0, v[154:155]
	ds_read_b128 v[206:209], v188 offset:32768
	ds_read_b128 v[210:213], v188 offset:33792
	ds_read_b128 v[214:217], v188 offset:34816
	ds_read_b128 v[218:221], v188 offset:35840
	ds_read_b128 v[222:225], v188 offset:36864
	ds_read_b128 v[226:229], v188 offset:37888
	ds_read_b128 v[230:233], v188 offset:38912
	ds_read_b128 v[234:237], v188 offset:39936
	global_load_lds_dwordx4 v[246:247], off
	v_lshl_add_u64 v[246:247], s[62:63], 0, v[158:159]
	s_mov_b32 m0, s77
	s_nop 0
	global_load_lds_dwordx4 v[246:247], off
	s_waitcnt vmcnt(8)
	s_waitcnt lgkmcnt(0)
	s_barrier
	s_setprio 1
	s_waitcnt lgkmcnt(0)
	v_mfma_scale_f32_16x16x128_f8f6f4 v[134:137], v[2:9], v[206:213], v[134:137], v186, v186 op_sel_hi:[0,0,0]
	v_mfma_scale_f32_16x16x128_f8f6f4 v[130:133], v[174:181], v[206:213], v[130:133], v186, v186 op_sel_hi:[0,0,0]
	v_mfma_scale_f32_16x16x128_f8f6f4 v[122:125], v[174:181], v[214:221], v[122:125], v186, v186 op_sel_hi:[0,0,0]
	v_mfma_scale_f32_16x16x128_f8f6f4 v[126:129], v[2:9], v[214:221], v[126:129], v186, v186 op_sel_hi:[0,0,0]
	v_mfma_scale_f32_16x16x128_f8f6f4 v[118:121], v[2:9], v[222:229], v[118:121], v186, v186 op_sel_hi:[0,0,0]
	v_mfma_scale_f32_16x16x128_f8f6f4 v[114:117], v[174:181], v[222:229], v[114:117], v186, v186 op_sel_hi:[0,0,0]
	v_mfma_scale_f32_16x16x128_f8f6f4 v[106:109], v[174:181], v[230:237], v[106:109], v186, v186 op_sel_hi:[0,0,0]
	v_mfma_scale_f32_16x16x128_f8f6f4 v[110:113], v[2:9], v[230:237], v[110:113], v186, v186 op_sel_hi:[0,0,0]
	s_setprio 0
	s_setprio 1
	v_mfma_scale_f32_16x16x128_f8f6f4 v[78:81], v[190:197], v[230:237], v[78:81], v186, v186 op_sel_hi:[0,0,0]
	v_mfma_scale_f32_16x16x128_f8f6f4 v[74:77], v[198:205], v[230:237], v[74:77], v186, v186 op_sel_hi:[0,0,0]
	v_mfma_scale_f32_16x16x128_f8f6f4 v[82:85], v[198:205], v[222:229], v[82:85], v186, v186 op_sel_hi:[0,0,0]
	v_mfma_scale_f32_16x16x128_f8f6f4 v[86:89], v[190:197], v[222:229], v[86:89], v186, v186 op_sel_hi:[0,0,0]
	v_mfma_scale_f32_16x16x128_f8f6f4 v[94:97], v[190:197], v[214:221], v[94:97], v186, v186 op_sel_hi:[0,0,0]
	v_mfma_scale_f32_16x16x128_f8f6f4 v[90:93], v[198:205], v[214:221], v[90:93], v186, v186 op_sel_hi:[0,0,0]
	v_mfma_scale_f32_16x16x128_f8f6f4 v[98:101], v[198:205], v[206:213], v[98:101], v186, v186 op_sel_hi:[0,0,0]
	v_mfma_scale_f32_16x16x128_f8f6f4 v[102:105], v[190:197], v[206:213], v[102:105], v186, v186 op_sel_hi:[0,0,0]
	s_setprio 0
	s_barrier
	s_mov_b32 m0, s83
	v_lshl_add_u64 v[182:183], v[182:183], 0, s[26:27]
	s_add_u32 s54, s54, 0x158080
	ds_read_b128 v[206:209], v188 offset:49152
	ds_read_b128 v[210:213], v188 offset:50176
	ds_read_b128 v[214:217], v188 offset:51200
	ds_read_b128 v[218:221], v188 offset:52224
	ds_read_b128 v[222:225], v188 offset:53248
	ds_read_b128 v[226:229], v188 offset:54272
	ds_read_b128 v[230:233], v188 offset:55296
	ds_read_b128 v[234:237], v188 offset:56320
	global_load_lds_dwordx4 v[182:183], off
	v_lshl_add_u64 v[182:183], v[238:239], 0, s[26:27]
	s_mov_b32 m0, s84
	s_addc_u32 s55, s55, 0
	global_load_lds_dwordx4 v[182:183], off
	v_lshl_add_u64 v[182:183], s[54:55], 0, v[156:157]
	s_mov_b32 m0, s87
	s_nop 0
	global_load_lds_dwordx4 v[182:183], off
	v_lshl_add_u64 v[182:183], s[54:55], 0, v[160:161]
	s_mov_b32 m0, s88
	s_nop 0
	global_load_lds_dwordx4 v[182:183], off
	v_lshl_add_u64 v[182:183], v[242:243], 0, s[26:27]
	s_mov_b32 m0, s85
	s_nop 0
	global_load_lds_dwordx4 v[182:183], off
	v_lshl_add_u64 v[182:183], v[244:245], 0, s[26:27]
	s_mov_b32 m0, s86
	s_nop 0
	global_load_lds_dwordx4 v[182:183], off
	s_waitcnt vmcnt(8)
	s_waitcnt lgkmcnt(0)
	s_barrier
	s_setprio 1
	s_waitcnt lgkmcnt(0)
	v_mfma_scale_f32_16x16x128_f8f6f4 v[70:73], v[2:9], v[206:213], v[70:73], v186, v186 op_sel_hi:[0,0,0]
	v_mfma_scale_f32_16x16x128_f8f6f4 v[66:69], v[174:181], v[206:213], v[66:69], v186, v186 op_sel_hi:[0,0,0]
	v_mfma_scale_f32_16x16x128_f8f6f4 v[58:61], v[174:181], v[214:221], v[58:61], v186, v186 op_sel_hi:[0,0,0]
	v_mfma_scale_f32_16x16x128_f8f6f4 v[62:65], v[2:9], v[214:221], v[62:65], v186, v186 op_sel_hi:[0,0,0]
	v_mfma_scale_f32_16x16x128_f8f6f4 v[54:57], v[2:9], v[222:229], v[54:57], v186, v186 op_sel_hi:[0,0,0]
	v_mfma_scale_f32_16x16x128_f8f6f4 v[50:53], v[174:181], v[222:229], v[50:53], v186, v186 op_sel_hi:[0,0,0]
	v_mfma_scale_f32_16x16x128_f8f6f4 v[42:45], v[174:181], v[230:237], v[42:45], v186, v186 op_sel_hi:[0,0,0]
	v_mfma_scale_f32_16x16x128_f8f6f4 v[46:49], v[2:9], v[230:237], v[46:49], v186, v186 op_sel_hi:[0,0,0]
	s_setprio 0
	s_setprio 1
	v_mfma_scale_f32_16x16x128_f8f6f4 v[14:17], v[190:197], v[230:237], v[14:17], v186, v186 op_sel_hi:[0,0,0]
	v_mfma_scale_f32_16x16x128_f8f6f4 v[10:13], v[198:205], v[230:237], v[10:13], v186, v186 op_sel_hi:[0,0,0]
	v_mfma_scale_f32_16x16x128_f8f6f4 v[18:21], v[198:205], v[222:229], v[18:21], v186, v186 op_sel_hi:[0,0,0]
	v_mfma_scale_f32_16x16x128_f8f6f4 v[22:25], v[190:197], v[222:229], v[22:25], v186, v186 op_sel_hi:[0,0,0]
	v_mfma_scale_f32_16x16x128_f8f6f4 v[30:33], v[190:197], v[214:221], v[30:33], v186, v186 op_sel_hi:[0,0,0]
	v_mfma_scale_f32_16x16x128_f8f6f4 v[26:29], v[198:205], v[214:221], v[26:29], v186, v186 op_sel_hi:[0,0,0]
	v_mfma_scale_f32_16x16x128_f8f6f4 v[34:37], v[198:205], v[206:213], v[34:37], v186, v186 op_sel_hi:[0,0,0]
	v_mfma_scale_f32_16x16x128_f8f6f4 v[38:41], v[190:197], v[206:213], v[38:41], v186, v186 op_sel_hi:[0,0,0]
	s_setprio 0
	s_barrier
	s_cmp_lt_u32 s95, 3
	s_cbranch_scc1 .LBB0_287
	s_add_u32 s54, s79, s9
	s_addc_u32 s55, s80, s8
	s_add_u32 s52, s52, 0x158180
	s_addc_u32 s53, s53, 0
	s_add_u32 s8, s50, 0x200
	v_lshl_add_u64 v[174:175], v[172:173], 2, s[54:55]
	s_addc_u32 s9, s51, 0
	s_mov_b32 s72, 4
	s_cmp_eq_u32 s95, s72
	s_cselect_b64 s[50:51], -1, 0
	s_cmp_lg_u32 s95, s72
	s_cbranch_scc1 .LBB0_285

.LBB0_285:
	ds_read_b128 v[2:5], v187
	ds_read_b128 v[6:9], v187 offset:1024
	ds_read_b128 v[190:193], v187 offset:2048
	ds_read_b128 v[194:197], v187 offset:3072
	ds_read_b128 v[198:201], v187 offset:16384
	ds_read_b128 v[202:205], v187 offset:17408
	ds_read_b128 v[206:209], v187 offset:18432
	ds_read_b128 v[210:213], v187 offset:19456
	s_add_u32 s54, s52, 0xffea8080
	s_addc_u32 s55, s53, -1
	s_and_b64 s[50:51], s[50:51], exec
	s_cselect_b32 s50, s4, s8
	s_cselect_b32 s55, s1, s55
	s_cselect_b32 s54, s0, s54
	s_cselect_b32 s51, s5, s9
	s_mov_b32 m0, s49
	v_lshl_add_u64 v[238:239], s[52:53], 0, v[162:163]
	ds_read_b128 v[176:179], v188
	ds_read_b128 v[180:183], v188 offset:1024
	ds_read_b128 v[214:217], v188 offset:2048
	ds_read_b128 v[218:221], v188 offset:3072
	ds_read_b128 v[222:225], v188 offset:4096
	ds_read_b128 v[226:229], v188 offset:5120
	ds_read_b128 v[230:233], v188 offset:6144
	ds_read_b128 v[234:237], v188 offset:7168
	global_load_lds_dwordx4 v[238:239], off
	v_lshl_add_u64 v[238:239], s[52:53], 0, v[164:165]
	s_mov_b32 m0, s71
	s_nop 0
	global_load_lds_dwordx4 v[238:239], off
	s_waitcnt vmcnt(8)
	s_waitcnt lgkmcnt(0)
	s_barrier
	s_setprio 1
	s_waitcnt lgkmcnt(0)
	v_mfma_scale_f32_16x16x128_f8f6f4 v[134:137], v[2:9], v[176:183], v[134:137], v186, v186 op_sel_hi:[0,0,0]
	v_mfma_scale_f32_16x16x128_f8f6f4 v[130:133], v[190:197], v[176:183], v[130:133], v186, v186 op_sel_hi:[0,0,0]
	v_mfma_scale_f32_16x16x128_f8f6f4 v[122:125], v[190:197], v[214:221], v[122:125], v186, v186 op_sel_hi:[0,0,0]
	v_mfma_scale_f32_16x16x128_f8f6f4 v[126:129], v[2:9], v[214:221], v[126:129], v186, v186 op_sel_hi:[0,0,0]
	v_mfma_scale_f32_16x16x128_f8f6f4 v[118:121], v[2:9], v[222:229], v[118:121], v186, v186 op_sel_hi:[0,0,0]
	v_mfma_scale_f32_16x16x128_f8f6f4 v[114:117], v[190:197], v[222:229], v[114:117], v186, v186 op_sel_hi:[0,0,0]
	v_mfma_scale_f32_16x16x128_f8f6f4 v[106:109], v[190:197], v[230:237], v[106:109], v186, v186 op_sel_hi:[0,0,0]
	v_mfma_scale_f32_16x16x128_f8f6f4 v[110:113], v[2:9], v[230:237], v[110:113], v186, v186 op_sel_hi:[0,0,0]
	s_setprio 0
	s_setprio 1
	v_mfma_scale_f32_16x16x128_f8f6f4 v[78:81], v[198:205], v[230:237], v[78:81], v186, v186 op_sel_hi:[0,0,0]
	v_mfma_scale_f32_16x16x128_f8f6f4 v[74:77], v[206:213], v[230:237], v[74:77], v186, v186 op_sel_hi:[0,0,0]
	v_mfma_scale_f32_16x16x128_f8f6f4 v[82:85], v[206:213], v[222:229], v[82:85], v186, v186 op_sel_hi:[0,0,0]
	v_mfma_scale_f32_16x16x128_f8f6f4 v[86:89], v[198:205], v[222:229], v[86:89], v186, v186 op_sel_hi:[0,0,0]
	v_mfma_scale_f32_16x16x128_f8f6f4 v[94:97], v[198:205], v[214:221], v[94:97], v186, v186 op_sel_hi:[0,0,0]
	v_mfma_scale_f32_16x16x128_f8f6f4 v[90:93], v[206:213], v[214:221], v[90:93], v186, v186 op_sel_hi:[0,0,0]
	v_mfma_scale_f32_16x16x128_f8f6f4 v[98:101], v[206:213], v[176:183], v[98:101], v186, v186 op_sel_hi:[0,0,0]
	v_mfma_scale_f32_16x16x128_f8f6f4 v[102:105], v[198:205], v[176:183], v[102:105], v186, v186 op_sel_hi:[0,0,0]
	s_setprio 0
	s_barrier
	s_mov_b32 m0, s47
	v_lshl_add_u64 v[176:177], s[50:51], 0, v[156:157]
	s_add_u32 s62, s50, 0x158000
	ds_read_b128 v[214:217], v188 offset:16384
	ds_read_b128 v[218:221], v188 offset:17408
	ds_read_b128 v[222:225], v188 offset:18432
	ds_read_b128 v[226:229], v188 offset:19456
	ds_read_b128 v[230:233], v188 offset:20480
	ds_read_b128 v[234:237], v188 offset:21504
	ds_read_b128 v[242:245], v188 offset:22528
	ds_read_b128 v[246:249], v188 offset:23552
	global_load_lds_dwordx4 v[176:177], off
	v_lshl_add_u64 v[178:179], s[50:51], 0, v[160:161]
	s_mov_b32 m0, s68
	s_addc_u32 s63, s51, 0
	global_load_lds_dwordx4 v[178:179], off
	v_lshl_add_u64 v[180:181], s[62:63], 0, v[156:157]
	s_mov_b32 m0, s69
	v_lshl_add_u64 v[182:183], s[54:55], 0, v[158:159]
	global_load_lds_dwordx4 v[180:181], off
	v_lshl_add_u64 v[180:181], s[62:63], 0, v[160:161]
	s_mov_b32 m0, s74
	s_nop 0
	global_load_lds_dwordx4 v[180:181], off
	v_lshl_add_u64 v[180:181], s[54:55], 0, v[154:155]
	s_mov_b32 m0, s33
	s_nop 0
	global_load_lds_dwordx4 v[180:181], off
	s_mov_b32 m0, s75
	s_nop 0
	global_load_lds_dwordx4 v[182:183], off
	s_waitcnt vmcnt(8)
	s_waitcnt lgkmcnt(0)
	s_barrier
	s_setprio 1
	s_waitcnt lgkmcnt(0)
	v_mfma_scale_f32_16x16x128_f8f6f4 v[70:73], v[2:9], v[214:221], v[70:73], v186, v186 op_sel_hi:[0,0,0]
	v_mfma_scale_f32_16x16x128_f8f6f4 v[66:69], v[190:197], v[214:221], v[66:69], v186, v186 op_sel_hi:[0,0,0]
	v_mfma_scale_f32_16x16x128_f8f6f4 v[58:61], v[190:197], v[222:229], v[58:61], v186, v186 op_sel_hi:[0,0,0]
	v_mfma_scale_f32_16x16x128_f8f6f4 v[62:65], v[2:9], v[222:229], v[62:65], v186, v186 op_sel_hi:[0,0,0]
	v_mfma_scale_f32_16x16x128_f8f6f4 v[54:57], v[2:9], v[230:237], v[54:57], v186, v186 op_sel_hi:[0,0,0]
	v_mfma_scale_f32_16x16x128_f8f6f4 v[50:53], v[190:197], v[230:237], v[50:53], v186, v186 op_sel_hi:[0,0,0]
	v_mfma_scale_f32_16x16x128_f8f6f4 v[42:45], v[190:197], v[242:249], v[42:45], v186, v186 op_sel_hi:[0,0,0]
	v_mfma_scale_f32_16x16x128_f8f6f4 v[46:49], v[2:9], v[242:249], v[46:49], v186, v186 op_sel_hi:[0,0,0]
	s_setprio 0
	s_setprio 1
	v_mfma_scale_f32_16x16x128_f8f6f4 v[14:17], v[198:205], v[242:249], v[14:17], v186, v186 op_sel_hi:[0,0,0]
	v_mfma_scale_f32_16x16x128_f8f6f4 v[10:13], v[206:213], v[242:249], v[10:13], v186, v186 op_sel_hi:[0,0,0]
	v_mfma_scale_f32_16x16x128_f8f6f4 v[18:21], v[206:213], v[230:237], v[18:21], v186, v186 op_sel_hi:[0,0,0]
	v_mfma_scale_f32_16x16x128_f8f6f4 v[22:25], v[198:205], v[230:237], v[22:25], v186, v186 op_sel_hi:[0,0,0]
	v_mfma_scale_f32_16x16x128_f8f6f4 v[30:33], v[198:205], v[222:229], v[30:33], v186, v186 op_sel_hi:[0,0,0]
	v_mfma_scale_f32_16x16x128_f8f6f4 v[26:29], v[206:213], v[222:229], v[26:29], v186, v186 op_sel_hi:[0,0,0]
	v_mfma_scale_f32_16x16x128_f8f6f4 v[34:37], v[206:213], v[214:221], v[34:37], v186, v186 op_sel_hi:[0,0,0]
	v_mfma_scale_f32_16x16x128_f8f6f4 v[38:41], v[198:205], v[214:221], v[38:41], v186, v186 op_sel_hi:[0,0,0]
	s_setprio 0
	s_barrier
	ds_read_b128 v[190:193], v187 offset:32768
	ds_read_b128 v[194:197], v187 offset:33792
	ds_read_b128 v[198:201], v187 offset:34816
	ds_read_b128 v[202:205], v187 offset:35840
	ds_read_b128 v[2:5], v187 offset:49152
	ds_read_b128 v[6:9], v187 offset:50176
	ds_read_b128 v[206:209], v187 offset:51200
	ds_read_b128 v[210:213], v187 offset:52224
	s_add_u32 s54, s54, 0x158000
	s_addc_u32 s55, s55, 0
	s_mov_b32 m0, s76
	v_lshl_add_u64 v[238:239], s[54:55], 0, v[154:155]
	ds_read_b128 v[214:217], v188 offset:32768
	ds_read_b128 v[218:221], v188 offset:33792
	ds_read_b128 v[222:225], v188 offset:34816
	ds_read_b128 v[226:229], v188 offset:35840
	ds_read_b128 v[230:233], v188 offset:36864
	ds_read_b128 v[234:237], v188 offset:37888
	ds_read_b128 v[242:245], v188 offset:38912
	ds_read_b128 v[246:249], v188 offset:39936
	global_load_lds_dwordx4 v[238:239], off
	v_lshl_add_u64 v[238:239], s[54:55], 0, v[158:159]
	s_mov_b32 m0, s77
	s_nop 0
	global_load_lds_dwordx4 v[238:239], off
	s_waitcnt vmcnt(8)
	s_waitcnt lgkmcnt(0)
	s_barrier
	s_setprio 1
	s_waitcnt lgkmcnt(0)
	v_mfma_scale_f32_16x16x128_f8f6f4 v[134:137], v[190:197], v[214:221], v[134:137], v186, v186 op_sel_hi:[0,0,0]
	v_mfma_scale_f32_16x16x128_f8f6f4 v[130:133], v[198:205], v[214:221], v[130:133], v186, v186 op_sel_hi:[0,0,0]
	v_mfma_scale_f32_16x16x128_f8f6f4 v[122:125], v[198:205], v[222:229], v[122:125], v186, v186 op_sel_hi:[0,0,0]
	v_mfma_scale_f32_16x16x128_f8f6f4 v[126:129], v[190:197], v[222:229], v[126:129], v186, v186 op_sel_hi:[0,0,0]
	v_mfma_scale_f32_16x16x128_f8f6f4 v[118:121], v[190:197], v[230:237], v[118:121], v186, v186 op_sel_hi:[0,0,0]
	v_mfma_scale_f32_16x16x128_f8f6f4 v[114:117], v[198:205], v[230:237], v[114:117], v186, v186 op_sel_hi:[0,0,0]
	v_mfma_scale_f32_16x16x128_f8f6f4 v[106:109], v[198:205], v[242:249], v[106:109], v186, v186 op_sel_hi:[0,0,0]
	v_mfma_scale_f32_16x16x128_f8f6f4 v[110:113], v[190:197], v[242:249], v[110:113], v186, v186 op_sel_hi:[0,0,0]
	s_setprio 0
	s_setprio 1
	v_mfma_scale_f32_16x16x128_f8f6f4 v[78:81], v[2:9], v[242:249], v[78:81], v186, v186 op_sel_hi:[0,0,0]
	v_mfma_scale_f32_16x16x128_f8f6f4 v[74:77], v[206:213], v[242:249], v[74:77], v186, v186 op_sel_hi:[0,0,0]
	v_mfma_scale_f32_16x16x128_f8f6f4 v[82:85], v[206:213], v[230:237], v[82:85], v186, v186 op_sel_hi:[0,0,0]
	v_mfma_scale_f32_16x16x128_f8f6f4 v[86:89], v[2:9], v[230:237], v[86:89], v186, v186 op_sel_hi:[0,0,0]
	v_mfma_scale_f32_16x16x128_f8f6f4 v[94:97], v[2:9], v[222:229], v[94:97], v186, v186 op_sel_hi:[0,0,0]
	v_mfma_scale_f32_16x16x128_f8f6f4 v[90:93], v[206:213], v[222:229], v[90:93], v186, v186 op_sel_hi:[0,0,0]
	v_mfma_scale_f32_16x16x128_f8f6f4 v[98:101], v[206:213], v[214:221], v[98:101], v186, v186 op_sel_hi:[0,0,0]
	v_mfma_scale_f32_16x16x128_f8f6f4 v[102:105], v[2:9], v[214:221], v[102:105], v186, v186 op_sel_hi:[0,0,0]
	s_setprio 0
	s_barrier
	s_mov_b32 m0, s83
	v_lshl_add_u64 v[176:177], v[176:177], 0, s[26:27]
	s_add_u32 s50, s50, 0x158080
	ds_read_b128 v[214:217], v188 offset:49152
	ds_read_b128 v[218:221], v188 offset:50176
	ds_read_b128 v[222:225], v188 offset:51200
	ds_read_b128 v[226:229], v188 offset:52224
	ds_read_b128 v[230:233], v188 offset:53248
	ds_read_b128 v[234:237], v188 offset:54272
	ds_read_b128 v[242:245], v188 offset:55296
	ds_read_b128 v[246:249], v188 offset:56320
	global_load_lds_dwordx4 v[176:177], off
	v_lshl_add_u64 v[176:177], v[178:179], 0, s[26:27]
	s_mov_b32 m0, s84
	s_addc_u32 s51, s51, 0
	global_load_lds_dwordx4 v[176:177], off
	v_lshl_add_u64 v[176:177], s[50:51], 0, v[156:157]
	s_mov_b32 m0, s87
	s_nop 0
	global_load_lds_dwordx4 v[176:177], off
	v_lshl_add_u64 v[176:177], s[50:51], 0, v[160:161]
	s_mov_b32 m0, s88
	s_nop 0
	global_load_lds_dwordx4 v[176:177], off
	v_lshl_add_u64 v[176:177], v[180:181], 0, s[26:27]
	s_mov_b32 m0, s85
	s_nop 0
	global_load_lds_dwordx4 v[176:177], off
	v_lshl_add_u64 v[176:177], v[182:183], 0, s[26:27]
	s_mov_b32 m0, s86
	s_nop 0
	global_load_lds_dwordx4 v[176:177], off
	s_waitcnt vmcnt(8)
	s_waitcnt lgkmcnt(0)
	s_barrier
	s_setprio 1
	s_waitcnt lgkmcnt(0)
	v_mfma_scale_f32_16x16x128_f8f6f4 v[70:73], v[190:197], v[214:221], v[70:73], v186, v186 op_sel_hi:[0,0,0]
	v_mfma_scale_f32_16x16x128_f8f6f4 v[66:69], v[198:205], v[214:221], v[66:69], v186, v186 op_sel_hi:[0,0,0]
	v_mfma_scale_f32_16x16x128_f8f6f4 v[58:61], v[198:205], v[222:229], v[58:61], v186, v186 op_sel_hi:[0,0,0]
	v_mfma_scale_f32_16x16x128_f8f6f4 v[62:65], v[190:197], v[222:229], v[62:65], v186, v186 op_sel_hi:[0,0,0]
	v_mfma_scale_f32_16x16x128_f8f6f4 v[54:57], v[190:197], v[230:237], v[54:57], v186, v186 op_sel_hi:[0,0,0]
	v_mfma_scale_f32_16x16x128_f8f6f4 v[50:53], v[198:205], v[230:237], v[50:53], v186, v186 op_sel_hi:[0,0,0]
	v_mfma_scale_f32_16x16x128_f8f6f4 v[42:45], v[198:205], v[242:249], v[42:45], v186, v186 op_sel_hi:[0,0,0]
	v_mfma_scale_f32_16x16x128_f8f6f4 v[46:49], v[190:197], v[242:249], v[46:49], v186, v186 op_sel_hi:[0,0,0]
	s_setprio 0
	s_setprio 1
	v_mfma_scale_f32_16x16x128_f8f6f4 v[14:17], v[2:9], v[242:249], v[14:17], v186, v186 op_sel_hi:[0,0,0]
	v_mfma_scale_f32_16x16x128_f8f6f4 v[10:13], v[206:213], v[242:249], v[10:13], v186, v186 op_sel_hi:[0,0,0]
	v_mfma_scale_f32_16x16x128_f8f6f4 v[18:21], v[206:213], v[230:237], v[18:21], v186, v186 op_sel_hi:[0,0,0]
	v_mfma_scale_f32_16x16x128_f8f6f4 v[22:25], v[2:9], v[230:237], v[22:25], v186, v186 op_sel_hi:[0,0,0]
	v_mfma_scale_f32_16x16x128_f8f6f4 v[30:33], v[2:9], v[222:229], v[30:33], v186, v186 op_sel_hi:[0,0,0]
	v_mfma_scale_f32_16x16x128_f8f6f4 v[26:29], v[206:213], v[222:229], v[26:29], v186, v186 op_sel_hi:[0,0,0]
	v_mfma_scale_f32_16x16x128_f8f6f4 v[34:37], v[206:213], v[214:221], v[34:37], v186, v186 op_sel_hi:[0,0,0]
	v_mfma_scale_f32_16x16x128_f8f6f4 v[38:41], v[2:9], v[214:221], v[38:41], v186, v186 op_sel_hi:[0,0,0]
	s_setprio 0
	s_barrier
	s_add_i32 s50, s72, 2
	s_add_u32 s52, s52, 0x100
	s_addc_u32 s53, s53, 0
	s_add_u32 s8, s8, 0x100
	s_addc_u32 s9, s9, 0
	s_cmp_ge_i32 s72, s95
	s_cbranch_scc1 .LBB0_287
	s_mov_b32 s72, s50
	s_cmp_eq_u32 s95, s72
	s_cselect_b64 s[50:51], -1, 0
	s_cmp_lg_u32 s95, s72
	s_cbranch_scc0 .LBB0_284
	s_branch .LBB0_285

.LBB0_437:
	s_ashr_i32 s47, s46, 31
	ds_read_b128 v[18:21], v200
	ds_read_b128 v[22:25], v200 offset:1024
	ds_read_b128 v[26:29], v200 offset:2048
	ds_read_b128 v[30:33], v200 offset:3072
	ds_read_b128 v[2:5], v200 offset:16384
	ds_read_b128 v[6:9], v200 offset:17408
	ds_read_b128 v[10:13], v200 offset:18432
	ds_read_b128 v[14:17], v200 offset:19456
	s_lshl_b64 s[8:9], s[46:47], 20
	s_add_u32 s48, s12, s8
	s_addc_u32 s49, s13, s9
	s_and_b64 s[8:9], s[2:3], exec
	s_cselect_b32 s47, s49, s73
	s_cselect_b32 s71, s48, s72
	s_ashr_i32 s45, s44, 31
	s_lshl_b64 s[8:9], s[44:45], 20
	s_add_u32 s50, s39, s8
	s_addc_u32 s51, s76, s9
	s_and_b64 s[8:9], s[2:3], exec
	s_cselect_b32 s45, s51, s55
	s_cselect_b32 s94, s50, s54
	s_add_u32 s8, s72, 0x80080
	s_addc_u32 s9, s73, 0
	s_mov_b32 m0, s33
	v_lshl_add_u64 v[226:227], s[8:9], 0, v[162:163]
	ds_read_b128 v[180:183], v201
	ds_read_b128 v[184:187], v201 offset:1024
	ds_read_b128 v[202:205], v201 offset:2048
	ds_read_b128 v[206:209], v201 offset:3072
	ds_read_b128 v[210:213], v201 offset:4096
	ds_read_b128 v[214:217], v201 offset:5120
	ds_read_b128 v[218:221], v201 offset:6144
	ds_read_b128 v[222:225], v201 offset:7168
	global_load_lds_dwordx4 v[226:227], off
	v_lshl_add_u64 v[226:227], s[8:9], 0, v[166:167]
	s_mov_b32 m0, s93
	s_nop 0
	global_load_lds_dwordx4 v[226:227], off
	s_waitcnt vmcnt(8)
	s_waitcnt lgkmcnt(0)
	s_barrier
	s_setprio 1
	s_waitcnt lgkmcnt(0)
	v_mfma_scale_f32_16x16x128_f8f6f4 v[158:161], v[18:25], v[180:187], 0, v199, v199 op_sel_hi:[0,0,0]
	v_mfma_scale_f32_16x16x128_f8f6f4 v[154:157], v[26:33], v[180:187], 0, v199, v199 op_sel_hi:[0,0,0]
	v_mfma_scale_f32_16x16x128_f8f6f4 v[146:149], v[26:33], v[202:209], 0, v199, v199 op_sel_hi:[0,0,0]
	v_mfma_scale_f32_16x16x128_f8f6f4 v[150:153], v[18:25], v[202:209], 0, v199, v199 op_sel_hi:[0,0,0]
	v_mfma_scale_f32_16x16x128_f8f6f4 v[142:145], v[18:25], v[210:217], 0, v199, v199 op_sel_hi:[0,0,0]
	v_mfma_scale_f32_16x16x128_f8f6f4 v[138:141], v[26:33], v[210:217], 0, v199, v199 op_sel_hi:[0,0,0]
	v_mfma_scale_f32_16x16x128_f8f6f4 v[130:133], v[26:33], v[218:225], 0, v199, v199 op_sel_hi:[0,0,0]
	v_mfma_scale_f32_16x16x128_f8f6f4 v[134:137], v[18:25], v[218:225], 0, v199, v199 op_sel_hi:[0,0,0]
	s_setprio 0
	s_setprio 1
	v_mfma_scale_f32_16x16x128_f8f6f4 v[102:105], v[2:9], v[218:225], 0, v199, v199 op_sel_hi:[0,0,0]
	v_mfma_scale_f32_16x16x128_f8f6f4 v[98:101], v[10:17], v[218:225], 0, v199, v199 op_sel_hi:[0,0,0]
	v_mfma_scale_f32_16x16x128_f8f6f4 v[106:109], v[10:17], v[210:217], 0, v199, v199 op_sel_hi:[0,0,0]
	v_mfma_scale_f32_16x16x128_f8f6f4 v[110:113], v[2:9], v[210:217], 0, v199, v199 op_sel_hi:[0,0,0]
	v_mfma_scale_f32_16x16x128_f8f6f4 v[118:121], v[2:9], v[202:209], 0, v199, v199 op_sel_hi:[0,0,0]
	v_mfma_scale_f32_16x16x128_f8f6f4 v[114:117], v[10:17], v[202:209], 0, v199, v199 op_sel_hi:[0,0,0]
	v_mfma_scale_f32_16x16x128_f8f6f4 v[122:125], v[10:17], v[180:187], 0, v199, v199 op_sel_hi:[0,0,0]
	v_mfma_scale_f32_16x16x128_f8f6f4 v[126:129], v[2:9], v[180:187], 0, v199, v199 op_sel_hi:[0,0,0]
	s_setprio 0
	s_barrier
	v_lshl_add_u64 v[180:181], s[54:55], 0, v[164:165]
	s_mov_b32 m0, s78
	v_lshl_add_u64 v[182:183], v[180:181], 0, s[26:27]
	ds_read_b128 v[202:205], v201 offset:16384
	ds_read_b128 v[206:209], v201 offset:17408
	ds_read_b128 v[210:213], v201 offset:18432
	ds_read_b128 v[214:217], v201 offset:19456
	ds_read_b128 v[218:221], v201 offset:20480
	ds_read_b128 v[222:225], v201 offset:21504
	ds_read_b128 v[226:229], v201 offset:22528
	ds_read_b128 v[230:233], v201 offset:23552
	global_load_lds_dwordx4 v[182:183], off
	v_lshl_add_u64 v[182:183], s[54:55], 0, v[168:169]
	s_add_u32 s8, s54, 0x80100
	v_lshl_add_u64 v[184:185], v[182:183], 0, s[26:27]
	s_mov_b32 m0, s79
	s_addc_u32 s9, s55, 0
	global_load_lds_dwordx4 v[184:185], off
	v_lshl_add_u64 v[184:185], s[8:9], 0, v[164:165]
	s_mov_b32 m0, s80
	s_nop 0
	global_load_lds_dwordx4 v[184:185], off
	v_lshl_add_u64 v[184:185], s[8:9], 0, v[168:169]
	s_mov_b32 m0, s81
	s_nop 0
	global_load_lds_dwordx4 v[184:185], off
	v_lshl_add_u64 v[184:185], s[72:73], 0, v[162:163]
	v_lshl_add_u64 v[186:187], v[184:185], 0, s[26:27]
	s_mov_b32 m0, s53
	s_nop 0
	global_load_lds_dwordx4 v[186:187], off
	v_lshl_add_u64 v[186:187], s[72:73], 0, v[166:167]
	v_lshl_add_u64 v[234:235], v[186:187], 0, s[26:27]
	s_mov_b32 m0, s82
	s_nop 0
	global_load_lds_dwordx4 v[234:235], off
	s_waitcnt vmcnt(8)
	s_waitcnt lgkmcnt(0)
	s_barrier
	s_setprio 1
	s_waitcnt lgkmcnt(0)
	v_mfma_scale_f32_16x16x128_f8f6f4 v[94:97], v[18:25], v[202:209], 0, v199, v199 op_sel_hi:[0,0,0]
	v_mfma_scale_f32_16x16x128_f8f6f4 v[90:93], v[26:33], v[202:209], 0, v199, v199 op_sel_hi:[0,0,0]
	v_mfma_scale_f32_16x16x128_f8f6f4 v[82:85], v[26:33], v[210:217], 0, v199, v199 op_sel_hi:[0,0,0]
	v_mfma_scale_f32_16x16x128_f8f6f4 v[86:89], v[18:25], v[210:217], 0, v199, v199 op_sel_hi:[0,0,0]
	v_mfma_scale_f32_16x16x128_f8f6f4 v[78:81], v[18:25], v[218:225], 0, v199, v199 op_sel_hi:[0,0,0]
	v_mfma_scale_f32_16x16x128_f8f6f4 v[74:77], v[26:33], v[218:225], 0, v199, v199 op_sel_hi:[0,0,0]
	v_mfma_scale_f32_16x16x128_f8f6f4 v[66:69], v[26:33], v[226:233], 0, v199, v199 op_sel_hi:[0,0,0]
	v_mfma_scale_f32_16x16x128_f8f6f4 v[70:73], v[18:25], v[226:233], 0, v199, v199 op_sel_hi:[0,0,0]
	s_setprio 0
	s_setprio 1
	v_mfma_scale_f32_16x16x128_f8f6f4 v[38:41], v[2:9], v[226:233], 0, v199, v199 op_sel_hi:[0,0,0]
	v_mfma_scale_f32_16x16x128_f8f6f4 v[34:37], v[10:17], v[226:233], 0, v199, v199 op_sel_hi:[0,0,0]
	v_mfma_scale_f32_16x16x128_f8f6f4 v[42:45], v[10:17], v[218:225], 0, v199, v199 op_sel_hi:[0,0,0]
	v_mfma_scale_f32_16x16x128_f8f6f4 v[46:49], v[2:9], v[218:225], 0, v199, v199 op_sel_hi:[0,0,0]
	v_mfma_scale_f32_16x16x128_f8f6f4 v[54:57], v[2:9], v[210:217], 0, v199, v199 op_sel_hi:[0,0,0]
	v_mfma_scale_f32_16x16x128_f8f6f4 v[50:53], v[10:17], v[210:217], 0, v199, v199 op_sel_hi:[0,0,0]
	v_mfma_scale_f32_16x16x128_f8f6f4 v[58:61], v[10:17], v[202:209], 0, v199, v199 op_sel_hi:[0,0,0]
	v_mfma_scale_f32_16x16x128_f8f6f4 v[62:65], v[2:9], v[202:209], 0, v199, v199 op_sel_hi:[0,0,0]
	s_setprio 0
	s_barrier
	ds_read_b128 v[18:21], v200 offset:32768
	ds_read_b128 v[22:25], v200 offset:33792
	ds_read_b128 v[26:29], v200 offset:34816
	ds_read_b128 v[30:33], v200 offset:35840
	ds_read_b128 v[2:5], v200 offset:49152
	ds_read_b128 v[6:9], v200 offset:50176
	ds_read_b128 v[10:13], v200 offset:51200
	ds_read_b128 v[14:17], v200 offset:52224
	s_add_u32 s8, s72, 0x80100
	s_addc_u32 s9, s73, 0
	s_mov_b32 m0, s83
	v_lshl_add_u64 v[234:235], s[8:9], 0, v[162:163]
	ds_read_b128 v[202:205], v201 offset:32768
	ds_read_b128 v[206:209], v201 offset:33792
	ds_read_b128 v[210:213], v201 offset:34816
	ds_read_b128 v[214:217], v201 offset:35840
	ds_read_b128 v[218:221], v201 offset:36864
	ds_read_b128 v[222:225], v201 offset:37888
	ds_read_b128 v[226:229], v201 offset:38912
	ds_read_b128 v[230:233], v201 offset:39936
	global_load_lds_dwordx4 v[234:235], off
	v_lshl_add_u64 v[234:235], s[8:9], 0, v[166:167]
	s_mov_b32 m0, s84
	s_nop 0
	global_load_lds_dwordx4 v[234:235], off
	s_waitcnt vmcnt(8)
	s_waitcnt lgkmcnt(0)
	s_barrier
	s_setprio 1
	s_waitcnt lgkmcnt(0)
	v_mfma_scale_f32_16x16x128_f8f6f4 v[158:161], v[18:25], v[202:209], v[158:161], v199, v199 op_sel_hi:[0,0,0]
	v_mfma_scale_f32_16x16x128_f8f6f4 v[154:157], v[26:33], v[202:209], v[154:157], v199, v199 op_sel_hi:[0,0,0]
	v_mfma_scale_f32_16x16x128_f8f6f4 v[146:149], v[26:33], v[210:217], v[146:149], v199, v199 op_sel_hi:[0,0,0]
	v_mfma_scale_f32_16x16x128_f8f6f4 v[150:153], v[18:25], v[210:217], v[150:153], v199, v199 op_sel_hi:[0,0,0]
	v_mfma_scale_f32_16x16x128_f8f6f4 v[142:145], v[18:25], v[218:225], v[142:145], v199, v199 op_sel_hi:[0,0,0]
	v_mfma_scale_f32_16x16x128_f8f6f4 v[138:141], v[26:33], v[218:225], v[138:141], v199, v199 op_sel_hi:[0,0,0]
	v_mfma_scale_f32_16x16x128_f8f6f4 v[130:133], v[26:33], v[226:233], v[130:133], v199, v199 op_sel_hi:[0,0,0]
	v_mfma_scale_f32_16x16x128_f8f6f4 v[134:137], v[18:25], v[226:233], v[134:137], v199, v199 op_sel_hi:[0,0,0]
	s_setprio 0
	s_setprio 1
	v_mfma_scale_f32_16x16x128_f8f6f4 v[102:105], v[2:9], v[226:233], v[102:105], v199, v199 op_sel_hi:[0,0,0]
	v_mfma_scale_f32_16x16x128_f8f6f4 v[98:101], v[10:17], v[226:233], v[98:101], v199, v199 op_sel_hi:[0,0,0]
	v_mfma_scale_f32_16x16x128_f8f6f4 v[106:109], v[10:17], v[218:225], v[106:109], v199, v199 op_sel_hi:[0,0,0]
	v_mfma_scale_f32_16x16x128_f8f6f4 v[110:113], v[2:9], v[218:225], v[110:113], v199, v199 op_sel_hi:[0,0,0]
	v_mfma_scale_f32_16x16x128_f8f6f4 v[118:121], v[2:9], v[210:217], v[118:121], v199, v199 op_sel_hi:[0,0,0]
	v_mfma_scale_f32_16x16x128_f8f6f4 v[114:117], v[10:17], v[210:217], v[114:117], v199, v199 op_sel_hi:[0,0,0]
	v_mfma_scale_f32_16x16x128_f8f6f4 v[122:125], v[10:17], v[202:209], v[122:125], v199, v199 op_sel_hi:[0,0,0]
	v_mfma_scale_f32_16x16x128_f8f6f4 v[126:129], v[2:9], v[202:209], v[126:129], v199, v199 op_sel_hi:[0,0,0]
	s_setprio 0
	s_barrier
	s_mov_b32 m0, s87
	v_lshl_add_u64 v[180:181], v[180:181], 0, s[36:37]
	s_add_u32 s8, s54, 0x80180
	ds_read_b128 v[202:205], v201 offset:49152
	ds_read_b128 v[206:209], v201 offset:50176
	ds_read_b128 v[210:213], v201 offset:51200
	ds_read_b128 v[214:217], v201 offset:52224
	ds_read_b128 v[218:221], v201 offset:53248
	ds_read_b128 v[222:225], v201 offset:54272
	ds_read_b128 v[226:229], v201 offset:55296
	ds_read_b128 v[230:233], v201 offset:56320
	global_load_lds_dwordx4 v[180:181], off
	v_lshl_add_u64 v[180:181], v[182:183], 0, s[36:37]
	s_mov_b32 m0, s88
	s_addc_u32 s9, s55, 0
	global_load_lds_dwordx4 v[180:181], off
	v_lshl_add_u64 v[180:181], s[8:9], 0, v[164:165]
	s_mov_b32 m0, s91
	s_nop 0
	global_load_lds_dwordx4 v[180:181], off
	v_lshl_add_u64 v[180:181], s[8:9], 0, v[168:169]
	s_mov_b32 m0, s92
	s_nop 0
	global_load_lds_dwordx4 v[180:181], off
	v_lshl_add_u64 v[180:181], v[184:185], 0, s[36:37]
	s_mov_b32 m0, s89
	s_nop 0
	global_load_lds_dwordx4 v[180:181], off
	v_lshl_add_u64 v[180:181], v[186:187], 0, s[36:37]
	s_mov_b32 m0, s90
	s_nop 0
	global_load_lds_dwordx4 v[180:181], off
	s_waitcnt vmcnt(8)
	s_waitcnt lgkmcnt(0)
	s_barrier
	s_setprio 1
	s_waitcnt lgkmcnt(0)
	v_mfma_scale_f32_16x16x128_f8f6f4 v[94:97], v[18:25], v[202:209], v[94:97], v199, v199 op_sel_hi:[0,0,0]
	v_mfma_scale_f32_16x16x128_f8f6f4 v[90:93], v[26:33], v[202:209], v[90:93], v199, v199 op_sel_hi:[0,0,0]
	v_mfma_scale_f32_16x16x128_f8f6f4 v[82:85], v[26:33], v[210:217], v[82:85], v199, v199 op_sel_hi:[0,0,0]
	v_mfma_scale_f32_16x16x128_f8f6f4 v[86:89], v[18:25], v[210:217], v[86:89], v199, v199 op_sel_hi:[0,0,0]
	v_mfma_scale_f32_16x16x128_f8f6f4 v[78:81], v[18:25], v[218:225], v[78:81], v199, v199 op_sel_hi:[0,0,0]
	v_mfma_scale_f32_16x16x128_f8f6f4 v[74:77], v[26:33], v[218:225], v[74:77], v199, v199 op_sel_hi:[0,0,0]
	v_mfma_scale_f32_16x16x128_f8f6f4 v[66:69], v[26:33], v[226:233], v[66:69], v199, v199 op_sel_hi:[0,0,0]
	v_mfma_scale_f32_16x16x128_f8f6f4 v[70:73], v[18:25], v[226:233], v[70:73], v199, v199 op_sel_hi:[0,0,0]
	s_setprio 0
	s_setprio 1
	v_mfma_scale_f32_16x16x128_f8f6f4 v[38:41], v[2:9], v[226:233], v[38:41], v199, v199 op_sel_hi:[0,0,0]
	v_mfma_scale_f32_16x16x128_f8f6f4 v[34:37], v[10:17], v[226:233], v[34:37], v199, v199 op_sel_hi:[0,0,0]
	v_mfma_scale_f32_16x16x128_f8f6f4 v[42:45], v[10:17], v[218:225], v[42:45], v199, v199 op_sel_hi:[0,0,0]
	v_mfma_scale_f32_16x16x128_f8f6f4 v[46:49], v[2:9], v[218:225], v[46:49], v199, v199 op_sel_hi:[0,0,0]
	v_mfma_scale_f32_16x16x128_f8f6f4 v[54:57], v[2:9], v[210:217], v[54:57], v199, v199 op_sel_hi:[0,0,0]
	v_mfma_scale_f32_16x16x128_f8f6f4 v[50:53], v[10:17], v[210:217], v[50:53], v199, v199 op_sel_hi:[0,0,0]
	v_mfma_scale_f32_16x16x128_f8f6f4 v[58:61], v[10:17], v[202:209], v[58:61], v199, v199 op_sel_hi:[0,0,0]
	v_mfma_scale_f32_16x16x128_f8f6f4 v[62:65], v[2:9], v[202:209], v[62:65], v199, v199 op_sel_hi:[0,0,0]
	s_setprio 0
	s_barrier
	s_add_u32 s72, s72, 0x80180
	s_addc_u32 s73, s73, 0
	s_add_u32 s8, s54, 0x200
	s_addc_u32 s9, s55, 0
	s_mov_b32 s62, 0
.LBB0_438:
	ds_read_b128 v[2:5], v200
	ds_read_b128 v[6:9], v200 offset:1024
	ds_read_b128 v[18:21], v200 offset:2048
	ds_read_b128 v[22:25], v200 offset:3072
	ds_read_b128 v[26:29], v200 offset:16384
	ds_read_b128 v[30:33], v200 offset:17408
	ds_read_b128 v[180:183], v200 offset:18432
	ds_read_b128 v[184:187], v200 offset:19456
	s_add_u32 s54, s72, 0xfff80080
	s_addc_u32 s55, s73, -1
	s_cmp_eq_u32 s62, 28
	s_cselect_b32 s75, s47, s55
	s_cselect_b32 s74, s71, s54
	s_cselect_b32 s55, s45, s9
	s_cselect_b32 s54, s94, s8
	s_mov_b32 m0, s33
	v_lshl_add_u64 v[226:227], s[72:73], 0, v[170:171]
	ds_read_b128 v[10:13], v201
	ds_read_b128 v[14:17], v201 offset:1024
	ds_read_b128 v[202:205], v201 offset:2048
	ds_read_b128 v[206:209], v201 offset:3072
	ds_read_b128 v[210:213], v201 offset:4096
	ds_read_b128 v[214:217], v201 offset:5120
	ds_read_b128 v[218:221], v201 offset:6144
	ds_read_b128 v[222:225], v201 offset:7168
	global_load_lds_dwordx4 v[226:227], off
	v_lshl_add_u64 v[226:227], s[72:73], 0, v[172:173]
	s_mov_b32 m0, s93
	s_nop 0
	global_load_lds_dwordx4 v[226:227], off
	s_waitcnt vmcnt(8)
	s_waitcnt lgkmcnt(0)
	s_barrier
	s_setprio 1
	s_waitcnt lgkmcnt(0)
	v_mfma_scale_f32_16x16x128_f8f6f4 v[158:161], v[2:9], v[10:17], v[158:161], v199, v199 op_sel_hi:[0,0,0]
	v_mfma_scale_f32_16x16x128_f8f6f4 v[154:157], v[18:25], v[10:17], v[154:157], v199, v199 op_sel_hi:[0,0,0]
	v_mfma_scale_f32_16x16x128_f8f6f4 v[146:149], v[18:25], v[202:209], v[146:149], v199, v199 op_sel_hi:[0,0,0]
	v_mfma_scale_f32_16x16x128_f8f6f4 v[150:153], v[2:9], v[202:209], v[150:153], v199, v199 op_sel_hi:[0,0,0]
	v_mfma_scale_f32_16x16x128_f8f6f4 v[142:145], v[2:9], v[210:217], v[142:145], v199, v199 op_sel_hi:[0,0,0]
	v_mfma_scale_f32_16x16x128_f8f6f4 v[138:141], v[18:25], v[210:217], v[138:141], v199, v199 op_sel_hi:[0,0,0]
	v_mfma_scale_f32_16x16x128_f8f6f4 v[130:133], v[18:25], v[218:225], v[130:133], v199, v199 op_sel_hi:[0,0,0]
	v_mfma_scale_f32_16x16x128_f8f6f4 v[134:137], v[2:9], v[218:225], v[134:137], v199, v199 op_sel_hi:[0,0,0]
	s_setprio 0
	s_setprio 1
	v_mfma_scale_f32_16x16x128_f8f6f4 v[102:105], v[26:33], v[218:225], v[102:105], v199, v199 op_sel_hi:[0,0,0]
	v_mfma_scale_f32_16x16x128_f8f6f4 v[98:101], v[180:187], v[218:225], v[98:101], v199, v199 op_sel_hi:[0,0,0]
	v_mfma_scale_f32_16x16x128_f8f6f4 v[106:109], v[180:187], v[210:217], v[106:109], v199, v199 op_sel_hi:[0,0,0]
	v_mfma_scale_f32_16x16x128_f8f6f4 v[110:113], v[26:33], v[210:217], v[110:113], v199, v199 op_sel_hi:[0,0,0]
	v_mfma_scale_f32_16x16x128_f8f6f4 v[118:121], v[26:33], v[202:209], v[118:121], v199, v199 op_sel_hi:[0,0,0]
	v_mfma_scale_f32_16x16x128_f8f6f4 v[114:117], v[180:187], v[202:209], v[114:117], v199, v199 op_sel_hi:[0,0,0]
	v_mfma_scale_f32_16x16x128_f8f6f4 v[122:125], v[180:187], v[10:17], v[122:125], v199, v199 op_sel_hi:[0,0,0]
	v_mfma_scale_f32_16x16x128_f8f6f4 v[126:129], v[26:33], v[10:17], v[126:129], v199, v199 op_sel_hi:[0,0,0]
	s_setprio 0
	s_barrier
	s_mov_b32 m0, s78
	v_lshl_add_u64 v[10:11], s[54:55], 0, v[164:165]
	s_add_u32 s96, s54, 0x80000
	ds_read_b128 v[202:205], v201 offset:16384
	ds_read_b128 v[206:209], v201 offset:17408
	ds_read_b128 v[210:213], v201 offset:18432
	ds_read_b128 v[214:217], v201 offset:19456
	ds_read_b128 v[218:221], v201 offset:20480
	ds_read_b128 v[222:225], v201 offset:21504
	ds_read_b128 v[226:229], v201 offset:22528
	ds_read_b128 v[230:233], v201 offset:23552
	global_load_lds_dwordx4 v[10:11], off
	v_lshl_add_u64 v[12:13], s[54:55], 0, v[168:169]
	s_mov_b32 m0, s79
	s_addc_u32 s97, s55, 0
	global_load_lds_dwordx4 v[12:13], off
	v_lshl_add_u64 v[14:15], s[96:97], 0, v[164:165]
	s_mov_b32 m0, s80
	v_lshl_add_u64 v[16:17], s[74:75], 0, v[166:167]
	global_load_lds_dwordx4 v[14:15], off
	v_lshl_add_u64 v[14:15], s[96:97], 0, v[168:169]
	s_mov_b32 m0, s81
	s_nop 0
	global_load_lds_dwordx4 v[14:15], off
	v_lshl_add_u64 v[14:15], s[74:75], 0, v[162:163]
	s_mov_b32 m0, s53
	s_nop 0
	global_load_lds_dwordx4 v[14:15], off
	s_mov_b32 m0, s82
	s_nop 0
	global_load_lds_dwordx4 v[16:17], off
	s_waitcnt vmcnt(8)
	s_waitcnt lgkmcnt(0)
	s_barrier
	s_setprio 1
	s_waitcnt lgkmcnt(0)
	v_mfma_scale_f32_16x16x128_f8f6f4 v[94:97], v[2:9], v[202:209], v[94:97], v199, v199 op_sel_hi:[0,0,0]
	v_mfma_scale_f32_16x16x128_f8f6f4 v[90:93], v[18:25], v[202:209], v[90:93], v199, v199 op_sel_hi:[0,0,0]
	v_mfma_scale_f32_16x16x128_f8f6f4 v[82:85], v[18:25], v[210:217], v[82:85], v199, v199 op_sel_hi:[0,0,0]
	v_mfma_scale_f32_16x16x128_f8f6f4 v[86:89], v[2:9], v[210:217], v[86:89], v199, v199 op_sel_hi:[0,0,0]
	v_mfma_scale_f32_16x16x128_f8f6f4 v[78:81], v[2:9], v[218:225], v[78:81], v199, v199 op_sel_hi:[0,0,0]
	v_mfma_scale_f32_16x16x128_f8f6f4 v[74:77], v[18:25], v[218:225], v[74:77], v199, v199 op_sel_hi:[0,0,0]
	v_mfma_scale_f32_16x16x128_f8f6f4 v[66:69], v[18:25], v[226:233], v[66:69], v199, v199 op_sel_hi:[0,0,0]
	v_mfma_scale_f32_16x16x128_f8f6f4 v[70:73], v[2:9], v[226:233], v[70:73], v199, v199 op_sel_hi:[0,0,0]
	s_setprio 0
	s_setprio 1
	v_mfma_scale_f32_16x16x128_f8f6f4 v[38:41], v[26:33], v[226:233], v[38:41], v199, v199 op_sel_hi:[0,0,0]
	v_mfma_scale_f32_16x16x128_f8f6f4 v[34:37], v[180:187], v[226:233], v[34:37], v199, v199 op_sel_hi:[0,0,0]
	v_mfma_scale_f32_16x16x128_f8f6f4 v[42:45], v[180:187], v[218:225], v[42:45], v199, v199 op_sel_hi:[0,0,0]
	v_mfma_scale_f32_16x16x128_f8f6f4 v[46:49], v[26:33], v[218:225], v[46:49], v199, v199 op_sel_hi:[0,0,0]
	v_mfma_scale_f32_16x16x128_f8f6f4 v[54:57], v[26:33], v[210:217], v[54:57], v199, v199 op_sel_hi:[0,0,0]
	v_mfma_scale_f32_16x16x128_f8f6f4 v[50:53], v[180:187], v[210:217], v[50:53], v199, v199 op_sel_hi:[0,0,0]
	v_mfma_scale_f32_16x16x128_f8f6f4 v[58:61], v[180:187], v[202:209], v[58:61], v199, v199 op_sel_hi:[0,0,0]
	v_mfma_scale_f32_16x16x128_f8f6f4 v[62:65], v[26:33], v[202:209], v[62:65], v199, v199 op_sel_hi:[0,0,0]
	s_setprio 0
	s_barrier
	ds_read_b128 v[18:21], v200 offset:32768
	ds_read_b128 v[22:25], v200 offset:33792
	ds_read_b128 v[26:29], v200 offset:34816
	ds_read_b128 v[30:33], v200 offset:35840
	ds_read_b128 v[2:5], v200 offset:49152
	ds_read_b128 v[6:9], v200 offset:50176
	ds_read_b128 v[180:183], v200 offset:51200
	ds_read_b128 v[184:187], v200 offset:52224
	s_add_u32 s74, s74, 0x80000
	s_addc_u32 s75, s75, 0
	s_mov_b32 m0, s83
	v_lshl_add_u64 v[234:235], s[74:75], 0, v[162:163]
	ds_read_b128 v[202:205], v201 offset:32768
	ds_read_b128 v[206:209], v201 offset:33792
	ds_read_b128 v[210:213], v201 offset:34816
	ds_read_b128 v[214:217], v201 offset:35840
	ds_read_b128 v[218:221], v201 offset:36864
	ds_read_b128 v[222:225], v201 offset:37888
	ds_read_b128 v[226:229], v201 offset:38912
	ds_read_b128 v[230:233], v201 offset:39936
	global_load_lds_dwordx4 v[234:235], off
	v_lshl_add_u64 v[234:235], s[74:75], 0, v[166:167]
	s_mov_b32 m0, s84
	s_nop 0
	global_load_lds_dwordx4 v[234:235], off
	s_waitcnt vmcnt(8)
	s_waitcnt lgkmcnt(0)
	s_barrier
	s_setprio 1
	s_waitcnt lgkmcnt(0)
	v_mfma_scale_f32_16x16x128_f8f6f4 v[158:161], v[18:25], v[202:209], v[158:161], v199, v199 op_sel_hi:[0,0,0]
	v_mfma_scale_f32_16x16x128_f8f6f4 v[154:157], v[26:33], v[202:209], v[154:157], v199, v199 op_sel_hi:[0,0,0]
	v_mfma_scale_f32_16x16x128_f8f6f4 v[146:149], v[26:33], v[210:217], v[146:149], v199, v199 op_sel_hi:[0,0,0]
	v_mfma_scale_f32_16x16x128_f8f6f4 v[150:153], v[18:25], v[210:217], v[150:153], v199, v199 op_sel_hi:[0,0,0]
	v_mfma_scale_f32_16x16x128_f8f6f4 v[142:145], v[18:25], v[218:225], v[142:145], v199, v199 op_sel_hi:[0,0,0]
	v_mfma_scale_f32_16x16x128_f8f6f4 v[138:141], v[26:33], v[218:225], v[138:141], v199, v199 op_sel_hi:[0,0,0]
	v_mfma_scale_f32_16x16x128_f8f6f4 v[130:133], v[26:33], v[226:233], v[130:133], v199, v199 op_sel_hi:[0,0,0]
	v_mfma_scale_f32_16x16x128_f8f6f4 v[134:137], v[18:25], v[226:233], v[134:137], v199, v199 op_sel_hi:[0,0,0]
	s_setprio 0
	s_setprio 1
	v_mfma_scale_f32_16x16x128_f8f6f4 v[102:105], v[2:9], v[226:233], v[102:105], v199, v199 op_sel_hi:[0,0,0]
	v_mfma_scale_f32_16x16x128_f8f6f4 v[98:101], v[180:187], v[226:233], v[98:101], v199, v199 op_sel_hi:[0,0,0]
	v_mfma_scale_f32_16x16x128_f8f6f4 v[106:109], v[180:187], v[218:225], v[106:109], v199, v199 op_sel_hi:[0,0,0]
	v_mfma_scale_f32_16x16x128_f8f6f4 v[110:113], v[2:9], v[218:225], v[110:113], v199, v199 op_sel_hi:[0,0,0]
	v_mfma_scale_f32_16x16x128_f8f6f4 v[118:121], v[2:9], v[210:217], v[118:121], v199, v199 op_sel_hi:[0,0,0]
	v_mfma_scale_f32_16x16x128_f8f6f4 v[114:117], v[180:187], v[210:217], v[114:117], v199, v199 op_sel_hi:[0,0,0]
	v_mfma_scale_f32_16x16x128_f8f6f4 v[122:125], v[180:187], v[202:209], v[122:125], v199, v199 op_sel_hi:[0,0,0]
	v_mfma_scale_f32_16x16x128_f8f6f4 v[126:129], v[2:9], v[202:209], v[126:129], v199, v199 op_sel_hi:[0,0,0]
	s_setprio 0
	s_barrier
	s_mov_b32 m0, s87
	v_lshl_add_u64 v[10:11], v[10:11], 0, s[4:5]
	s_add_u32 s54, s54, 0x80080
	ds_read_b128 v[202:205], v201 offset:49152
	ds_read_b128 v[206:209], v201 offset:50176
	ds_read_b128 v[210:213], v201 offset:51200
	ds_read_b128 v[214:217], v201 offset:52224
	ds_read_b128 v[218:221], v201 offset:53248
	ds_read_b128 v[222:225], v201 offset:54272
	ds_read_b128 v[226:229], v201 offset:55296
	ds_read_b128 v[230:233], v201 offset:56320
	global_load_lds_dwordx4 v[10:11], off
	v_lshl_add_u64 v[10:11], v[12:13], 0, s[4:5]
	s_mov_b32 m0, s88
	s_addc_u32 s55, s55, 0
	global_load_lds_dwordx4 v[10:11], off
	v_lshl_add_u64 v[10:11], s[54:55], 0, v[164:165]
	s_mov_b32 m0, s91
	s_nop 0
	global_load_lds_dwordx4 v[10:11], off
	v_lshl_add_u64 v[10:11], s[54:55], 0, v[168:169]
	s_mov_b32 m0, s92
	s_nop 0
	global_load_lds_dwordx4 v[10:11], off
	v_lshl_add_u64 v[10:11], v[14:15], 0, s[4:5]
	s_mov_b32 m0, s89
	s_nop 0
	global_load_lds_dwordx4 v[10:11], off
	v_lshl_add_u64 v[10:11], v[16:17], 0, s[4:5]
	s_mov_b32 m0, s90
	s_nop 0
	global_load_lds_dwordx4 v[10:11], off
	s_waitcnt vmcnt(8)
	s_waitcnt lgkmcnt(0)
	s_barrier
	s_setprio 1
	s_waitcnt lgkmcnt(0)
	v_mfma_scale_f32_16x16x128_f8f6f4 v[94:97], v[18:25], v[202:209], v[94:97], v199, v199 op_sel_hi:[0,0,0]
	v_mfma_scale_f32_16x16x128_f8f6f4 v[90:93], v[26:33], v[202:209], v[90:93], v199, v199 op_sel_hi:[0,0,0]
	v_mfma_scale_f32_16x16x128_f8f6f4 v[82:85], v[26:33], v[210:217], v[82:85], v199, v199 op_sel_hi:[0,0,0]
	v_mfma_scale_f32_16x16x128_f8f6f4 v[86:89], v[18:25], v[210:217], v[86:89], v199, v199 op_sel_hi:[0,0,0]
	v_mfma_scale_f32_16x16x128_f8f6f4 v[78:81], v[18:25], v[218:225], v[78:81], v199, v199 op_sel_hi:[0,0,0]
	v_mfma_scale_f32_16x16x128_f8f6f4 v[74:77], v[26:33], v[218:225], v[74:77], v199, v199 op_sel_hi:[0,0,0]
	v_mfma_scale_f32_16x16x128_f8f6f4 v[66:69], v[26:33], v[226:233], v[66:69], v199, v199 op_sel_hi:[0,0,0]
	v_mfma_scale_f32_16x16x128_f8f6f4 v[70:73], v[18:25], v[226:233], v[70:73], v199, v199 op_sel_hi:[0,0,0]
	s_setprio 0
	s_setprio 1
	v_mfma_scale_f32_16x16x128_f8f6f4 v[38:41], v[2:9], v[226:233], v[38:41], v199, v199 op_sel_hi:[0,0,0]
	v_mfma_scale_f32_16x16x128_f8f6f4 v[34:37], v[180:187], v[226:233], v[34:37], v199, v199 op_sel_hi:[0,0,0]
	v_mfma_scale_f32_16x16x128_f8f6f4 v[42:45], v[180:187], v[218:225], v[42:45], v199, v199 op_sel_hi:[0,0,0]
	v_mfma_scale_f32_16x16x128_f8f6f4 v[46:49], v[2:9], v[218:225], v[46:49], v199, v199 op_sel_hi:[0,0,0]
	v_mfma_scale_f32_16x16x128_f8f6f4 v[54:57], v[2:9], v[210:217], v[54:57], v199, v199 op_sel_hi:[0,0,0]
	v_mfma_scale_f32_16x16x128_f8f6f4 v[50:53], v[180:187], v[210:217], v[50:53], v199, v199 op_sel_hi:[0,0,0]
	v_mfma_scale_f32_16x16x128_f8f6f4 v[58:61], v[180:187], v[202:209], v[58:61], v199, v199 op_sel_hi:[0,0,0]
	v_mfma_scale_f32_16x16x128_f8f6f4 v[62:65], v[2:9], v[202:209], v[62:65], v199, v199 op_sel_hi:[0,0,0]
	s_setprio 0
	s_barrier
	s_add_i32 s62, s62, 2
	s_add_u32 s72, s72, 0x100
	s_addc_u32 s73, s73, 0
	s_add_u32 s8, s8, 0x100
	s_addc_u32 s9, s9, 0
	s_cmp_gt_u32 s62, 29
	s_cbranch_scc0 .LBB0_438
	s_and_b64 vcc, exec, s[6:7]
	s_cbranch_vccz .LBB0_441
	s_barrier

.LBB0_600:
	s_ashr_i32 s55, s54, 31
	ds_read_b128 v[18:21], v200
	ds_read_b128 v[22:25], v200 offset:1024
	ds_read_b128 v[26:29], v200 offset:2048
	ds_read_b128 v[30:33], v200 offset:3072
	ds_read_b128 v[2:5], v200 offset:16384
	ds_read_b128 v[6:9], v200 offset:17408
	ds_read_b128 v[10:13], v200 offset:18432
	ds_read_b128 v[14:17], v200 offset:19456
	s_lshl_b64 s[4:5], s[54:55], 18
	s_add_u32 s72, s38, s4
	s_addc_u32 s73, s39, s5
	s_and_b64 s[4:5], s[2:3], exec
	s_cselect_b32 s4, s73, s81
	s_cselect_b32 s5, s72, s80
	s_ashr_i32 s53, s52, 31
	s_lshl_b64 s[8:9], s[52:53], 18
	s_add_u32 s74, s94, s8
	v_readlane_b32 s8, v254, 6
	s_addc_u32 s75, s8, s9
	s_and_b64 s[8:9], s[2:3], exec
	s_cselect_b32 s53, s75, s79
	s_cselect_b32 s55, s74, s78
	s_add_u32 s8, s80, 0x20080
	s_addc_u32 s9, s81, 0
	s_mov_b32 m0, s96
	v_lshl_add_u64 v[226:227], s[8:9], 0, v[162:163]
	ds_read_b128 v[182:185], v201
	ds_read_b128 v[186:189], v201 offset:1024
	ds_read_b128 v[202:205], v201 offset:2048
	ds_read_b128 v[206:209], v201 offset:3072
	ds_read_b128 v[210:213], v201 offset:4096
	ds_read_b128 v[214:217], v201 offset:5120
	ds_read_b128 v[218:221], v201 offset:6144
	ds_read_b128 v[222:225], v201 offset:7168
	global_load_lds_dwordx4 v[226:227], off
	v_lshl_add_u64 v[226:227], s[8:9], 0, v[166:167]
	s_mov_b32 m0, s61
	s_nop 0
	global_load_lds_dwordx4 v[226:227], off
	s_waitcnt vmcnt(8)
	s_waitcnt lgkmcnt(0)
	s_barrier
	s_setprio 1
	s_waitcnt lgkmcnt(0)
	v_mfma_scale_f32_16x16x128_f8f6f4 v[158:161], v[18:25], v[182:189], 0, v199, v199 op_sel_hi:[0,0,0]
	v_mfma_scale_f32_16x16x128_f8f6f4 v[154:157], v[26:33], v[182:189], 0, v199, v199 op_sel_hi:[0,0,0]
	v_mfma_scale_f32_16x16x128_f8f6f4 v[146:149], v[26:33], v[202:209], 0, v199, v199 op_sel_hi:[0,0,0]
	v_mfma_scale_f32_16x16x128_f8f6f4 v[150:153], v[18:25], v[202:209], 0, v199, v199 op_sel_hi:[0,0,0]
	v_mfma_scale_f32_16x16x128_f8f6f4 v[142:145], v[18:25], v[210:217], 0, v199, v199 op_sel_hi:[0,0,0]
	v_mfma_scale_f32_16x16x128_f8f6f4 v[138:141], v[26:33], v[210:217], 0, v199, v199 op_sel_hi:[0,0,0]
	v_mfma_scale_f32_16x16x128_f8f6f4 v[130:133], v[26:33], v[218:225], 0, v199, v199 op_sel_hi:[0,0,0]
	v_mfma_scale_f32_16x16x128_f8f6f4 v[134:137], v[18:25], v[218:225], 0, v199, v199 op_sel_hi:[0,0,0]
	s_setprio 0
	s_setprio 1
	v_mfma_scale_f32_16x16x128_f8f6f4 v[102:105], v[2:9], v[218:225], 0, v199, v199 op_sel_hi:[0,0,0]
	v_mfma_scale_f32_16x16x128_f8f6f4 v[98:101], v[10:17], v[218:225], 0, v199, v199 op_sel_hi:[0,0,0]
	v_mfma_scale_f32_16x16x128_f8f6f4 v[106:109], v[10:17], v[210:217], 0, v199, v199 op_sel_hi:[0,0,0]
	v_mfma_scale_f32_16x16x128_f8f6f4 v[110:113], v[2:9], v[210:217], 0, v199, v199 op_sel_hi:[0,0,0]
	v_mfma_scale_f32_16x16x128_f8f6f4 v[118:121], v[2:9], v[202:209], 0, v199, v199 op_sel_hi:[0,0,0]
	v_mfma_scale_f32_16x16x128_f8f6f4 v[114:117], v[10:17], v[202:209], 0, v199, v199 op_sel_hi:[0,0,0]
	v_mfma_scale_f32_16x16x128_f8f6f4 v[122:125], v[10:17], v[182:189], 0, v199, v199 op_sel_hi:[0,0,0]
	v_mfma_scale_f32_16x16x128_f8f6f4 v[126:129], v[2:9], v[182:189], 0, v199, v199 op_sel_hi:[0,0,0]
	s_setprio 0
	s_barrier
	v_lshl_add_u64 v[182:183], s[78:79], 0, v[164:165]
	s_mov_b32 m0, s68
	v_lshl_add_u64 v[184:185], v[182:183], 0, s[46:47]
	ds_read_b128 v[202:205], v201 offset:16384
	ds_read_b128 v[206:209], v201 offset:17408
	ds_read_b128 v[210:213], v201 offset:18432
	ds_read_b128 v[214:217], v201 offset:19456
	ds_read_b128 v[218:221], v201 offset:20480
	ds_read_b128 v[222:225], v201 offset:21504
	ds_read_b128 v[226:229], v201 offset:22528
	ds_read_b128 v[230:233], v201 offset:23552
	global_load_lds_dwordx4 v[184:185], off
	v_lshl_add_u64 v[184:185], s[78:79], 0, v[168:169]
	s_add_u32 s8, s78, 0x20100
	v_lshl_add_u64 v[186:187], v[184:185], 0, s[46:47]
	s_mov_b32 m0, s69
	s_addc_u32 s9, s79, 0
	global_load_lds_dwordx4 v[186:187], off
	v_lshl_add_u64 v[186:187], s[8:9], 0, v[164:165]
	s_mov_b32 m0, s77
	s_nop 0
	global_load_lds_dwordx4 v[186:187], off
	v_lshl_add_u64 v[186:187], s[8:9], 0, v[168:169]
	s_mov_b32 m0, s84
	s_nop 0
	global_load_lds_dwordx4 v[186:187], off
	v_lshl_add_u64 v[186:187], s[80:81], 0, v[162:163]
	v_lshl_add_u64 v[188:189], v[186:187], 0, s[46:47]
	s_mov_b32 m0, s33
	s_nop 0
	global_load_lds_dwordx4 v[188:189], off
	v_lshl_add_u64 v[188:189], s[80:81], 0, v[166:167]
	v_lshl_add_u64 v[234:235], v[188:189], 0, s[46:47]
	s_mov_b32 m0, s85
	s_nop 0
	global_load_lds_dwordx4 v[234:235], off
	s_waitcnt vmcnt(8)
	s_waitcnt lgkmcnt(0)
	s_barrier
	s_setprio 1
	s_waitcnt lgkmcnt(0)
	v_mfma_scale_f32_16x16x128_f8f6f4 v[94:97], v[18:25], v[202:209], 0, v199, v199 op_sel_hi:[0,0,0]
	v_mfma_scale_f32_16x16x128_f8f6f4 v[90:93], v[26:33], v[202:209], 0, v199, v199 op_sel_hi:[0,0,0]
	v_mfma_scale_f32_16x16x128_f8f6f4 v[82:85], v[26:33], v[210:217], 0, v199, v199 op_sel_hi:[0,0,0]
	v_mfma_scale_f32_16x16x128_f8f6f4 v[86:89], v[18:25], v[210:217], 0, v199, v199 op_sel_hi:[0,0,0]
	v_mfma_scale_f32_16x16x128_f8f6f4 v[78:81], v[18:25], v[218:225], 0, v199, v199 op_sel_hi:[0,0,0]
	v_mfma_scale_f32_16x16x128_f8f6f4 v[74:77], v[26:33], v[218:225], 0, v199, v199 op_sel_hi:[0,0,0]
	v_mfma_scale_f32_16x16x128_f8f6f4 v[66:69], v[26:33], v[226:233], 0, v199, v199 op_sel_hi:[0,0,0]
	v_mfma_scale_f32_16x16x128_f8f6f4 v[70:73], v[18:25], v[226:233], 0, v199, v199 op_sel_hi:[0,0,0]
	s_setprio 0
	s_setprio 1
	v_mfma_scale_f32_16x16x128_f8f6f4 v[38:41], v[2:9], v[226:233], 0, v199, v199 op_sel_hi:[0,0,0]
	v_mfma_scale_f32_16x16x128_f8f6f4 v[34:37], v[10:17], v[226:233], 0, v199, v199 op_sel_hi:[0,0,0]
	v_mfma_scale_f32_16x16x128_f8f6f4 v[42:45], v[10:17], v[218:225], 0, v199, v199 op_sel_hi:[0,0,0]
	v_mfma_scale_f32_16x16x128_f8f6f4 v[46:49], v[2:9], v[218:225], 0, v199, v199 op_sel_hi:[0,0,0]
	v_mfma_scale_f32_16x16x128_f8f6f4 v[54:57], v[2:9], v[210:217], 0, v199, v199 op_sel_hi:[0,0,0]
	v_mfma_scale_f32_16x16x128_f8f6f4 v[50:53], v[10:17], v[210:217], 0, v199, v199 op_sel_hi:[0,0,0]
	v_mfma_scale_f32_16x16x128_f8f6f4 v[58:61], v[10:17], v[202:209], 0, v199, v199 op_sel_hi:[0,0,0]
	v_mfma_scale_f32_16x16x128_f8f6f4 v[62:65], v[2:9], v[202:209], 0, v199, v199 op_sel_hi:[0,0,0]
	s_setprio 0
	s_barrier
	ds_read_b128 v[18:21], v200 offset:32768
	ds_read_b128 v[22:25], v200 offset:33792
	ds_read_b128 v[26:29], v200 offset:34816
	ds_read_b128 v[30:33], v200 offset:35840
	ds_read_b128 v[2:5], v200 offset:49152
	ds_read_b128 v[6:9], v200 offset:50176
	ds_read_b128 v[10:13], v200 offset:51200
	ds_read_b128 v[14:17], v200 offset:52224
	s_add_u32 s8, s80, 0x20100
	s_addc_u32 s9, s81, 0
	s_mov_b32 m0, s86
	v_lshl_add_u64 v[234:235], s[8:9], 0, v[162:163]
	ds_read_b128 v[202:205], v201 offset:32768
	ds_read_b128 v[206:209], v201 offset:33792
	ds_read_b128 v[210:213], v201 offset:34816
	ds_read_b128 v[214:217], v201 offset:35840
	ds_read_b128 v[218:221], v201 offset:36864
	ds_read_b128 v[222:225], v201 offset:37888
	ds_read_b128 v[226:229], v201 offset:38912
	ds_read_b128 v[230:233], v201 offset:39936
	global_load_lds_dwordx4 v[234:235], off
	v_lshl_add_u64 v[234:235], s[8:9], 0, v[166:167]
	s_mov_b32 m0, s87
	s_nop 0
	global_load_lds_dwordx4 v[234:235], off
	s_waitcnt vmcnt(8)
	s_waitcnt lgkmcnt(0)
	s_barrier
	s_setprio 1
	s_waitcnt lgkmcnt(0)
	v_mfma_scale_f32_16x16x128_f8f6f4 v[158:161], v[18:25], v[202:209], v[158:161], v199, v199 op_sel_hi:[0,0,0]
	v_mfma_scale_f32_16x16x128_f8f6f4 v[154:157], v[26:33], v[202:209], v[154:157], v199, v199 op_sel_hi:[0,0,0]
	v_mfma_scale_f32_16x16x128_f8f6f4 v[146:149], v[26:33], v[210:217], v[146:149], v199, v199 op_sel_hi:[0,0,0]
	v_mfma_scale_f32_16x16x128_f8f6f4 v[150:153], v[18:25], v[210:217], v[150:153], v199, v199 op_sel_hi:[0,0,0]
	v_mfma_scale_f32_16x16x128_f8f6f4 v[142:145], v[18:25], v[218:225], v[142:145], v199, v199 op_sel_hi:[0,0,0]
	v_mfma_scale_f32_16x16x128_f8f6f4 v[138:141], v[26:33], v[218:225], v[138:141], v199, v199 op_sel_hi:[0,0,0]
	v_mfma_scale_f32_16x16x128_f8f6f4 v[130:133], v[26:33], v[226:233], v[130:133], v199, v199 op_sel_hi:[0,0,0]
	v_mfma_scale_f32_16x16x128_f8f6f4 v[134:137], v[18:25], v[226:233], v[134:137], v199, v199 op_sel_hi:[0,0,0]
	s_setprio 0
	s_setprio 1
	v_mfma_scale_f32_16x16x128_f8f6f4 v[102:105], v[2:9], v[226:233], v[102:105], v199, v199 op_sel_hi:[0,0,0]
	v_mfma_scale_f32_16x16x128_f8f6f4 v[98:101], v[10:17], v[226:233], v[98:101], v199, v199 op_sel_hi:[0,0,0]
	v_mfma_scale_f32_16x16x128_f8f6f4 v[106:109], v[10:17], v[218:225], v[106:109], v199, v199 op_sel_hi:[0,0,0]
	v_mfma_scale_f32_16x16x128_f8f6f4 v[110:113], v[2:9], v[218:225], v[110:113], v199, v199 op_sel_hi:[0,0,0]
	v_mfma_scale_f32_16x16x128_f8f6f4 v[118:121], v[2:9], v[210:217], v[118:121], v199, v199 op_sel_hi:[0,0,0]
	v_mfma_scale_f32_16x16x128_f8f6f4 v[114:117], v[10:17], v[210:217], v[114:117], v199, v199 op_sel_hi:[0,0,0]
	v_mfma_scale_f32_16x16x128_f8f6f4 v[122:125], v[10:17], v[202:209], v[122:125], v199, v199 op_sel_hi:[0,0,0]
	v_mfma_scale_f32_16x16x128_f8f6f4 v[126:129], v[2:9], v[202:209], v[126:129], v199, v199 op_sel_hi:[0,0,0]
	s_setprio 0
	s_barrier
	s_mov_b32 m0, s89
	v_lshl_add_u64 v[182:183], v[182:183], 0, s[48:49]
	s_add_u32 s8, s78, 0x20180
	ds_read_b128 v[202:205], v201 offset:49152
	ds_read_b128 v[206:209], v201 offset:50176
	ds_read_b128 v[210:213], v201 offset:51200
	ds_read_b128 v[214:217], v201 offset:52224
	ds_read_b128 v[218:221], v201 offset:53248
	ds_read_b128 v[222:225], v201 offset:54272
	ds_read_b128 v[226:229], v201 offset:55296
	ds_read_b128 v[230:233], v201 offset:56320
	global_load_lds_dwordx4 v[182:183], off
	v_lshl_add_u64 v[182:183], v[184:185], 0, s[48:49]
	s_mov_b32 m0, s90
	s_addc_u32 s9, s79, 0
	global_load_lds_dwordx4 v[182:183], off
	v_lshl_add_u64 v[182:183], s[8:9], 0, v[164:165]
	s_mov_b32 m0, s93
	s_nop 0
	global_load_lds_dwordx4 v[182:183], off
	v_lshl_add_u64 v[182:183], s[8:9], 0, v[168:169]
	s_mov_b32 m0, s95
	s_nop 0
	global_load_lds_dwordx4 v[182:183], off
	v_lshl_add_u64 v[182:183], v[186:187], 0, s[48:49]
	s_mov_b32 m0, s91
	s_nop 0
	global_load_lds_dwordx4 v[182:183], off
	v_lshl_add_u64 v[182:183], v[188:189], 0, s[48:49]
	s_mov_b32 m0, s92
	s_nop 0
	global_load_lds_dwordx4 v[182:183], off
	s_waitcnt vmcnt(8)
	s_waitcnt lgkmcnt(0)
	s_barrier
	s_setprio 1
	s_waitcnt lgkmcnt(0)
	v_mfma_scale_f32_16x16x128_f8f6f4 v[94:97], v[18:25], v[202:209], v[94:97], v199, v199 op_sel_hi:[0,0,0]
	v_mfma_scale_f32_16x16x128_f8f6f4 v[90:93], v[26:33], v[202:209], v[90:93], v199, v199 op_sel_hi:[0,0,0]
	v_mfma_scale_f32_16x16x128_f8f6f4 v[82:85], v[26:33], v[210:217], v[82:85], v199, v199 op_sel_hi:[0,0,0]
	v_mfma_scale_f32_16x16x128_f8f6f4 v[86:89], v[18:25], v[210:217], v[86:89], v199, v199 op_sel_hi:[0,0,0]
	v_mfma_scale_f32_16x16x128_f8f6f4 v[78:81], v[18:25], v[218:225], v[78:81], v199, v199 op_sel_hi:[0,0,0]
	v_mfma_scale_f32_16x16x128_f8f6f4 v[74:77], v[26:33], v[218:225], v[74:77], v199, v199 op_sel_hi:[0,0,0]
	v_mfma_scale_f32_16x16x128_f8f6f4 v[66:69], v[26:33], v[226:233], v[66:69], v199, v199 op_sel_hi:[0,0,0]
	v_mfma_scale_f32_16x16x128_f8f6f4 v[70:73], v[18:25], v[226:233], v[70:73], v199, v199 op_sel_hi:[0,0,0]
	s_setprio 0
	s_setprio 1
	v_mfma_scale_f32_16x16x128_f8f6f4 v[38:41], v[2:9], v[226:233], v[38:41], v199, v199 op_sel_hi:[0,0,0]
	v_mfma_scale_f32_16x16x128_f8f6f4 v[34:37], v[10:17], v[226:233], v[34:37], v199, v199 op_sel_hi:[0,0,0]
	v_mfma_scale_f32_16x16x128_f8f6f4 v[42:45], v[10:17], v[218:225], v[42:45], v199, v199 op_sel_hi:[0,0,0]
	v_mfma_scale_f32_16x16x128_f8f6f4 v[46:49], v[2:9], v[218:225], v[46:49], v199, v199 op_sel_hi:[0,0,0]
	v_mfma_scale_f32_16x16x128_f8f6f4 v[54:57], v[2:9], v[210:217], v[54:57], v199, v199 op_sel_hi:[0,0,0]
	v_mfma_scale_f32_16x16x128_f8f6f4 v[50:53], v[10:17], v[210:217], v[50:53], v199, v199 op_sel_hi:[0,0,0]
	v_mfma_scale_f32_16x16x128_f8f6f4 v[58:61], v[10:17], v[202:209], v[58:61], v199, v199 op_sel_hi:[0,0,0]
	v_mfma_scale_f32_16x16x128_f8f6f4 v[62:65], v[2:9], v[202:209], v[62:65], v199, v199 op_sel_hi:[0,0,0]
	s_setprio 0
	s_barrier
	s_add_u32 s80, s80, 0x20180
	s_addc_u32 s81, s81, 0
	s_add_u32 s8, s78, 0x200
	s_addc_u32 s9, s79, 0
	s_mov_b32 s62, 0
.LBB0_601:
	ds_read_b128 v[2:5], v200
	ds_read_b128 v[6:9], v200 offset:1024
	ds_read_b128 v[18:21], v200 offset:2048
	ds_read_b128 v[22:25], v200 offset:3072
	ds_read_b128 v[26:29], v200 offset:16384
	ds_read_b128 v[30:33], v200 offset:17408
	ds_read_b128 v[182:185], v200 offset:18432
	ds_read_b128 v[186:189], v200 offset:19456
	s_add_u32 s63, s80, 0xfffe0080
	s_addc_u32 s71, s81, -1
	s_cmp_eq_u32 s62, 4
	s_cselect_b32 s83, s4, s71
	s_cselect_b32 s82, s5, s63
	s_cselect_b32 s79, s53, s9
	s_cselect_b32 s78, s55, s8
	s_mov_b32 m0, s96
	v_lshl_add_u64 v[226:227], s[80:81], 0, v[170:171]
	ds_read_b128 v[10:13], v201
	ds_read_b128 v[14:17], v201 offset:1024
	ds_read_b128 v[202:205], v201 offset:2048
	ds_read_b128 v[206:209], v201 offset:3072
	ds_read_b128 v[210:213], v201 offset:4096
	ds_read_b128 v[214:217], v201 offset:5120
	ds_read_b128 v[218:221], v201 offset:6144
	ds_read_b128 v[222:225], v201 offset:7168
	global_load_lds_dwordx4 v[226:227], off
	v_lshl_add_u64 v[226:227], s[80:81], 0, v[172:173]
	s_mov_b32 m0, s61
	s_nop 0
	global_load_lds_dwordx4 v[226:227], off
	s_waitcnt vmcnt(8)
	s_waitcnt lgkmcnt(0)
	s_barrier
	s_setprio 1
	s_waitcnt lgkmcnt(0)
	v_mfma_scale_f32_16x16x128_f8f6f4 v[158:161], v[2:9], v[10:17], v[158:161], v199, v199 op_sel_hi:[0,0,0]
	v_mfma_scale_f32_16x16x128_f8f6f4 v[154:157], v[18:25], v[10:17], v[154:157], v199, v199 op_sel_hi:[0,0,0]
	v_mfma_scale_f32_16x16x128_f8f6f4 v[146:149], v[18:25], v[202:209], v[146:149], v199, v199 op_sel_hi:[0,0,0]
	v_mfma_scale_f32_16x16x128_f8f6f4 v[150:153], v[2:9], v[202:209], v[150:153], v199, v199 op_sel_hi:[0,0,0]
	v_mfma_scale_f32_16x16x128_f8f6f4 v[142:145], v[2:9], v[210:217], v[142:145], v199, v199 op_sel_hi:[0,0,0]
	v_mfma_scale_f32_16x16x128_f8f6f4 v[138:141], v[18:25], v[210:217], v[138:141], v199, v199 op_sel_hi:[0,0,0]
	v_mfma_scale_f32_16x16x128_f8f6f4 v[130:133], v[18:25], v[218:225], v[130:133], v199, v199 op_sel_hi:[0,0,0]
	v_mfma_scale_f32_16x16x128_f8f6f4 v[134:137], v[2:9], v[218:225], v[134:137], v199, v199 op_sel_hi:[0,0,0]
	s_setprio 0
	s_setprio 1
	v_mfma_scale_f32_16x16x128_f8f6f4 v[102:105], v[26:33], v[218:225], v[102:105], v199, v199 op_sel_hi:[0,0,0]
	v_mfma_scale_f32_16x16x128_f8f6f4 v[98:101], v[182:189], v[218:225], v[98:101], v199, v199 op_sel_hi:[0,0,0]
	v_mfma_scale_f32_16x16x128_f8f6f4 v[106:109], v[182:189], v[210:217], v[106:109], v199, v199 op_sel_hi:[0,0,0]
	v_mfma_scale_f32_16x16x128_f8f6f4 v[110:113], v[26:33], v[210:217], v[110:113], v199, v199 op_sel_hi:[0,0,0]
	v_mfma_scale_f32_16x16x128_f8f6f4 v[118:121], v[26:33], v[202:209], v[118:121], v199, v199 op_sel_hi:[0,0,0]
	v_mfma_scale_f32_16x16x128_f8f6f4 v[114:117], v[182:189], v[202:209], v[114:117], v199, v199 op_sel_hi:[0,0,0]
	v_mfma_scale_f32_16x16x128_f8f6f4 v[122:125], v[182:189], v[10:17], v[122:125], v199, v199 op_sel_hi:[0,0,0]
	v_mfma_scale_f32_16x16x128_f8f6f4 v[126:129], v[26:33], v[10:17], v[126:129], v199, v199 op_sel_hi:[0,0,0]
	s_setprio 0
	s_barrier
	s_mov_b32 m0, s68
	v_lshl_add_u64 v[10:11], s[78:79], 0, v[164:165]
	s_add_u32 vcc_lo, s78, 0x20000
	ds_read_b128 v[202:205], v201 offset:16384
	ds_read_b128 v[206:209], v201 offset:17408
	ds_read_b128 v[210:213], v201 offset:18432
	ds_read_b128 v[214:217], v201 offset:19456
	ds_read_b128 v[218:221], v201 offset:20480
	ds_read_b128 v[222:225], v201 offset:21504
	ds_read_b128 v[226:229], v201 offset:22528
	ds_read_b128 v[230:233], v201 offset:23552
	global_load_lds_dwordx4 v[10:11], off
	v_lshl_add_u64 v[12:13], s[78:79], 0, v[168:169]
	s_mov_b32 m0, s69
	s_addc_u32 vcc_hi, s79, 0
	global_load_lds_dwordx4 v[12:13], off
	v_lshl_add_u64 v[14:15], vcc, 0, v[164:165]
	s_mov_b32 m0, s77
	v_lshl_add_u64 v[16:17], s[82:83], 0, v[166:167]
	global_load_lds_dwordx4 v[14:15], off
	v_lshl_add_u64 v[14:15], vcc, 0, v[168:169]
	s_mov_b32 m0, s84
	s_nop 0
	global_load_lds_dwordx4 v[14:15], off
	v_lshl_add_u64 v[14:15], s[82:83], 0, v[162:163]
	s_mov_b32 m0, s33
	s_nop 0
	global_load_lds_dwordx4 v[14:15], off
	s_mov_b32 m0, s85
	s_nop 0
	global_load_lds_dwordx4 v[16:17], off
	s_waitcnt vmcnt(8)
	s_waitcnt lgkmcnt(0)
	s_barrier
	s_setprio 1
	s_waitcnt lgkmcnt(0)
	v_mfma_scale_f32_16x16x128_f8f6f4 v[94:97], v[2:9], v[202:209], v[94:97], v199, v199 op_sel_hi:[0,0,0]
	v_mfma_scale_f32_16x16x128_f8f6f4 v[90:93], v[18:25], v[202:209], v[90:93], v199, v199 op_sel_hi:[0,0,0]
	v_mfma_scale_f32_16x16x128_f8f6f4 v[82:85], v[18:25], v[210:217], v[82:85], v199, v199 op_sel_hi:[0,0,0]
	v_mfma_scale_f32_16x16x128_f8f6f4 v[86:89], v[2:9], v[210:217], v[86:89], v199, v199 op_sel_hi:[0,0,0]
	v_mfma_scale_f32_16x16x128_f8f6f4 v[78:81], v[2:9], v[218:225], v[78:81], v199, v199 op_sel_hi:[0,0,0]
	v_mfma_scale_f32_16x16x128_f8f6f4 v[74:77], v[18:25], v[218:225], v[74:77], v199, v199 op_sel_hi:[0,0,0]
	v_mfma_scale_f32_16x16x128_f8f6f4 v[66:69], v[18:25], v[226:233], v[66:69], v199, v199 op_sel_hi:[0,0,0]
	v_mfma_scale_f32_16x16x128_f8f6f4 v[70:73], v[2:9], v[226:233], v[70:73], v199, v199 op_sel_hi:[0,0,0]
	s_setprio 0
	s_setprio 1
	v_mfma_scale_f32_16x16x128_f8f6f4 v[38:41], v[26:33], v[226:233], v[38:41], v199, v199 op_sel_hi:[0,0,0]
	v_mfma_scale_f32_16x16x128_f8f6f4 v[34:37], v[182:189], v[226:233], v[34:37], v199, v199 op_sel_hi:[0,0,0]
	v_mfma_scale_f32_16x16x128_f8f6f4 v[42:45], v[182:189], v[218:225], v[42:45], v199, v199 op_sel_hi:[0,0,0]
	v_mfma_scale_f32_16x16x128_f8f6f4 v[46:49], v[26:33], v[218:225], v[46:49], v199, v199 op_sel_hi:[0,0,0]
	v_mfma_scale_f32_16x16x128_f8f6f4 v[54:57], v[26:33], v[210:217], v[54:57], v199, v199 op_sel_hi:[0,0,0]
	v_mfma_scale_f32_16x16x128_f8f6f4 v[50:53], v[182:189], v[210:217], v[50:53], v199, v199 op_sel_hi:[0,0,0]
	v_mfma_scale_f32_16x16x128_f8f6f4 v[58:61], v[182:189], v[202:209], v[58:61], v199, v199 op_sel_hi:[0,0,0]
	v_mfma_scale_f32_16x16x128_f8f6f4 v[62:65], v[26:33], v[202:209], v[62:65], v199, v199 op_sel_hi:[0,0,0]
	s_setprio 0
	s_barrier
	ds_read_b128 v[18:21], v200 offset:32768
	ds_read_b128 v[22:25], v200 offset:33792
	ds_read_b128 v[26:29], v200 offset:34816
	ds_read_b128 v[30:33], v200 offset:35840
	ds_read_b128 v[2:5], v200 offset:49152
	ds_read_b128 v[6:9], v200 offset:50176
	ds_read_b128 v[182:185], v200 offset:51200
	ds_read_b128 v[186:189], v200 offset:52224
	s_add_u32 s82, s82, 0x20000
	s_addc_u32 s83, s83, 0
	s_mov_b32 m0, s86
	v_lshl_add_u64 v[234:235], s[82:83], 0, v[162:163]
	ds_read_b128 v[202:205], v201 offset:32768
	ds_read_b128 v[206:209], v201 offset:33792
	ds_read_b128 v[210:213], v201 offset:34816
	ds_read_b128 v[214:217], v201 offset:35840
	ds_read_b128 v[218:221], v201 offset:36864
	ds_read_b128 v[222:225], v201 offset:37888
	ds_read_b128 v[226:229], v201 offset:38912
	ds_read_b128 v[230:233], v201 offset:39936
	global_load_lds_dwordx4 v[234:235], off
	v_lshl_add_u64 v[234:235], s[82:83], 0, v[166:167]
	s_mov_b32 m0, s87
	s_nop 0
	global_load_lds_dwordx4 v[234:235], off
	s_waitcnt vmcnt(8)
	s_waitcnt lgkmcnt(0)
	s_barrier
	s_setprio 1
	s_waitcnt lgkmcnt(0)
	v_mfma_scale_f32_16x16x128_f8f6f4 v[158:161], v[18:25], v[202:209], v[158:161], v199, v199 op_sel_hi:[0,0,0]
	v_mfma_scale_f32_16x16x128_f8f6f4 v[154:157], v[26:33], v[202:209], v[154:157], v199, v199 op_sel_hi:[0,0,0]
	v_mfma_scale_f32_16x16x128_f8f6f4 v[146:149], v[26:33], v[210:217], v[146:149], v199, v199 op_sel_hi:[0,0,0]
	v_mfma_scale_f32_16x16x128_f8f6f4 v[150:153], v[18:25], v[210:217], v[150:153], v199, v199 op_sel_hi:[0,0,0]
	v_mfma_scale_f32_16x16x128_f8f6f4 v[142:145], v[18:25], v[218:225], v[142:145], v199, v199 op_sel_hi:[0,0,0]
	v_mfma_scale_f32_16x16x128_f8f6f4 v[138:141], v[26:33], v[218:225], v[138:141], v199, v199 op_sel_hi:[0,0,0]
	v_mfma_scale_f32_16x16x128_f8f6f4 v[130:133], v[26:33], v[226:233], v[130:133], v199, v199 op_sel_hi:[0,0,0]
	v_mfma_scale_f32_16x16x128_f8f6f4 v[134:137], v[18:25], v[226:233], v[134:137], v199, v199 op_sel_hi:[0,0,0]
	s_setprio 0
	s_setprio 1
	v_mfma_scale_f32_16x16x128_f8f6f4 v[102:105], v[2:9], v[226:233], v[102:105], v199, v199 op_sel_hi:[0,0,0]
	v_mfma_scale_f32_16x16x128_f8f6f4 v[98:101], v[182:189], v[226:233], v[98:101], v199, v199 op_sel_hi:[0,0,0]
	v_mfma_scale_f32_16x16x128_f8f6f4 v[106:109], v[182:189], v[218:225], v[106:109], v199, v199 op_sel_hi:[0,0,0]
	v_mfma_scale_f32_16x16x128_f8f6f4 v[110:113], v[2:9], v[218:225], v[110:113], v199, v199 op_sel_hi:[0,0,0]
	v_mfma_scale_f32_16x16x128_f8f6f4 v[118:121], v[2:9], v[210:217], v[118:121], v199, v199 op_sel_hi:[0,0,0]
	v_mfma_scale_f32_16x16x128_f8f6f4 v[114:117], v[182:189], v[210:217], v[114:117], v199, v199 op_sel_hi:[0,0,0]
	v_mfma_scale_f32_16x16x128_f8f6f4 v[122:125], v[182:189], v[202:209], v[122:125], v199, v199 op_sel_hi:[0,0,0]
	v_mfma_scale_f32_16x16x128_f8f6f4 v[126:129], v[2:9], v[202:209], v[126:129], v199, v199 op_sel_hi:[0,0,0]
	s_setprio 0
	s_barrier
	s_mov_b32 m0, s89
	v_lshl_add_u64 v[10:11], v[10:11], 0, s[42:43]
	s_add_u32 s78, s78, 0x20080
	ds_read_b128 v[202:205], v201 offset:49152
	ds_read_b128 v[206:209], v201 offset:50176
	ds_read_b128 v[210:213], v201 offset:51200
	ds_read_b128 v[214:217], v201 offset:52224
	ds_read_b128 v[218:221], v201 offset:53248
	ds_read_b128 v[222:225], v201 offset:54272
	ds_read_b128 v[226:229], v201 offset:55296
	ds_read_b128 v[230:233], v201 offset:56320
	global_load_lds_dwordx4 v[10:11], off
	v_lshl_add_u64 v[10:11], v[12:13], 0, s[42:43]
	s_mov_b32 m0, s90
	s_addc_u32 s79, s79, 0
	global_load_lds_dwordx4 v[10:11], off
	v_lshl_add_u64 v[10:11], s[78:79], 0, v[164:165]
	s_mov_b32 m0, s93
	s_nop 0
	global_load_lds_dwordx4 v[10:11], off
	v_lshl_add_u64 v[10:11], s[78:79], 0, v[168:169]
	s_mov_b32 m0, s95
	s_nop 0
	global_load_lds_dwordx4 v[10:11], off
	v_lshl_add_u64 v[10:11], v[14:15], 0, s[42:43]
	s_mov_b32 m0, s91
	s_nop 0
	global_load_lds_dwordx4 v[10:11], off
	v_lshl_add_u64 v[10:11], v[16:17], 0, s[42:43]
	s_mov_b32 m0, s92
	s_nop 0
	global_load_lds_dwordx4 v[10:11], off
	s_waitcnt vmcnt(8)
	s_waitcnt lgkmcnt(0)
	s_barrier
	s_setprio 1
	s_waitcnt lgkmcnt(0)
	v_mfma_scale_f32_16x16x128_f8f6f4 v[94:97], v[18:25], v[202:209], v[94:97], v199, v199 op_sel_hi:[0,0,0]
	v_mfma_scale_f32_16x16x128_f8f6f4 v[90:93], v[26:33], v[202:209], v[90:93], v199, v199 op_sel_hi:[0,0,0]
	v_mfma_scale_f32_16x16x128_f8f6f4 v[82:85], v[26:33], v[210:217], v[82:85], v199, v199 op_sel_hi:[0,0,0]
	v_mfma_scale_f32_16x16x128_f8f6f4 v[86:89], v[18:25], v[210:217], v[86:89], v199, v199 op_sel_hi:[0,0,0]
	v_mfma_scale_f32_16x16x128_f8f6f4 v[78:81], v[18:25], v[218:225], v[78:81], v199, v199 op_sel_hi:[0,0,0]
	v_mfma_scale_f32_16x16x128_f8f6f4 v[74:77], v[26:33], v[218:225], v[74:77], v199, v199 op_sel_hi:[0,0,0]
	v_mfma_scale_f32_16x16x128_f8f6f4 v[66:69], v[26:33], v[226:233], v[66:69], v199, v199 op_sel_hi:[0,0,0]
	v_mfma_scale_f32_16x16x128_f8f6f4 v[70:73], v[18:25], v[226:233], v[70:73], v199, v199 op_sel_hi:[0,0,0]
	s_setprio 0
	s_setprio 1
	v_mfma_scale_f32_16x16x128_f8f6f4 v[38:41], v[2:9], v[226:233], v[38:41], v199, v199 op_sel_hi:[0,0,0]
	v_mfma_scale_f32_16x16x128_f8f6f4 v[34:37], v[182:189], v[226:233], v[34:37], v199, v199 op_sel_hi:[0,0,0]
	v_mfma_scale_f32_16x16x128_f8f6f4 v[42:45], v[182:189], v[218:225], v[42:45], v199, v199 op_sel_hi:[0,0,0]
	v_mfma_scale_f32_16x16x128_f8f6f4 v[46:49], v[2:9], v[218:225], v[46:49], v199, v199 op_sel_hi:[0,0,0]
	v_mfma_scale_f32_16x16x128_f8f6f4 v[54:57], v[2:9], v[210:217], v[54:57], v199, v199 op_sel_hi:[0,0,0]
	v_mfma_scale_f32_16x16x128_f8f6f4 v[50:53], v[182:189], v[210:217], v[50:53], v199, v199 op_sel_hi:[0,0,0]
	v_mfma_scale_f32_16x16x128_f8f6f4 v[58:61], v[182:189], v[202:209], v[58:61], v199, v199 op_sel_hi:[0,0,0]
	v_mfma_scale_f32_16x16x128_f8f6f4 v[62:65], v[2:9], v[202:209], v[62:65], v199, v199 op_sel_hi:[0,0,0]
	s_setprio 0
	s_barrier
	s_add_i32 s62, s62, 2
	s_add_u32 s80, s80, 0x100
	s_addc_u32 s81, s81, 0
	s_add_u32 s8, s8, 0x100
	s_addc_u32 s9, s9, 0
	s_cmp_gt_u32 s62, 5
	s_cbranch_scc0 .LBB0_601
	s_and_b64 vcc, exec, s[44:45]
	s_cbranch_vccz .LBB0_604
	s_barrier

.LBB0_616:
	ds_read_b128 v[18:21], v188
	ds_read_b128 v[22:25], v188 offset:1024
	ds_read_b128 v[26:29], v188 offset:2048
	ds_read_b128 v[30:33], v188 offset:3072
	ds_read_b128 v[2:5], v188 offset:16384
	ds_read_b128 v[6:9], v188 offset:17408
	ds_read_b128 v[10:13], v188 offset:18432
	ds_read_b128 v[14:17], v188 offset:19456
	s_ashr_i32 s55, s54, 31
	s_lshl_b64 s[62:63], s[54:55], 17
	s_add_u32 s72, s36, s62
	s_addc_u32 s73, s37, s63
	s_and_b64 s[62:63], s[2:3], exec
	s_cselect_b32 s85, s73, s79
	s_cselect_b32 s84, s72, s78
	s_ashr_i32 s53, s52, 31
	s_lshl_b64 s[62:63], s[52:53], 17
	s_add_u32 s74, s94, s62
	v_readlane_b32 s5, v254, 8
	s_addc_u32 s75, s5, s63
	s_and_b64 s[62:63], s[2:3], exec
	s_cselect_b32 s83, s75, s81
	s_cselect_b32 s82, s74, s80
	s_add_u32 s62, s78, 0x10080
	s_addc_u32 s63, s79, 0
	s_mov_b32 m0, s96
	v_lshl_add_u64 v[174:175], s[62:63], 0, v[166:167]
	ds_read_b128 v[196:199], v189
	ds_read_b128 v[200:203], v189 offset:1024
	ds_read_b128 v[204:207], v189 offset:2048
	ds_read_b128 v[208:211], v189 offset:3072
	ds_read_b128 v[212:215], v189 offset:4096
	ds_read_b128 v[216:219], v189 offset:5120
	ds_read_b128 v[220:223], v189 offset:6144
	ds_read_b128 v[224:227], v189 offset:7168
	global_load_lds_dwordx4 v[174:175], off
	v_lshl_add_u64 v[174:175], s[62:63], 0, v[168:169]
	s_mov_b32 m0, s97
	s_nop 0
	global_load_lds_dwordx4 v[174:175], off
	s_waitcnt vmcnt(8)
	s_waitcnt lgkmcnt(0)
	s_barrier
	s_setprio 1
	s_waitcnt lgkmcnt(0)
	v_mfma_scale_f32_16x16x128_f8f6f4 v[158:161], v[18:25], v[196:203], 0, v195, v195 op_sel_hi:[0,0,0]
	v_mfma_scale_f32_16x16x128_f8f6f4 v[154:157], v[26:33], v[196:203], 0, v195, v195 op_sel_hi:[0,0,0]
	v_mfma_scale_f32_16x16x128_f8f6f4 v[146:149], v[26:33], v[204:211], 0, v195, v195 op_sel_hi:[0,0,0]
	v_mfma_scale_f32_16x16x128_f8f6f4 v[150:153], v[18:25], v[204:211], 0, v195, v195 op_sel_hi:[0,0,0]
	v_mfma_scale_f32_16x16x128_f8f6f4 v[142:145], v[18:25], v[212:219], 0, v195, v195 op_sel_hi:[0,0,0]
	v_mfma_scale_f32_16x16x128_f8f6f4 v[138:141], v[26:33], v[212:219], 0, v195, v195 op_sel_hi:[0,0,0]
	v_mfma_scale_f32_16x16x128_f8f6f4 v[130:133], v[26:33], v[220:227], 0, v195, v195 op_sel_hi:[0,0,0]
	v_mfma_scale_f32_16x16x128_f8f6f4 v[134:137], v[18:25], v[220:227], 0, v195, v195 op_sel_hi:[0,0,0]
	s_setprio 0
	s_setprio 1
	v_mfma_scale_f32_16x16x128_f8f6f4 v[102:105], v[2:9], v[220:227], 0, v195, v195 op_sel_hi:[0,0,0]
	v_mfma_scale_f32_16x16x128_f8f6f4 v[98:101], v[10:17], v[220:227], 0, v195, v195 op_sel_hi:[0,0,0]
	v_mfma_scale_f32_16x16x128_f8f6f4 v[106:109], v[10:17], v[212:219], 0, v195, v195 op_sel_hi:[0,0,0]
	v_mfma_scale_f32_16x16x128_f8f6f4 v[110:113], v[2:9], v[212:219], 0, v195, v195 op_sel_hi:[0,0,0]
	v_mfma_scale_f32_16x16x128_f8f6f4 v[118:121], v[2:9], v[204:211], 0, v195, v195 op_sel_hi:[0,0,0]
	v_mfma_scale_f32_16x16x128_f8f6f4 v[114:117], v[10:17], v[204:211], 0, v195, v195 op_sel_hi:[0,0,0]
	v_mfma_scale_f32_16x16x128_f8f6f4 v[122:125], v[10:17], v[196:203], 0, v195, v195 op_sel_hi:[0,0,0]
	v_mfma_scale_f32_16x16x128_f8f6f4 v[126:129], v[2:9], v[196:203], 0, v195, v195 op_sel_hi:[0,0,0]
	s_setprio 0
	s_barrier
	v_lshl_add_u64 v[174:175], s[80:81], 0, v[162:163]
	s_mov_b32 m0, s61
	v_lshl_add_u64 v[176:177], v[174:175], 0, s[46:47]
	ds_read_b128 v[196:199], v189 offset:16384
	ds_read_b128 v[200:203], v189 offset:17408
	ds_read_b128 v[204:207], v189 offset:18432
	ds_read_b128 v[208:211], v189 offset:19456
	ds_read_b128 v[212:215], v189 offset:20480
	ds_read_b128 v[216:219], v189 offset:21504
	ds_read_b128 v[220:223], v189 offset:22528
	ds_read_b128 v[224:227], v189 offset:23552
	global_load_lds_dwordx4 v[176:177], off
	v_lshl_add_u64 v[176:177], s[80:81], 0, v[164:165]
	s_add_u32 s62, s80, 0x10100
	v_lshl_add_u64 v[182:183], v[176:177], 0, s[46:47]
	s_mov_b32 m0, s68
	s_addc_u32 s63, s81, 0
	global_load_lds_dwordx4 v[182:183], off
	v_lshl_add_u64 v[182:183], s[62:63], 0, v[162:163]
	s_mov_b32 m0, s69
	s_nop 0
	global_load_lds_dwordx4 v[182:183], off
	v_lshl_add_u64 v[182:183], s[62:63], 0, v[164:165]
	s_mov_b32 m0, s77
	s_nop 0
	global_load_lds_dwordx4 v[182:183], off
	v_lshl_add_u64 v[182:183], s[78:79], 0, v[166:167]
	v_lshl_add_u64 v[184:185], v[182:183], 0, s[46:47]
	s_mov_b32 m0, s51
	s_nop 0
	global_load_lds_dwordx4 v[184:185], off
	v_lshl_add_u64 v[184:185], s[78:79], 0, v[168:169]
	v_lshl_add_u64 v[228:229], v[184:185], 0, s[46:47]
	s_mov_b32 m0, s86
	s_nop 0
	global_load_lds_dwordx4 v[228:229], off
	s_waitcnt vmcnt(8)
	s_waitcnt lgkmcnt(0)
	s_barrier
	s_setprio 1
	s_waitcnt lgkmcnt(0)
	v_mfma_scale_f32_16x16x128_f8f6f4 v[94:97], v[18:25], v[196:203], 0, v195, v195 op_sel_hi:[0,0,0]
	v_mfma_scale_f32_16x16x128_f8f6f4 v[90:93], v[26:33], v[196:203], 0, v195, v195 op_sel_hi:[0,0,0]
	v_mfma_scale_f32_16x16x128_f8f6f4 v[82:85], v[26:33], v[204:211], 0, v195, v195 op_sel_hi:[0,0,0]
	v_mfma_scale_f32_16x16x128_f8f6f4 v[86:89], v[18:25], v[204:211], 0, v195, v195 op_sel_hi:[0,0,0]
	v_mfma_scale_f32_16x16x128_f8f6f4 v[78:81], v[18:25], v[212:219], 0, v195, v195 op_sel_hi:[0,0,0]
	v_mfma_scale_f32_16x16x128_f8f6f4 v[74:77], v[26:33], v[212:219], 0, v195, v195 op_sel_hi:[0,0,0]
	v_mfma_scale_f32_16x16x128_f8f6f4 v[66:69], v[26:33], v[220:227], 0, v195, v195 op_sel_hi:[0,0,0]
	v_mfma_scale_f32_16x16x128_f8f6f4 v[70:73], v[18:25], v[220:227], 0, v195, v195 op_sel_hi:[0,0,0]
	s_setprio 0
	s_setprio 1
	v_mfma_scale_f32_16x16x128_f8f6f4 v[38:41], v[2:9], v[220:227], 0, v195, v195 op_sel_hi:[0,0,0]
	v_mfma_scale_f32_16x16x128_f8f6f4 v[34:37], v[10:17], v[220:227], 0, v195, v195 op_sel_hi:[0,0,0]
	v_mfma_scale_f32_16x16x128_f8f6f4 v[42:45], v[10:17], v[212:219], 0, v195, v195 op_sel_hi:[0,0,0]
	v_mfma_scale_f32_16x16x128_f8f6f4 v[46:49], v[2:9], v[212:219], 0, v195, v195 op_sel_hi:[0,0,0]
	v_mfma_scale_f32_16x16x128_f8f6f4 v[54:57], v[2:9], v[204:211], 0, v195, v195 op_sel_hi:[0,0,0]
	v_mfma_scale_f32_16x16x128_f8f6f4 v[50:53], v[10:17], v[204:211], 0, v195, v195 op_sel_hi:[0,0,0]
	v_mfma_scale_f32_16x16x128_f8f6f4 v[58:61], v[10:17], v[196:203], 0, v195, v195 op_sel_hi:[0,0,0]
	v_mfma_scale_f32_16x16x128_f8f6f4 v[62:65], v[2:9], v[196:203], 0, v195, v195 op_sel_hi:[0,0,0]
	s_setprio 0
	s_barrier
	ds_read_b128 v[2:5], v188 offset:32768
	ds_read_b128 v[6:9], v188 offset:33792
	ds_read_b128 v[10:13], v188 offset:34816
	ds_read_b128 v[14:17], v188 offset:35840
	ds_read_b128 v[18:21], v188 offset:49152
	ds_read_b128 v[22:25], v188 offset:50176
	ds_read_b128 v[26:29], v188 offset:51200
	ds_read_b128 v[30:33], v188 offset:52224
	s_add_u32 s62, s78, 0x10100
	s_addc_u32 s63, s79, 0
	s_mov_b32 m0, s87
	v_lshl_add_u64 v[228:229], s[62:63], 0, v[166:167]
	ds_read_b128 v[196:199], v189 offset:32768
	ds_read_b128 v[200:203], v189 offset:33792
	ds_read_b128 v[204:207], v189 offset:34816
	ds_read_b128 v[208:211], v189 offset:35840
	ds_read_b128 v[212:215], v189 offset:36864
	ds_read_b128 v[216:219], v189 offset:37888
	ds_read_b128 v[220:223], v189 offset:38912
	ds_read_b128 v[224:227], v189 offset:39936
	global_load_lds_dwordx4 v[228:229], off
	v_lshl_add_u64 v[228:229], s[62:63], 0, v[168:169]
	s_mov_b32 m0, s88
	s_nop 0
	global_load_lds_dwordx4 v[228:229], off
	s_waitcnt vmcnt(8)
	s_waitcnt lgkmcnt(0)
	s_barrier
	s_setprio 1
	s_waitcnt lgkmcnt(0)
	v_mfma_scale_f32_16x16x128_f8f6f4 v[158:161], v[2:9], v[196:203], v[158:161], v195, v195 op_sel_hi:[0,0,0]
	v_mfma_scale_f32_16x16x128_f8f6f4 v[154:157], v[10:17], v[196:203], v[154:157], v195, v195 op_sel_hi:[0,0,0]
	v_mfma_scale_f32_16x16x128_f8f6f4 v[146:149], v[10:17], v[204:211], v[146:149], v195, v195 op_sel_hi:[0,0,0]
	v_mfma_scale_f32_16x16x128_f8f6f4 v[150:153], v[2:9], v[204:211], v[150:153], v195, v195 op_sel_hi:[0,0,0]
	v_mfma_scale_f32_16x16x128_f8f6f4 v[142:145], v[2:9], v[212:219], v[142:145], v195, v195 op_sel_hi:[0,0,0]
	v_mfma_scale_f32_16x16x128_f8f6f4 v[138:141], v[10:17], v[212:219], v[138:141], v195, v195 op_sel_hi:[0,0,0]
	v_mfma_scale_f32_16x16x128_f8f6f4 v[130:133], v[10:17], v[220:227], v[130:133], v195, v195 op_sel_hi:[0,0,0]
	v_mfma_scale_f32_16x16x128_f8f6f4 v[134:137], v[2:9], v[220:227], v[134:137], v195, v195 op_sel_hi:[0,0,0]
	s_setprio 0
	s_setprio 1
	v_mfma_scale_f32_16x16x128_f8f6f4 v[102:105], v[18:25], v[220:227], v[102:105], v195, v195 op_sel_hi:[0,0,0]
	v_mfma_scale_f32_16x16x128_f8f6f4 v[98:101], v[26:33], v[220:227], v[98:101], v195, v195 op_sel_hi:[0,0,0]
	v_mfma_scale_f32_16x16x128_f8f6f4 v[106:109], v[26:33], v[212:219], v[106:109], v195, v195 op_sel_hi:[0,0,0]
	v_mfma_scale_f32_16x16x128_f8f6f4 v[110:113], v[18:25], v[212:219], v[110:113], v195, v195 op_sel_hi:[0,0,0]
	v_mfma_scale_f32_16x16x128_f8f6f4 v[118:121], v[18:25], v[204:211], v[118:121], v195, v195 op_sel_hi:[0,0,0]
	v_mfma_scale_f32_16x16x128_f8f6f4 v[114:117], v[26:33], v[204:211], v[114:117], v195, v195 op_sel_hi:[0,0,0]
	v_mfma_scale_f32_16x16x128_f8f6f4 v[122:125], v[26:33], v[196:203], v[122:125], v195, v195 op_sel_hi:[0,0,0]
	v_mfma_scale_f32_16x16x128_f8f6f4 v[126:129], v[18:25], v[196:203], v[126:129], v195, v195 op_sel_hi:[0,0,0]
	s_setprio 0
	s_barrier
	s_mov_b32 m0, s89
	v_lshl_add_u64 v[174:175], v[174:175], 0, s[48:49]
	s_add_u32 s62, s80, 0x10180
	ds_read_b128 v[196:199], v189 offset:49152
	ds_read_b128 v[200:203], v189 offset:50176
	ds_read_b128 v[204:207], v189 offset:51200
	ds_read_b128 v[208:211], v189 offset:52224
	ds_read_b128 v[212:215], v189 offset:53248
	ds_read_b128 v[216:219], v189 offset:54272
	ds_read_b128 v[220:223], v189 offset:55296
	ds_read_b128 v[224:227], v189 offset:56320
	global_load_lds_dwordx4 v[174:175], off
	v_lshl_add_u64 v[174:175], v[176:177], 0, s[48:49]
	s_mov_b32 m0, s90
	s_addc_u32 s63, s81, 0
	global_load_lds_dwordx4 v[174:175], off
	v_lshl_add_u64 v[174:175], s[62:63], 0, v[162:163]
	s_mov_b32 m0, s93
	s_nop 0
	global_load_lds_dwordx4 v[174:175], off
	v_lshl_add_u64 v[174:175], s[62:63], 0, v[164:165]
	s_mov_b32 m0, s95
	s_nop 0
	global_load_lds_dwordx4 v[174:175], off
	v_lshl_add_u64 v[174:175], v[182:183], 0, s[48:49]
	s_mov_b32 m0, s91
	s_nop 0
	global_load_lds_dwordx4 v[174:175], off
	v_lshl_add_u64 v[174:175], v[184:185], 0, s[48:49]
	s_mov_b32 m0, s92
	s_nop 0
	global_load_lds_dwordx4 v[174:175], off
	s_waitcnt vmcnt(8)
	s_waitcnt lgkmcnt(0)
	s_barrier
	s_setprio 1
	s_waitcnt lgkmcnt(0)
	v_mfma_scale_f32_16x16x128_f8f6f4 v[94:97], v[2:9], v[196:203], v[94:97], v195, v195 op_sel_hi:[0,0,0]
	v_mfma_scale_f32_16x16x128_f8f6f4 v[90:93], v[10:17], v[196:203], v[90:93], v195, v195 op_sel_hi:[0,0,0]
	v_mfma_scale_f32_16x16x128_f8f6f4 v[82:85], v[10:17], v[204:211], v[82:85], v195, v195 op_sel_hi:[0,0,0]
	v_mfma_scale_f32_16x16x128_f8f6f4 v[86:89], v[2:9], v[204:211], v[86:89], v195, v195 op_sel_hi:[0,0,0]
	v_mfma_scale_f32_16x16x128_f8f6f4 v[78:81], v[2:9], v[212:219], v[78:81], v195, v195 op_sel_hi:[0,0,0]
	v_mfma_scale_f32_16x16x128_f8f6f4 v[74:77], v[10:17], v[212:219], v[74:77], v195, v195 op_sel_hi:[0,0,0]
	v_mfma_scale_f32_16x16x128_f8f6f4 v[66:69], v[10:17], v[220:227], v[66:69], v195, v195 op_sel_hi:[0,0,0]
	v_mfma_scale_f32_16x16x128_f8f6f4 v[70:73], v[2:9], v[220:227], v[70:73], v195, v195 op_sel_hi:[0,0,0]
	s_setprio 0
	s_setprio 1
	v_mfma_scale_f32_16x16x128_f8f6f4 v[38:41], v[18:25], v[220:227], v[38:41], v195, v195 op_sel_hi:[0,0,0]
	v_mfma_scale_f32_16x16x128_f8f6f4 v[34:37], v[26:33], v[220:227], v[34:37], v195, v195 op_sel_hi:[0,0,0]
	v_mfma_scale_f32_16x16x128_f8f6f4 v[42:45], v[26:33], v[212:219], v[42:45], v195, v195 op_sel_hi:[0,0,0]
	v_mfma_scale_f32_16x16x128_f8f6f4 v[46:49], v[18:25], v[212:219], v[46:49], v195, v195 op_sel_hi:[0,0,0]
	v_mfma_scale_f32_16x16x128_f8f6f4 v[54:57], v[18:25], v[204:211], v[54:57], v195, v195 op_sel_hi:[0,0,0]
	v_mfma_scale_f32_16x16x128_f8f6f4 v[50:53], v[26:33], v[204:211], v[50:53], v195, v195 op_sel_hi:[0,0,0]
	v_mfma_scale_f32_16x16x128_f8f6f4 v[58:61], v[26:33], v[196:203], v[58:61], v195, v195 op_sel_hi:[0,0,0]
	v_mfma_scale_f32_16x16x128_f8f6f4 v[62:65], v[18:25], v[196:203], v[62:65], v195, v195 op_sel_hi:[0,0,0]
	s_setprio 0
	s_barrier
	ds_read_b128 v[2:5], v188
	ds_read_b128 v[6:9], v188 offset:1024
	ds_read_b128 v[10:13], v188 offset:2048
	ds_read_b128 v[14:17], v188 offset:3072
	ds_read_b128 v[18:21], v188 offset:16384
	ds_read_b128 v[22:25], v188 offset:17408
	ds_read_b128 v[26:29], v188 offset:18432
	ds_read_b128 v[30:33], v188 offset:19456
	s_add_u32 s62, s78, 0x10180
	s_addc_u32 s63, s79, 0
	s_mov_b32 m0, s96
	v_lshl_add_u64 v[174:175], s[62:63], 0, v[166:167]
	ds_read_b128 v[196:199], v189
	ds_read_b128 v[200:203], v189 offset:1024
	ds_read_b128 v[204:207], v189 offset:2048
	ds_read_b128 v[208:211], v189 offset:3072
	ds_read_b128 v[212:215], v189 offset:4096
	ds_read_b128 v[216:219], v189 offset:5120
	ds_read_b128 v[220:223], v189 offset:6144
	ds_read_b128 v[224:227], v189 offset:7168
	global_load_lds_dwordx4 v[174:175], off
	v_lshl_add_u64 v[174:175], s[62:63], 0, v[168:169]
	s_mov_b32 m0, s97
	s_nop 0
	global_load_lds_dwordx4 v[174:175], off
	s_waitcnt vmcnt(8)
	s_waitcnt lgkmcnt(0)
	s_barrier
	s_setprio 1
	s_waitcnt lgkmcnt(0)
	v_mfma_scale_f32_16x16x128_f8f6f4 v[158:161], v[2:9], v[196:203], v[158:161], v195, v195 op_sel_hi:[0,0,0]
	v_mfma_scale_f32_16x16x128_f8f6f4 v[154:157], v[10:17], v[196:203], v[154:157], v195, v195 op_sel_hi:[0,0,0]
	v_mfma_scale_f32_16x16x128_f8f6f4 v[146:149], v[10:17], v[204:211], v[146:149], v195, v195 op_sel_hi:[0,0,0]
	v_mfma_scale_f32_16x16x128_f8f6f4 v[150:153], v[2:9], v[204:211], v[150:153], v195, v195 op_sel_hi:[0,0,0]
	v_mfma_scale_f32_16x16x128_f8f6f4 v[142:145], v[2:9], v[212:219], v[142:145], v195, v195 op_sel_hi:[0,0,0]
	v_mfma_scale_f32_16x16x128_f8f6f4 v[138:141], v[10:17], v[212:219], v[138:141], v195, v195 op_sel_hi:[0,0,0]
	v_mfma_scale_f32_16x16x128_f8f6f4 v[130:133], v[10:17], v[220:227], v[130:133], v195, v195 op_sel_hi:[0,0,0]
	v_mfma_scale_f32_16x16x128_f8f6f4 v[134:137], v[2:9], v[220:227], v[134:137], v195, v195 op_sel_hi:[0,0,0]
	s_setprio 0
	s_setprio 1
	v_mfma_scale_f32_16x16x128_f8f6f4 v[102:105], v[18:25], v[220:227], v[102:105], v195, v195 op_sel_hi:[0,0,0]
	v_mfma_scale_f32_16x16x128_f8f6f4 v[98:101], v[26:33], v[220:227], v[98:101], v195, v195 op_sel_hi:[0,0,0]
	v_mfma_scale_f32_16x16x128_f8f6f4 v[106:109], v[26:33], v[212:219], v[106:109], v195, v195 op_sel_hi:[0,0,0]
	v_mfma_scale_f32_16x16x128_f8f6f4 v[110:113], v[18:25], v[212:219], v[110:113], v195, v195 op_sel_hi:[0,0,0]
	v_mfma_scale_f32_16x16x128_f8f6f4 v[118:121], v[18:25], v[204:211], v[118:121], v195, v195 op_sel_hi:[0,0,0]
	v_mfma_scale_f32_16x16x128_f8f6f4 v[114:117], v[26:33], v[204:211], v[114:117], v195, v195 op_sel_hi:[0,0,0]
	v_mfma_scale_f32_16x16x128_f8f6f4 v[122:125], v[26:33], v[196:203], v[122:125], v195, v195 op_sel_hi:[0,0,0]
	v_mfma_scale_f32_16x16x128_f8f6f4 v[126:129], v[18:25], v[196:203], v[126:129], v195, v195 op_sel_hi:[0,0,0]
	s_setprio 0
	s_barrier
	s_mov_b32 m0, s61
	v_lshl_add_u64 v[174:175], s[82:83], 0, v[162:163]
	s_add_u32 s62, s82, 0x10000
	ds_read_b128 v[196:199], v189 offset:16384
	ds_read_b128 v[200:203], v189 offset:17408
	ds_read_b128 v[204:207], v189 offset:18432
	ds_read_b128 v[208:211], v189 offset:19456
	ds_read_b128 v[212:215], v189 offset:20480
	ds_read_b128 v[216:219], v189 offset:21504
	ds_read_b128 v[220:223], v189 offset:22528
	ds_read_b128 v[224:227], v189 offset:23552
	global_load_lds_dwordx4 v[174:175], off
	v_lshl_add_u64 v[176:177], s[82:83], 0, v[164:165]
	s_mov_b32 m0, s68
	s_addc_u32 s63, s83, 0
	global_load_lds_dwordx4 v[176:177], off
	v_lshl_add_u64 v[182:183], s[62:63], 0, v[162:163]
	s_mov_b32 m0, s69
	v_lshl_add_u64 v[184:185], s[84:85], 0, v[168:169]
	global_load_lds_dwordx4 v[182:183], off
	v_lshl_add_u64 v[182:183], s[62:63], 0, v[164:165]
	s_mov_b32 m0, s77
	s_nop 0
	global_load_lds_dwordx4 v[182:183], off
	v_lshl_add_u64 v[182:183], s[84:85], 0, v[166:167]
	s_mov_b32 m0, s51
	s_nop 0
	global_load_lds_dwordx4 v[182:183], off
	s_mov_b32 m0, s86
	s_nop 0
	global_load_lds_dwordx4 v[184:185], off
	s_waitcnt vmcnt(8)
	s_waitcnt lgkmcnt(0)
	s_barrier
	s_setprio 1
	s_waitcnt lgkmcnt(0)
	v_mfma_scale_f32_16x16x128_f8f6f4 v[94:97], v[2:9], v[196:203], v[94:97], v195, v195 op_sel_hi:[0,0,0]
	v_mfma_scale_f32_16x16x128_f8f6f4 v[90:93], v[10:17], v[196:203], v[90:93], v195, v195 op_sel_hi:[0,0,0]
	v_mfma_scale_f32_16x16x128_f8f6f4 v[82:85], v[10:17], v[204:211], v[82:85], v195, v195 op_sel_hi:[0,0,0]
	v_mfma_scale_f32_16x16x128_f8f6f4 v[86:89], v[2:9], v[204:211], v[86:89], v195, v195 op_sel_hi:[0,0,0]
	v_mfma_scale_f32_16x16x128_f8f6f4 v[78:81], v[2:9], v[212:219], v[78:81], v195, v195 op_sel_hi:[0,0,0]
	v_mfma_scale_f32_16x16x128_f8f6f4 v[74:77], v[10:17], v[212:219], v[74:77], v195, v195 op_sel_hi:[0,0,0]
	v_mfma_scale_f32_16x16x128_f8f6f4 v[66:69], v[10:17], v[220:227], v[66:69], v195, v195 op_sel_hi:[0,0,0]
	v_mfma_scale_f32_16x16x128_f8f6f4 v[70:73], v[2:9], v[220:227], v[70:73], v195, v195 op_sel_hi:[0,0,0]
	s_setprio 0
	s_setprio 1
	v_mfma_scale_f32_16x16x128_f8f6f4 v[38:41], v[18:25], v[220:227], v[38:41], v195, v195 op_sel_hi:[0,0,0]
	v_mfma_scale_f32_16x16x128_f8f6f4 v[34:37], v[26:33], v[220:227], v[34:37], v195, v195 op_sel_hi:[0,0,0]
	v_mfma_scale_f32_16x16x128_f8f6f4 v[42:45], v[26:33], v[212:219], v[42:45], v195, v195 op_sel_hi:[0,0,0]
	v_mfma_scale_f32_16x16x128_f8f6f4 v[46:49], v[18:25], v[212:219], v[46:49], v195, v195 op_sel_hi:[0,0,0]
	v_mfma_scale_f32_16x16x128_f8f6f4 v[54:57], v[18:25], v[204:211], v[54:57], v195, v195 op_sel_hi:[0,0,0]
	v_mfma_scale_f32_16x16x128_f8f6f4 v[50:53], v[26:33], v[204:211], v[50:53], v195, v195 op_sel_hi:[0,0,0]
	v_mfma_scale_f32_16x16x128_f8f6f4 v[58:61], v[26:33], v[196:203], v[58:61], v195, v195 op_sel_hi:[0,0,0]
	v_mfma_scale_f32_16x16x128_f8f6f4 v[62:65], v[18:25], v[196:203], v[62:65], v195, v195 op_sel_hi:[0,0,0]
	s_setprio 0
	s_barrier
	ds_read_b128 v[2:5], v188 offset:32768
	ds_read_b128 v[6:9], v188 offset:33792
	ds_read_b128 v[10:13], v188 offset:34816
	ds_read_b128 v[14:17], v188 offset:35840
	ds_read_b128 v[18:21], v188 offset:49152
	ds_read_b128 v[22:25], v188 offset:50176
	ds_read_b128 v[26:29], v188 offset:51200
	ds_read_b128 v[30:33], v188 offset:52224
	s_add_u32 s62, s84, 0x10000
	s_addc_u32 s63, s85, 0
	s_mov_b32 m0, s87
	v_lshl_add_u64 v[228:229], s[62:63], 0, v[166:167]
	ds_read_b128 v[196:199], v189 offset:32768
	ds_read_b128 v[200:203], v189 offset:33792
	ds_read_b128 v[204:207], v189 offset:34816
	ds_read_b128 v[208:211], v189 offset:35840
	ds_read_b128 v[212:215], v189 offset:36864
	ds_read_b128 v[216:219], v189 offset:37888
	ds_read_b128 v[220:223], v189 offset:38912
	ds_read_b128 v[224:227], v189 offset:39936
	global_load_lds_dwordx4 v[228:229], off
	v_lshl_add_u64 v[228:229], s[62:63], 0, v[168:169]
	s_mov_b32 m0, s88
	s_nop 0
	global_load_lds_dwordx4 v[228:229], off
	s_waitcnt vmcnt(8)
	s_waitcnt lgkmcnt(0)
	s_barrier
	s_setprio 1
	s_waitcnt lgkmcnt(0)
	v_mfma_scale_f32_16x16x128_f8f6f4 v[158:161], v[2:9], v[196:203], v[158:161], v195, v195 op_sel_hi:[0,0,0]
	v_mfma_scale_f32_16x16x128_f8f6f4 v[154:157], v[10:17], v[196:203], v[154:157], v195, v195 op_sel_hi:[0,0,0]
	v_mfma_scale_f32_16x16x128_f8f6f4 v[146:149], v[10:17], v[204:211], v[146:149], v195, v195 op_sel_hi:[0,0,0]
	v_mfma_scale_f32_16x16x128_f8f6f4 v[150:153], v[2:9], v[204:211], v[150:153], v195, v195 op_sel_hi:[0,0,0]
	v_mfma_scale_f32_16x16x128_f8f6f4 v[142:145], v[2:9], v[212:219], v[142:145], v195, v195 op_sel_hi:[0,0,0]
	v_mfma_scale_f32_16x16x128_f8f6f4 v[138:141], v[10:17], v[212:219], v[138:141], v195, v195 op_sel_hi:[0,0,0]
	v_mfma_scale_f32_16x16x128_f8f6f4 v[130:133], v[10:17], v[220:227], v[130:133], v195, v195 op_sel_hi:[0,0,0]
	v_mfma_scale_f32_16x16x128_f8f6f4 v[134:137], v[2:9], v[220:227], v[134:137], v195, v195 op_sel_hi:[0,0,0]
	s_setprio 0
	s_setprio 1
	v_mfma_scale_f32_16x16x128_f8f6f4 v[102:105], v[18:25], v[220:227], v[102:105], v195, v195 op_sel_hi:[0,0,0]
	v_mfma_scale_f32_16x16x128_f8f6f4 v[98:101], v[26:33], v[220:227], v[98:101], v195, v195 op_sel_hi:[0,0,0]
	v_mfma_scale_f32_16x16x128_f8f6f4 v[106:109], v[26:33], v[212:219], v[106:109], v195, v195 op_sel_hi:[0,0,0]
	v_mfma_scale_f32_16x16x128_f8f6f4 v[110:113], v[18:25], v[212:219], v[110:113], v195, v195 op_sel_hi:[0,0,0]
	v_mfma_scale_f32_16x16x128_f8f6f4 v[118:121], v[18:25], v[204:211], v[118:121], v195, v195 op_sel_hi:[0,0,0]
	v_mfma_scale_f32_16x16x128_f8f6f4 v[114:117], v[26:33], v[204:211], v[114:117], v195, v195 op_sel_hi:[0,0,0]
	v_mfma_scale_f32_16x16x128_f8f6f4 v[122:125], v[26:33], v[196:203], v[122:125], v195, v195 op_sel_hi:[0,0,0]
	v_mfma_scale_f32_16x16x128_f8f6f4 v[126:129], v[18:25], v[196:203], v[126:129], v195, v195 op_sel_hi:[0,0,0]
	s_setprio 0
	s_barrier
	s_mov_b32 m0, s89
	v_lshl_add_u64 v[174:175], v[174:175], 0, s[40:41]
	s_add_u32 s62, s82, 0x10080
	ds_read_b128 v[196:199], v189 offset:49152
	ds_read_b128 v[200:203], v189 offset:50176
	ds_read_b128 v[204:207], v189 offset:51200
	ds_read_b128 v[208:211], v189 offset:52224
	ds_read_b128 v[212:215], v189 offset:53248
	ds_read_b128 v[216:219], v189 offset:54272
	ds_read_b128 v[220:223], v189 offset:55296
	ds_read_b128 v[224:227], v189 offset:56320
	global_load_lds_dwordx4 v[174:175], off
	v_lshl_add_u64 v[174:175], v[176:177], 0, s[40:41]
	s_mov_b32 m0, s90
	s_addc_u32 s63, s83, 0
	global_load_lds_dwordx4 v[174:175], off
	v_lshl_add_u64 v[174:175], s[62:63], 0, v[162:163]
	s_mov_b32 m0, s93
	s_nop 0
	global_load_lds_dwordx4 v[174:175], off
	v_lshl_add_u64 v[174:175], s[62:63], 0, v[164:165]
	s_mov_b32 m0, s95
	s_nop 0
	global_load_lds_dwordx4 v[174:175], off
	v_lshl_add_u64 v[174:175], v[182:183], 0, s[40:41]
	s_mov_b32 m0, s91
	s_nop 0
	global_load_lds_dwordx4 v[174:175], off
	v_lshl_add_u64 v[174:175], v[184:185], 0, s[40:41]
	s_mov_b32 m0, s92
	s_nop 0
	global_load_lds_dwordx4 v[174:175], off
	s_waitcnt vmcnt(8)
	s_waitcnt lgkmcnt(0)
	s_barrier
	s_setprio 1
	s_waitcnt lgkmcnt(0)
	v_mfma_scale_f32_16x16x128_f8f6f4 v[94:97], v[2:9], v[196:203], v[94:97], v195, v195 op_sel_hi:[0,0,0]
	v_mfma_scale_f32_16x16x128_f8f6f4 v[90:93], v[10:17], v[196:203], v[90:93], v195, v195 op_sel_hi:[0,0,0]
	v_mfma_scale_f32_16x16x128_f8f6f4 v[82:85], v[10:17], v[204:211], v[82:85], v195, v195 op_sel_hi:[0,0,0]
	v_mfma_scale_f32_16x16x128_f8f6f4 v[86:89], v[2:9], v[204:211], v[86:89], v195, v195 op_sel_hi:[0,0,0]
	v_mfma_scale_f32_16x16x128_f8f6f4 v[78:81], v[2:9], v[212:219], v[78:81], v195, v195 op_sel_hi:[0,0,0]
	v_mfma_scale_f32_16x16x128_f8f6f4 v[74:77], v[10:17], v[212:219], v[74:77], v195, v195 op_sel_hi:[0,0,0]
	v_mfma_scale_f32_16x16x128_f8f6f4 v[66:69], v[10:17], v[220:227], v[66:69], v195, v195 op_sel_hi:[0,0,0]
	v_mfma_scale_f32_16x16x128_f8f6f4 v[70:73], v[2:9], v[220:227], v[70:73], v195, v195 op_sel_hi:[0,0,0]
	s_setprio 0
	s_setprio 1
	v_mfma_scale_f32_16x16x128_f8f6f4 v[38:41], v[18:25], v[220:227], v[38:41], v195, v195 op_sel_hi:[0,0,0]
	v_mfma_scale_f32_16x16x128_f8f6f4 v[34:37], v[26:33], v[220:227], v[34:37], v195, v195 op_sel_hi:[0,0,0]
	v_mfma_scale_f32_16x16x128_f8f6f4 v[42:45], v[26:33], v[212:219], v[42:45], v195, v195 op_sel_hi:[0,0,0]
	v_mfma_scale_f32_16x16x128_f8f6f4 v[46:49], v[18:25], v[212:219], v[46:49], v195, v195 op_sel_hi:[0,0,0]
	v_mfma_scale_f32_16x16x128_f8f6f4 v[54:57], v[18:25], v[204:211], v[54:57], v195, v195 op_sel_hi:[0,0,0]
	v_mfma_scale_f32_16x16x128_f8f6f4 v[50:53], v[26:33], v[204:211], v[50:53], v195, v195 op_sel_hi:[0,0,0]
	v_mfma_scale_f32_16x16x128_f8f6f4 v[58:61], v[26:33], v[196:203], v[58:61], v195, v195 op_sel_hi:[0,0,0]
	v_mfma_scale_f32_16x16x128_f8f6f4 v[62:65], v[18:25], v[196:203], v[62:65], v195, v195 op_sel_hi:[0,0,0]
	s_setprio 0
	s_barrier
	s_andn2_b64 vcc, exec, s[42:43]
	s_cbranch_vccnz .LBB0_618
	s_barrier

.LBB0_630:
	s_ashr_i32 s54, s48, 1
	s_ashr_i32 s51, s50, 31
	s_ashr_i32 s55, s54, 31
	s_lshl_b64 s[52:53], s[50:51], 19
	s_lshl_b64 s[54:55], s[54:55], 9
	s_waitcnt vmcnt(0)
	ds_read_b128 v[18:21], v181
	ds_read_b128 v[22:25], v181 offset:1024
	ds_read_b128 v[26:29], v181 offset:2048
	ds_read_b128 v[30:33], v181 offset:3072
	ds_read_b128 v[2:5], v181 offset:16384
	ds_read_b128 v[6:9], v181 offset:17408
	ds_read_b128 v[10:13], v181 offset:18432
	ds_read_b128 v[14:17], v181 offset:19456
	s_add_u32 s5, s26, s52
	s_addc_u32 s33, s27, s53
	s_add_u32 s52, s5, s54
	s_addc_u32 s53, s33, s55
	s_and_b64 s[54:55], s[2:3], exec
	s_cselect_b32 s81, s53, s75
	s_cselect_b32 s80, s52, s74
	s_ashr_i32 s49, s48, 31
	s_lshl_b64 s[54:55], s[48:49], 17
	v_readlane_b32 s5, v254, 9
	s_add_u32 s54, s5, s54
	v_readlane_b32 s5, v254, 10
	s_addc_u32 s55, s5, s55
	s_and_b64 s[62:63], s[2:3], exec
	s_cselect_b32 s79, s55, s77
	s_cselect_b32 s78, s54, s76
	s_add_u32 s62, s74, 0x40080
	s_addc_u32 s63, s75, 0
	s_add_i32 s33, s8, 0xc000
	v_lshl_add_u64 v[174:175], s[62:63], 0, v[166:167]
	s_mov_b32 m0, s33
	s_add_i32 s5, s8, 0xe000
	ds_read_b128 v[190:193], v187
	ds_read_b128 v[194:197], v187 offset:1024
	ds_read_b128 v[198:201], v187 offset:2048
	ds_read_b128 v[202:205], v187 offset:3072
	ds_read_b128 v[206:209], v187 offset:4096
	ds_read_b128 v[210:213], v187 offset:5120
	ds_read_b128 v[214:217], v187 offset:6144
	ds_read_b128 v[218:221], v187 offset:7168
	global_load_lds_dwordx4 v[174:175], off
	v_lshl_add_u64 v[174:175], s[62:63], 0, v[168:169]
	s_mov_b32 m0, s5
	s_nop 0
	global_load_lds_dwordx4 v[174:175], off
	s_waitcnt vmcnt(8)
	s_waitcnt lgkmcnt(0)
	s_barrier
	s_setprio 1
	s_waitcnt lgkmcnt(0)
	v_mfma_scale_f32_16x16x128_f8f6f4 v[158:161], v[18:25], v[190:197], 0, v188, v188 op_sel_hi:[0,0,0]
	v_mfma_scale_f32_16x16x128_f8f6f4 v[154:157], v[26:33], v[190:197], 0, v188, v188 op_sel_hi:[0,0,0]
	v_mfma_scale_f32_16x16x128_f8f6f4 v[146:149], v[26:33], v[198:205], 0, v188, v188 op_sel_hi:[0,0,0]
	v_mfma_scale_f32_16x16x128_f8f6f4 v[150:153], v[18:25], v[198:205], 0, v188, v188 op_sel_hi:[0,0,0]
	v_mfma_scale_f32_16x16x128_f8f6f4 v[142:145], v[18:25], v[206:213], 0, v188, v188 op_sel_hi:[0,0,0]
	v_mfma_scale_f32_16x16x128_f8f6f4 v[138:141], v[26:33], v[206:213], 0, v188, v188 op_sel_hi:[0,0,0]
	v_mfma_scale_f32_16x16x128_f8f6f4 v[130:133], v[26:33], v[214:221], 0, v188, v188 op_sel_hi:[0,0,0]
	v_mfma_scale_f32_16x16x128_f8f6f4 v[134:137], v[18:25], v[214:221], 0, v188, v188 op_sel_hi:[0,0,0]
	s_setprio 0
	s_setprio 1
	v_mfma_scale_f32_16x16x128_f8f6f4 v[102:105], v[2:9], v[214:221], 0, v188, v188 op_sel_hi:[0,0,0]
	v_mfma_scale_f32_16x16x128_f8f6f4 v[98:101], v[10:17], v[214:221], 0, v188, v188 op_sel_hi:[0,0,0]
	v_mfma_scale_f32_16x16x128_f8f6f4 v[106:109], v[10:17], v[206:213], 0, v188, v188 op_sel_hi:[0,0,0]
	v_mfma_scale_f32_16x16x128_f8f6f4 v[110:113], v[2:9], v[206:213], 0, v188, v188 op_sel_hi:[0,0,0]
	v_mfma_scale_f32_16x16x128_f8f6f4 v[118:121], v[2:9], v[198:205], 0, v188, v188 op_sel_hi:[0,0,0]
	v_mfma_scale_f32_16x16x128_f8f6f4 v[114:117], v[10:17], v[198:205], 0, v188, v188 op_sel_hi:[0,0,0]
	v_mfma_scale_f32_16x16x128_f8f6f4 v[122:125], v[10:17], v[190:197], 0, v188, v188 op_sel_hi:[0,0,0]
	v_mfma_scale_f32_16x16x128_f8f6f4 v[126:129], v[2:9], v[190:197], 0, v188, v188 op_sel_hi:[0,0,0]
	s_setprio 0
	s_barrier
	v_lshl_add_u64 v[174:175], s[76:77], 0, v[162:163]
	s_mov_b32 m0, s9
	v_lshl_add_u64 v[176:177], v[174:175], 0, s[44:45]
	ds_read_b128 v[190:193], v187 offset:16384
	ds_read_b128 v[194:197], v187 offset:17408
	ds_read_b128 v[198:201], v187 offset:18432
	ds_read_b128 v[202:205], v187 offset:19456
	ds_read_b128 v[206:209], v187 offset:20480
	ds_read_b128 v[210:213], v187 offset:21504
	ds_read_b128 v[214:217], v187 offset:22528
	ds_read_b128 v[218:221], v187 offset:23552
	global_load_lds_dwordx4 v[176:177], off
	v_lshl_add_u64 v[176:177], s[76:77], 0, v[164:165]
	s_add_u32 s62, s76, 0x10100
	v_lshl_add_u64 v[182:183], v[176:177], 0, s[44:45]
	s_mov_b32 m0, s61
	s_addc_u32 s63, s77, 0
	global_load_lds_dwordx4 v[182:183], off
	v_lshl_add_u64 v[182:183], s[62:63], 0, v[162:163]
	s_mov_b32 m0, s68
	s_nop 0
	global_load_lds_dwordx4 v[182:183], off
	v_lshl_add_u64 v[182:183], s[62:63], 0, v[164:165]
	s_mov_b32 m0, s69
	s_nop 0
	global_load_lds_dwordx4 v[182:183], off
	v_lshl_add_u64 v[182:183], s[74:75], 0, v[166:167]
	v_lshl_add_u64 v[184:185], v[182:183], 0, s[44:45]
	s_mov_b32 m0, s8
	s_nop 0
	global_load_lds_dwordx4 v[184:185], off
	v_lshl_add_u64 v[184:185], s[74:75], 0, v[168:169]
	v_lshl_add_u64 v[222:223], v[184:185], 0, s[44:45]
	s_mov_b32 m0, s71
	s_nop 0
	global_load_lds_dwordx4 v[222:223], off
	s_waitcnt vmcnt(8)
	s_waitcnt lgkmcnt(0)
	s_barrier
	s_setprio 1
	s_waitcnt lgkmcnt(0)
	v_mfma_scale_f32_16x16x128_f8f6f4 v[94:97], v[18:25], v[190:197], 0, v188, v188 op_sel_hi:[0,0,0]
	v_mfma_scale_f32_16x16x128_f8f6f4 v[90:93], v[26:33], v[190:197], 0, v188, v188 op_sel_hi:[0,0,0]
	v_mfma_scale_f32_16x16x128_f8f6f4 v[82:85], v[26:33], v[198:205], 0, v188, v188 op_sel_hi:[0,0,0]
	v_mfma_scale_f32_16x16x128_f8f6f4 v[86:89], v[18:25], v[198:205], 0, v188, v188 op_sel_hi:[0,0,0]
	v_mfma_scale_f32_16x16x128_f8f6f4 v[78:81], v[18:25], v[206:213], 0, v188, v188 op_sel_hi:[0,0,0]
	v_mfma_scale_f32_16x16x128_f8f6f4 v[74:77], v[26:33], v[206:213], 0, v188, v188 op_sel_hi:[0,0,0]
	v_mfma_scale_f32_16x16x128_f8f6f4 v[66:69], v[26:33], v[214:221], 0, v188, v188 op_sel_hi:[0,0,0]
	v_mfma_scale_f32_16x16x128_f8f6f4 v[70:73], v[18:25], v[214:221], 0, v188, v188 op_sel_hi:[0,0,0]
	s_setprio 0
	s_setprio 1
	v_mfma_scale_f32_16x16x128_f8f6f4 v[38:41], v[2:9], v[214:221], 0, v188, v188 op_sel_hi:[0,0,0]
	v_mfma_scale_f32_16x16x128_f8f6f4 v[34:37], v[10:17], v[214:221], 0, v188, v188 op_sel_hi:[0,0,0]
	v_mfma_scale_f32_16x16x128_f8f6f4 v[42:45], v[10:17], v[206:213], 0, v188, v188 op_sel_hi:[0,0,0]
	v_mfma_scale_f32_16x16x128_f8f6f4 v[46:49], v[2:9], v[206:213], 0, v188, v188 op_sel_hi:[0,0,0]
	v_mfma_scale_f32_16x16x128_f8f6f4 v[54:57], v[2:9], v[198:205], 0, v188, v188 op_sel_hi:[0,0,0]
	v_mfma_scale_f32_16x16x128_f8f6f4 v[50:53], v[10:17], v[198:205], 0, v188, v188 op_sel_hi:[0,0,0]
	v_mfma_scale_f32_16x16x128_f8f6f4 v[58:61], v[10:17], v[190:197], 0, v188, v188 op_sel_hi:[0,0,0]
	v_mfma_scale_f32_16x16x128_f8f6f4 v[62:65], v[2:9], v[190:197], 0, v188, v188 op_sel_hi:[0,0,0]
	s_setprio 0
	s_barrier
	ds_read_b128 v[2:5], v181 offset:32768
	ds_read_b128 v[6:9], v181 offset:33792
	ds_read_b128 v[10:13], v181 offset:34816
	ds_read_b128 v[14:17], v181 offset:35840
	ds_read_b128 v[18:21], v181 offset:49152
	ds_read_b128 v[22:25], v181 offset:50176
	ds_read_b128 v[26:29], v181 offset:51200
	ds_read_b128 v[30:33], v181 offset:52224
	s_add_u32 s62, s74, 0x40100
	s_addc_u32 s63, s75, 0
	s_mov_b32 m0, s73
	v_lshl_add_u64 v[222:223], s[62:63], 0, v[166:167]
	ds_read_b128 v[190:193], v187 offset:32768
	ds_read_b128 v[194:197], v187 offset:33792
	ds_read_b128 v[198:201], v187 offset:34816
	ds_read_b128 v[202:205], v187 offset:35840
	ds_read_b128 v[206:209], v187 offset:36864
	ds_read_b128 v[210:213], v187 offset:37888
	ds_read_b128 v[214:217], v187 offset:38912
	ds_read_b128 v[218:221], v187 offset:39936
	global_load_lds_dwordx4 v[222:223], off
	v_lshl_add_u64 v[222:223], s[62:63], 0, v[168:169]
	s_mov_b32 m0, s82
	s_nop 0
	global_load_lds_dwordx4 v[222:223], off
	s_waitcnt vmcnt(8)
	s_waitcnt lgkmcnt(0)
	s_barrier
	s_setprio 1
	s_waitcnt lgkmcnt(0)
	v_mfma_scale_f32_16x16x128_f8f6f4 v[158:161], v[2:9], v[190:197], v[158:161], v188, v188 op_sel_hi:[0,0,0]
	v_mfma_scale_f32_16x16x128_f8f6f4 v[154:157], v[10:17], v[190:197], v[154:157], v188, v188 op_sel_hi:[0,0,0]
	v_mfma_scale_f32_16x16x128_f8f6f4 v[146:149], v[10:17], v[198:205], v[146:149], v188, v188 op_sel_hi:[0,0,0]
	v_mfma_scale_f32_16x16x128_f8f6f4 v[150:153], v[2:9], v[198:205], v[150:153], v188, v188 op_sel_hi:[0,0,0]
	v_mfma_scale_f32_16x16x128_f8f6f4 v[142:145], v[2:9], v[206:213], v[142:145], v188, v188 op_sel_hi:[0,0,0]
	v_mfma_scale_f32_16x16x128_f8f6f4 v[138:141], v[10:17], v[206:213], v[138:141], v188, v188 op_sel_hi:[0,0,0]
	v_mfma_scale_f32_16x16x128_f8f6f4 v[130:133], v[10:17], v[214:221], v[130:133], v188, v188 op_sel_hi:[0,0,0]
	v_mfma_scale_f32_16x16x128_f8f6f4 v[134:137], v[2:9], v[214:221], v[134:137], v188, v188 op_sel_hi:[0,0,0]
	s_setprio 0
	s_setprio 1
	v_mfma_scale_f32_16x16x128_f8f6f4 v[102:105], v[18:25], v[214:221], v[102:105], v188, v188 op_sel_hi:[0,0,0]
	v_mfma_scale_f32_16x16x128_f8f6f4 v[98:101], v[26:33], v[214:221], v[98:101], v188, v188 op_sel_hi:[0,0,0]
	v_mfma_scale_f32_16x16x128_f8f6f4 v[106:109], v[26:33], v[206:213], v[106:109], v188, v188 op_sel_hi:[0,0,0]
	v_mfma_scale_f32_16x16x128_f8f6f4 v[110:113], v[18:25], v[206:213], v[110:113], v188, v188 op_sel_hi:[0,0,0]
	v_mfma_scale_f32_16x16x128_f8f6f4 v[118:121], v[18:25], v[198:205], v[118:121], v188, v188 op_sel_hi:[0,0,0]
	v_mfma_scale_f32_16x16x128_f8f6f4 v[114:117], v[26:33], v[198:205], v[114:117], v188, v188 op_sel_hi:[0,0,0]
	v_mfma_scale_f32_16x16x128_f8f6f4 v[122:125], v[26:33], v[190:197], v[122:125], v188, v188 op_sel_hi:[0,0,0]
	v_mfma_scale_f32_16x16x128_f8f6f4 v[126:129], v[18:25], v[190:197], v[126:129], v188, v188 op_sel_hi:[0,0,0]
	s_setprio 0
	s_barrier
	s_mov_b32 m0, s83
	v_lshl_add_u64 v[174:175], v[174:175], 0, s[46:47]
	s_add_u32 s62, s76, 0x10180
	ds_read_b128 v[190:193], v187 offset:49152
	ds_read_b128 v[194:197], v187 offset:50176
	ds_read_b128 v[198:201], v187 offset:51200
	ds_read_b128 v[202:205], v187 offset:52224
	ds_read_b128 v[206:209], v187 offset:53248
	ds_read_b128 v[210:213], v187 offset:54272
	ds_read_b128 v[214:217], v187 offset:55296
	ds_read_b128 v[218:221], v187 offset:56320
	global_load_lds_dwordx4 v[174:175], off
	v_lshl_add_u64 v[174:175], v[176:177], 0, s[46:47]
	s_mov_b32 m0, s84
	s_addc_u32 s63, s77, 0
	global_load_lds_dwordx4 v[174:175], off
	v_lshl_add_u64 v[174:175], s[62:63], 0, v[162:163]
	s_mov_b32 m0, s87
	s_nop 0
	global_load_lds_dwordx4 v[174:175], off
	v_lshl_add_u64 v[174:175], s[62:63], 0, v[164:165]
	s_mov_b32 m0, s88
	s_nop 0
	global_load_lds_dwordx4 v[174:175], off
	v_lshl_add_u64 v[174:175], v[182:183], 0, s[46:47]
	s_mov_b32 m0, s85
	s_nop 0
	global_load_lds_dwordx4 v[174:175], off
	v_lshl_add_u64 v[174:175], v[184:185], 0, s[46:47]
	s_mov_b32 m0, s86
	s_nop 0
	global_load_lds_dwordx4 v[174:175], off
	s_waitcnt vmcnt(8)
	s_waitcnt lgkmcnt(0)
	s_barrier
	s_setprio 1
	s_waitcnt lgkmcnt(0)
	v_mfma_scale_f32_16x16x128_f8f6f4 v[94:97], v[2:9], v[190:197], v[94:97], v188, v188 op_sel_hi:[0,0,0]
	v_mfma_scale_f32_16x16x128_f8f6f4 v[90:93], v[10:17], v[190:197], v[90:93], v188, v188 op_sel_hi:[0,0,0]
	v_mfma_scale_f32_16x16x128_f8f6f4 v[82:85], v[10:17], v[198:205], v[82:85], v188, v188 op_sel_hi:[0,0,0]
	v_mfma_scale_f32_16x16x128_f8f6f4 v[86:89], v[2:9], v[198:205], v[86:89], v188, v188 op_sel_hi:[0,0,0]
	v_mfma_scale_f32_16x16x128_f8f6f4 v[78:81], v[2:9], v[206:213], v[78:81], v188, v188 op_sel_hi:[0,0,0]
	v_mfma_scale_f32_16x16x128_f8f6f4 v[74:77], v[10:17], v[206:213], v[74:77], v188, v188 op_sel_hi:[0,0,0]
	v_mfma_scale_f32_16x16x128_f8f6f4 v[66:69], v[10:17], v[214:221], v[66:69], v188, v188 op_sel_hi:[0,0,0]
	v_mfma_scale_f32_16x16x128_f8f6f4 v[70:73], v[2:9], v[214:221], v[70:73], v188, v188 op_sel_hi:[0,0,0]
	s_setprio 0
	s_setprio 1
	v_mfma_scale_f32_16x16x128_f8f6f4 v[38:41], v[18:25], v[214:221], v[38:41], v188, v188 op_sel_hi:[0,0,0]
	v_mfma_scale_f32_16x16x128_f8f6f4 v[34:37], v[26:33], v[214:221], v[34:37], v188, v188 op_sel_hi:[0,0,0]
	v_mfma_scale_f32_16x16x128_f8f6f4 v[42:45], v[26:33], v[206:213], v[42:45], v188, v188 op_sel_hi:[0,0,0]
	v_mfma_scale_f32_16x16x128_f8f6f4 v[46:49], v[18:25], v[206:213], v[46:49], v188, v188 op_sel_hi:[0,0,0]
	v_mfma_scale_f32_16x16x128_f8f6f4 v[54:57], v[18:25], v[198:205], v[54:57], v188, v188 op_sel_hi:[0,0,0]
	v_mfma_scale_f32_16x16x128_f8f6f4 v[50:53], v[26:33], v[198:205], v[50:53], v188, v188 op_sel_hi:[0,0,0]
	v_mfma_scale_f32_16x16x128_f8f6f4 v[58:61], v[26:33], v[190:197], v[58:61], v188, v188 op_sel_hi:[0,0,0]
	v_mfma_scale_f32_16x16x128_f8f6f4 v[62:65], v[18:25], v[190:197], v[62:65], v188, v188 op_sel_hi:[0,0,0]
	s_setprio 0
	s_barrier
	ds_read_b128 v[2:5], v181
	ds_read_b128 v[6:9], v181 offset:1024
	ds_read_b128 v[10:13], v181 offset:2048
	ds_read_b128 v[14:17], v181 offset:3072
	ds_read_b128 v[18:21], v181 offset:16384
	ds_read_b128 v[22:25], v181 offset:17408
	ds_read_b128 v[26:29], v181 offset:18432
	ds_read_b128 v[30:33], v181 offset:19456
	s_add_u32 s62, s74, 0x40180
	s_addc_u32 s63, s75, 0
	s_mov_b32 m0, s33
	v_lshl_add_u64 v[174:175], s[62:63], 0, v[166:167]
	ds_read_b128 v[190:193], v187
	ds_read_b128 v[194:197], v187 offset:1024
	ds_read_b128 v[198:201], v187 offset:2048
	ds_read_b128 v[202:205], v187 offset:3072
	ds_read_b128 v[206:209], v187 offset:4096
	ds_read_b128 v[210:213], v187 offset:5120
	ds_read_b128 v[214:217], v187 offset:6144
	ds_read_b128 v[218:221], v187 offset:7168
	global_load_lds_dwordx4 v[174:175], off
	v_lshl_add_u64 v[174:175], s[62:63], 0, v[168:169]
	s_mov_b32 m0, s5
	s_nop 0
	global_load_lds_dwordx4 v[174:175], off
	s_waitcnt vmcnt(8)
	s_waitcnt lgkmcnt(0)
	s_barrier
	s_setprio 1
	s_waitcnt lgkmcnt(0)
	v_mfma_scale_f32_16x16x128_f8f6f4 v[158:161], v[2:9], v[190:197], v[158:161], v188, v188 op_sel_hi:[0,0,0]
	v_mfma_scale_f32_16x16x128_f8f6f4 v[154:157], v[10:17], v[190:197], v[154:157], v188, v188 op_sel_hi:[0,0,0]
	v_mfma_scale_f32_16x16x128_f8f6f4 v[146:149], v[10:17], v[198:205], v[146:149], v188, v188 op_sel_hi:[0,0,0]
	v_mfma_scale_f32_16x16x128_f8f6f4 v[150:153], v[2:9], v[198:205], v[150:153], v188, v188 op_sel_hi:[0,0,0]
	v_mfma_scale_f32_16x16x128_f8f6f4 v[142:145], v[2:9], v[206:213], v[142:145], v188, v188 op_sel_hi:[0,0,0]
	v_mfma_scale_f32_16x16x128_f8f6f4 v[138:141], v[10:17], v[206:213], v[138:141], v188, v188 op_sel_hi:[0,0,0]
	v_mfma_scale_f32_16x16x128_f8f6f4 v[130:133], v[10:17], v[214:221], v[130:133], v188, v188 op_sel_hi:[0,0,0]
	v_mfma_scale_f32_16x16x128_f8f6f4 v[134:137], v[2:9], v[214:221], v[134:137], v188, v188 op_sel_hi:[0,0,0]
	s_setprio 0
	s_setprio 1
	v_mfma_scale_f32_16x16x128_f8f6f4 v[102:105], v[18:25], v[214:221], v[102:105], v188, v188 op_sel_hi:[0,0,0]
	v_mfma_scale_f32_16x16x128_f8f6f4 v[98:101], v[26:33], v[214:221], v[98:101], v188, v188 op_sel_hi:[0,0,0]
	v_mfma_scale_f32_16x16x128_f8f6f4 v[106:109], v[26:33], v[206:213], v[106:109], v188, v188 op_sel_hi:[0,0,0]
	v_mfma_scale_f32_16x16x128_f8f6f4 v[110:113], v[18:25], v[206:213], v[110:113], v188, v188 op_sel_hi:[0,0,0]
	v_mfma_scale_f32_16x16x128_f8f6f4 v[118:121], v[18:25], v[198:205], v[118:121], v188, v188 op_sel_hi:[0,0,0]
	v_mfma_scale_f32_16x16x128_f8f6f4 v[114:117], v[26:33], v[198:205], v[114:117], v188, v188 op_sel_hi:[0,0,0]
	v_mfma_scale_f32_16x16x128_f8f6f4 v[122:125], v[26:33], v[190:197], v[122:125], v188, v188 op_sel_hi:[0,0,0]
	v_mfma_scale_f32_16x16x128_f8f6f4 v[126:129], v[18:25], v[190:197], v[126:129], v188, v188 op_sel_hi:[0,0,0]
	s_setprio 0
	s_barrier
	s_mov_b32 m0, s9
	v_lshl_add_u64 v[174:175], s[78:79], 0, v[162:163]
	s_add_u32 s62, s78, 0x10000
	ds_read_b128 v[190:193], v187 offset:16384
	ds_read_b128 v[194:197], v187 offset:17408
	ds_read_b128 v[198:201], v187 offset:18432
	ds_read_b128 v[202:205], v187 offset:19456
	ds_read_b128 v[206:209], v187 offset:20480
	ds_read_b128 v[210:213], v187 offset:21504
	ds_read_b128 v[214:217], v187 offset:22528
	ds_read_b128 v[218:221], v187 offset:23552
	global_load_lds_dwordx4 v[174:175], off
	v_lshl_add_u64 v[176:177], s[78:79], 0, v[164:165]
	s_mov_b32 m0, s61
	s_addc_u32 s63, s79, 0
	global_load_lds_dwordx4 v[176:177], off
	v_lshl_add_u64 v[182:183], s[62:63], 0, v[162:163]
	s_mov_b32 m0, s68
	v_lshl_add_u64 v[184:185], s[80:81], 0, v[168:169]
	global_load_lds_dwordx4 v[182:183], off
	v_lshl_add_u64 v[182:183], s[62:63], 0, v[164:165]
	s_mov_b32 m0, s69
	s_nop 0
	global_load_lds_dwordx4 v[182:183], off
	v_lshl_add_u64 v[182:183], s[80:81], 0, v[166:167]
	s_mov_b32 m0, s8
	s_nop 0
	global_load_lds_dwordx4 v[182:183], off
	s_mov_b32 m0, s71
	s_nop 0
	global_load_lds_dwordx4 v[184:185], off
	s_waitcnt vmcnt(8)
	s_waitcnt lgkmcnt(0)
	s_barrier
	s_setprio 1
	s_waitcnt lgkmcnt(0)
	v_mfma_scale_f32_16x16x128_f8f6f4 v[94:97], v[2:9], v[190:197], v[94:97], v188, v188 op_sel_hi:[0,0,0]
	v_mfma_scale_f32_16x16x128_f8f6f4 v[90:93], v[10:17], v[190:197], v[90:93], v188, v188 op_sel_hi:[0,0,0]
	v_mfma_scale_f32_16x16x128_f8f6f4 v[82:85], v[10:17], v[198:205], v[82:85], v188, v188 op_sel_hi:[0,0,0]
	v_mfma_scale_f32_16x16x128_f8f6f4 v[86:89], v[2:9], v[198:205], v[86:89], v188, v188 op_sel_hi:[0,0,0]
	v_mfma_scale_f32_16x16x128_f8f6f4 v[78:81], v[2:9], v[206:213], v[78:81], v188, v188 op_sel_hi:[0,0,0]
	v_mfma_scale_f32_16x16x128_f8f6f4 v[74:77], v[10:17], v[206:213], v[74:77], v188, v188 op_sel_hi:[0,0,0]
	v_mfma_scale_f32_16x16x128_f8f6f4 v[66:69], v[10:17], v[214:221], v[66:69], v188, v188 op_sel_hi:[0,0,0]
	v_mfma_scale_f32_16x16x128_f8f6f4 v[70:73], v[2:9], v[214:221], v[70:73], v188, v188 op_sel_hi:[0,0,0]
	s_setprio 0
	s_setprio 1
	v_mfma_scale_f32_16x16x128_f8f6f4 v[38:41], v[18:25], v[214:221], v[38:41], v188, v188 op_sel_hi:[0,0,0]
	v_mfma_scale_f32_16x16x128_f8f6f4 v[34:37], v[26:33], v[214:221], v[34:37], v188, v188 op_sel_hi:[0,0,0]
	v_mfma_scale_f32_16x16x128_f8f6f4 v[42:45], v[26:33], v[206:213], v[42:45], v188, v188 op_sel_hi:[0,0,0]
	v_mfma_scale_f32_16x16x128_f8f6f4 v[46:49], v[18:25], v[206:213], v[46:49], v188, v188 op_sel_hi:[0,0,0]
	v_mfma_scale_f32_16x16x128_f8f6f4 v[54:57], v[18:25], v[198:205], v[54:57], v188, v188 op_sel_hi:[0,0,0]
	v_mfma_scale_f32_16x16x128_f8f6f4 v[50:53], v[26:33], v[198:205], v[50:53], v188, v188 op_sel_hi:[0,0,0]
	v_mfma_scale_f32_16x16x128_f8f6f4 v[58:61], v[26:33], v[190:197], v[58:61], v188, v188 op_sel_hi:[0,0,0]
	v_mfma_scale_f32_16x16x128_f8f6f4 v[62:65], v[18:25], v[190:197], v[62:65], v188, v188 op_sel_hi:[0,0,0]
	s_setprio 0
	s_barrier
	ds_read_b128 v[2:5], v181 offset:32768
	ds_read_b128 v[6:9], v181 offset:33792
	ds_read_b128 v[10:13], v181 offset:34816
	ds_read_b128 v[14:17], v181 offset:35840
	ds_read_b128 v[18:21], v181 offset:49152
	ds_read_b128 v[22:25], v181 offset:50176
	ds_read_b128 v[26:29], v181 offset:51200
	ds_read_b128 v[30:33], v181 offset:52224
	s_add_u32 s62, s80, 0x40000
	s_addc_u32 s63, s81, 0
	s_mov_b32 m0, s73
	v_lshl_add_u64 v[222:223], s[62:63], 0, v[166:167]
	ds_read_b128 v[190:193], v187 offset:32768
	ds_read_b128 v[194:197], v187 offset:33792
	ds_read_b128 v[198:201], v187 offset:34816
	ds_read_b128 v[202:205], v187 offset:35840
	ds_read_b128 v[206:209], v187 offset:36864
	ds_read_b128 v[210:213], v187 offset:37888
	ds_read_b128 v[214:217], v187 offset:38912
	ds_read_b128 v[218:221], v187 offset:39936
	global_load_lds_dwordx4 v[222:223], off
	v_lshl_add_u64 v[222:223], s[62:63], 0, v[168:169]
	s_mov_b32 m0, s82
	s_nop 0
	global_load_lds_dwordx4 v[222:223], off
	s_waitcnt vmcnt(8)
	s_waitcnt lgkmcnt(0)
	s_barrier
	s_setprio 1
	s_waitcnt lgkmcnt(0)
	v_mfma_scale_f32_16x16x128_f8f6f4 v[158:161], v[2:9], v[190:197], v[158:161], v188, v188 op_sel_hi:[0,0,0]
	v_mfma_scale_f32_16x16x128_f8f6f4 v[154:157], v[10:17], v[190:197], v[154:157], v188, v188 op_sel_hi:[0,0,0]
	v_mfma_scale_f32_16x16x128_f8f6f4 v[146:149], v[10:17], v[198:205], v[146:149], v188, v188 op_sel_hi:[0,0,0]
	v_mfma_scale_f32_16x16x128_f8f6f4 v[150:153], v[2:9], v[198:205], v[150:153], v188, v188 op_sel_hi:[0,0,0]
	v_mfma_scale_f32_16x16x128_f8f6f4 v[142:145], v[2:9], v[206:213], v[142:145], v188, v188 op_sel_hi:[0,0,0]
	v_mfma_scale_f32_16x16x128_f8f6f4 v[138:141], v[10:17], v[206:213], v[138:141], v188, v188 op_sel_hi:[0,0,0]
	v_mfma_scale_f32_16x16x128_f8f6f4 v[130:133], v[10:17], v[214:221], v[130:133], v188, v188 op_sel_hi:[0,0,0]
	v_mfma_scale_f32_16x16x128_f8f6f4 v[134:137], v[2:9], v[214:221], v[134:137], v188, v188 op_sel_hi:[0,0,0]
	s_setprio 0
	s_setprio 1
	v_mfma_scale_f32_16x16x128_f8f6f4 v[102:105], v[18:25], v[214:221], v[102:105], v188, v188 op_sel_hi:[0,0,0]
	v_mfma_scale_f32_16x16x128_f8f6f4 v[98:101], v[26:33], v[214:221], v[98:101], v188, v188 op_sel_hi:[0,0,0]
	v_mfma_scale_f32_16x16x128_f8f6f4 v[106:109], v[26:33], v[206:213], v[106:109], v188, v188 op_sel_hi:[0,0,0]
	v_mfma_scale_f32_16x16x128_f8f6f4 v[110:113], v[18:25], v[206:213], v[110:113], v188, v188 op_sel_hi:[0,0,0]
	v_mfma_scale_f32_16x16x128_f8f6f4 v[118:121], v[18:25], v[198:205], v[118:121], v188, v188 op_sel_hi:[0,0,0]
	v_mfma_scale_f32_16x16x128_f8f6f4 v[114:117], v[26:33], v[198:205], v[114:117], v188, v188 op_sel_hi:[0,0,0]
	v_mfma_scale_f32_16x16x128_f8f6f4 v[122:125], v[26:33], v[190:197], v[122:125], v188, v188 op_sel_hi:[0,0,0]
	v_mfma_scale_f32_16x16x128_f8f6f4 v[126:129], v[18:25], v[190:197], v[126:129], v188, v188 op_sel_hi:[0,0,0]
	s_setprio 0
	s_barrier
	s_mov_b32 m0, s83
	v_lshl_add_u64 v[174:175], v[174:175], 0, s[38:39]
	s_add_u32 s62, s78, 0x10080
	ds_read_b128 v[190:193], v187 offset:49152
	ds_read_b128 v[194:197], v187 offset:50176
	ds_read_b128 v[198:201], v187 offset:51200
	ds_read_b128 v[202:205], v187 offset:52224
	ds_read_b128 v[206:209], v187 offset:53248
	ds_read_b128 v[210:213], v187 offset:54272
	ds_read_b128 v[214:217], v187 offset:55296
	ds_read_b128 v[218:221], v187 offset:56320
	global_load_lds_dwordx4 v[174:175], off
	v_lshl_add_u64 v[174:175], v[176:177], 0, s[38:39]
	s_mov_b32 m0, s84
	s_addc_u32 s63, s79, 0
	global_load_lds_dwordx4 v[174:175], off
	v_lshl_add_u64 v[174:175], s[62:63], 0, v[162:163]
	s_mov_b32 m0, s87
	s_nop 0
	global_load_lds_dwordx4 v[174:175], off
	v_lshl_add_u64 v[174:175], s[62:63], 0, v[164:165]
	s_mov_b32 m0, s88
	s_nop 0
	global_load_lds_dwordx4 v[174:175], off
	v_lshl_add_u64 v[174:175], v[182:183], 0, s[38:39]
	s_mov_b32 m0, s85
	s_nop 0
	global_load_lds_dwordx4 v[174:175], off
	v_lshl_add_u64 v[174:175], v[184:185], 0, s[38:39]
	s_mov_b32 m0, s86
	s_nop 0
	global_load_lds_dwordx4 v[174:175], off
	s_waitcnt vmcnt(8)
	s_waitcnt lgkmcnt(0)
	s_barrier
	s_setprio 1
	s_waitcnt lgkmcnt(0)
	v_mfma_scale_f32_16x16x128_f8f6f4 v[94:97], v[2:9], v[190:197], v[94:97], v188, v188 op_sel_hi:[0,0,0]
	v_mfma_scale_f32_16x16x128_f8f6f4 v[90:93], v[10:17], v[190:197], v[90:93], v188, v188 op_sel_hi:[0,0,0]
	v_mfma_scale_f32_16x16x128_f8f6f4 v[82:85], v[10:17], v[198:205], v[82:85], v188, v188 op_sel_hi:[0,0,0]
	v_mfma_scale_f32_16x16x128_f8f6f4 v[86:89], v[2:9], v[198:205], v[86:89], v188, v188 op_sel_hi:[0,0,0]
	v_mfma_scale_f32_16x16x128_f8f6f4 v[78:81], v[2:9], v[206:213], v[78:81], v188, v188 op_sel_hi:[0,0,0]
	v_mfma_scale_f32_16x16x128_f8f6f4 v[74:77], v[10:17], v[206:213], v[74:77], v188, v188 op_sel_hi:[0,0,0]
	v_mfma_scale_f32_16x16x128_f8f6f4 v[66:69], v[10:17], v[214:221], v[66:69], v188, v188 op_sel_hi:[0,0,0]
	v_mfma_scale_f32_16x16x128_f8f6f4 v[70:73], v[2:9], v[214:221], v[70:73], v188, v188 op_sel_hi:[0,0,0]
	s_setprio 0
	s_setprio 1
	v_mfma_scale_f32_16x16x128_f8f6f4 v[38:41], v[18:25], v[214:221], v[38:41], v188, v188 op_sel_hi:[0,0,0]
	v_mfma_scale_f32_16x16x128_f8f6f4 v[34:37], v[26:33], v[214:221], v[34:37], v188, v188 op_sel_hi:[0,0,0]
	v_mfma_scale_f32_16x16x128_f8f6f4 v[42:45], v[26:33], v[206:213], v[42:45], v188, v188 op_sel_hi:[0,0,0]
	v_mfma_scale_f32_16x16x128_f8f6f4 v[46:49], v[18:25], v[206:213], v[46:49], v188, v188 op_sel_hi:[0,0,0]
	v_mfma_scale_f32_16x16x128_f8f6f4 v[54:57], v[18:25], v[198:205], v[54:57], v188, v188 op_sel_hi:[0,0,0]
	v_mfma_scale_f32_16x16x128_f8f6f4 v[50:53], v[26:33], v[198:205], v[50:53], v188, v188 op_sel_hi:[0,0,0]
	v_mfma_scale_f32_16x16x128_f8f6f4 v[58:61], v[26:33], v[190:197], v[58:61], v188, v188 op_sel_hi:[0,0,0]
	v_mfma_scale_f32_16x16x128_f8f6f4 v[62:65], v[18:25], v[190:197], v[62:65], v188, v188 op_sel_hi:[0,0,0]
	s_setprio 0
	s_barrier
	s_andn2_b64 vcc, exec, s[40:41]
	s_cbranch_vccnz .LBB0_632
	s_barrier

.LBB0_791:
	ds_read_b128 v[2:5], v189
	ds_read_b128 v[6:9], v189 offset:1024
	ds_read_b128 v[192:195], v189 offset:2048
	ds_read_b128 v[196:199], v189 offset:3072
	ds_read_b128 v[200:203], v189 offset:16384
	ds_read_b128 v[204:207], v189 offset:17408
	ds_read_b128 v[208:211], v189 offset:18432
	ds_read_b128 v[212:215], v189 offset:19456
	s_add_u32 s37, s46, 0x100
	s_addc_u32 s39, s47, 0
	s_and_b64 s[50:51], s[48:49], exec
	s_cselect_b32 s51, s1, s39
	s_cselect_b32 s50, s0, s37
	s_add_u32 s37, s44, 0x100
	s_addc_u32 s39, s45, 0
	s_and_b64 s[48:49], s[48:49], exec
	s_cselect_b32 s49, s5, s39
	s_cselect_b32 s48, s4, s37
	s_add_u32 s88, s46, 0x80080
	s_addc_u32 s89, s47, 0
	s_add_i32 s37, s8, 0xc000
	v_lshl_add_u64 v[174:175], s[88:89], 0, v[154:155]
	s_mov_b32 m0, s37
	s_add_i32 s39, s8, 0xe000
	ds_read_b128 v[216:219], v190
	ds_read_b128 v[220:223], v190 offset:1024
	ds_read_b128 v[224:227], v190 offset:2048
	ds_read_b128 v[228:231], v190 offset:3072
	ds_read_b128 v[242:245], v190 offset:4096
	ds_read_b128 v[246:249], v190 offset:5120
	ds_read_b128 v[232:235], v190 offset:6144
	ds_read_b128 v[236:239], v190 offset:7168
	global_load_lds_dwordx4 v[174:175], off
	v_lshl_add_u64 v[174:175], s[88:89], 0, v[158:159]
	s_mov_b32 m0, s39
	s_nop 0
	global_load_lds_dwordx4 v[174:175], off
	s_waitcnt vmcnt(8)
	s_waitcnt lgkmcnt(0)
	s_barrier
	s_setprio 1
	s_waitcnt lgkmcnt(0)
	v_mfma_scale_f32_16x16x128_f8f6f4 v[134:137], v[2:9], v[216:223], 0, v188, v188 op_sel_hi:[0,0,0]
	v_mfma_scale_f32_16x16x128_f8f6f4 v[130:133], v[192:199], v[216:223], 0, v188, v188 op_sel_hi:[0,0,0]
	v_mfma_scale_f32_16x16x128_f8f6f4 v[122:125], v[192:199], v[224:231], 0, v188, v188 op_sel_hi:[0,0,0]
	v_mfma_scale_f32_16x16x128_f8f6f4 v[126:129], v[2:9], v[224:231], 0, v188, v188 op_sel_hi:[0,0,0]
	v_mfma_scale_f32_16x16x128_f8f6f4 v[118:121], v[2:9], v[242:249], 0, v188, v188 op_sel_hi:[0,0,0]
	v_mfma_scale_f32_16x16x128_f8f6f4 v[114:117], v[192:199], v[242:249], 0, v188, v188 op_sel_hi:[0,0,0]
	v_mfma_scale_f32_16x16x128_f8f6f4 v[106:109], v[192:199], v[232:239], 0, v188, v188 op_sel_hi:[0,0,0]
	v_mfma_scale_f32_16x16x128_f8f6f4 v[110:113], v[2:9], v[232:239], 0, v188, v188 op_sel_hi:[0,0,0]
	s_setprio 0
	s_setprio 1
	v_mfma_scale_f32_16x16x128_f8f6f4 v[78:81], v[200:207], v[232:239], 0, v188, v188 op_sel_hi:[0,0,0]
	v_mfma_scale_f32_16x16x128_f8f6f4 v[74:77], v[208:215], v[232:239], 0, v188, v188 op_sel_hi:[0,0,0]
	v_mfma_scale_f32_16x16x128_f8f6f4 v[82:85], v[208:215], v[242:249], 0, v188, v188 op_sel_hi:[0,0,0]
	v_mfma_scale_f32_16x16x128_f8f6f4 v[86:89], v[200:207], v[242:249], 0, v188, v188 op_sel_hi:[0,0,0]
	v_mfma_scale_f32_16x16x128_f8f6f4 v[94:97], v[200:207], v[224:231], 0, v188, v188 op_sel_hi:[0,0,0]
	v_mfma_scale_f32_16x16x128_f8f6f4 v[90:93], v[208:215], v[224:231], 0, v188, v188 op_sel_hi:[0,0,0]
	v_mfma_scale_f32_16x16x128_f8f6f4 v[98:101], v[208:215], v[216:223], 0, v188, v188 op_sel_hi:[0,0,0]
	v_mfma_scale_f32_16x16x128_f8f6f4 v[102:105], v[200:207], v[216:223], 0, v188, v188 op_sel_hi:[0,0,0]
	s_setprio 0
	s_barrier
	s_mov_b32 m0, s9
	v_lshl_add_u64 v[174:175], s[48:49], 0, v[156:157]
	s_add_u32 s88, s48, 0x80000
	ds_read_b128 v[216:219], v190 offset:16384
	ds_read_b128 v[220:223], v190 offset:17408
	ds_read_b128 v[224:227], v190 offset:18432
	ds_read_b128 v[228:231], v190 offset:19456
	ds_read_b128 v[232:235], v190 offset:20480
	ds_read_b128 v[236:239], v190 offset:21504
	ds_read_b128 v[242:245], v190 offset:22528
	ds_read_b128 v[246:249], v190 offset:23552
	global_load_lds_dwordx4 v[174:175], off
	v_lshl_add_u64 v[176:177], s[48:49], 0, v[160:161]
	s_mov_b32 m0, s27
	s_addc_u32 s89, s49, 0
	global_load_lds_dwordx4 v[176:177], off
	v_lshl_add_u64 v[182:183], s[88:89], 0, v[156:157]
	s_mov_b32 m0, s33
	v_lshl_add_u64 v[184:185], s[50:51], 0, v[158:159]
	global_load_lds_dwordx4 v[182:183], off
	v_lshl_add_u64 v[182:183], s[88:89], 0, v[160:161]
	s_mov_b32 m0, s35
	s_nop 0
	global_load_lds_dwordx4 v[182:183], off
	v_lshl_add_u64 v[182:183], s[50:51], 0, v[154:155]
	s_mov_b32 m0, s8
	s_nop 0
	global_load_lds_dwordx4 v[182:183], off
	s_mov_b32 m0, s43
	s_nop 0
	global_load_lds_dwordx4 v[184:185], off
	s_waitcnt vmcnt(8)
	s_waitcnt lgkmcnt(0)
	s_barrier
	s_setprio 1
	s_waitcnt lgkmcnt(0)
	v_mfma_scale_f32_16x16x128_f8f6f4 v[70:73], v[2:9], v[216:223], 0, v188, v188 op_sel_hi:[0,0,0]
	v_mfma_scale_f32_16x16x128_f8f6f4 v[66:69], v[192:199], v[216:223], 0, v188, v188 op_sel_hi:[0,0,0]
	v_mfma_scale_f32_16x16x128_f8f6f4 v[58:61], v[192:199], v[224:231], 0, v188, v188 op_sel_hi:[0,0,0]
	v_mfma_scale_f32_16x16x128_f8f6f4 v[62:65], v[2:9], v[224:231], 0, v188, v188 op_sel_hi:[0,0,0]
	v_mfma_scale_f32_16x16x128_f8f6f4 v[54:57], v[2:9], v[232:239], 0, v188, v188 op_sel_hi:[0,0,0]
	v_mfma_scale_f32_16x16x128_f8f6f4 v[50:53], v[192:199], v[232:239], 0, v188, v188 op_sel_hi:[0,0,0]
	v_mfma_scale_f32_16x16x128_f8f6f4 v[42:45], v[192:199], v[242:249], 0, v188, v188 op_sel_hi:[0,0,0]
	v_mfma_scale_f32_16x16x128_f8f6f4 v[46:49], v[2:9], v[242:249], 0, v188, v188 op_sel_hi:[0,0,0]
	s_setprio 0
	s_setprio 1
	v_mfma_scale_f32_16x16x128_f8f6f4 v[14:17], v[200:207], v[242:249], 0, v188, v188 op_sel_hi:[0,0,0]
	v_mfma_scale_f32_16x16x128_f8f6f4 v[10:13], v[208:215], v[242:249], 0, v188, v188 op_sel_hi:[0,0,0]
	v_mfma_scale_f32_16x16x128_f8f6f4 v[18:21], v[208:215], v[232:239], 0, v188, v188 op_sel_hi:[0,0,0]
	v_mfma_scale_f32_16x16x128_f8f6f4 v[22:25], v[200:207], v[232:239], 0, v188, v188 op_sel_hi:[0,0,0]
	v_mfma_scale_f32_16x16x128_f8f6f4 v[30:33], v[200:207], v[224:231], 0, v188, v188 op_sel_hi:[0,0,0]
	v_mfma_scale_f32_16x16x128_f8f6f4 v[26:29], v[208:215], v[224:231], 0, v188, v188 op_sel_hi:[0,0,0]
	v_mfma_scale_f32_16x16x128_f8f6f4 v[34:37], v[208:215], v[216:223], 0, v188, v188 op_sel_hi:[0,0,0]
	v_mfma_scale_f32_16x16x128_f8f6f4 v[38:41], v[200:207], v[216:223], 0, v188, v188 op_sel_hi:[0,0,0]
	s_setprio 0
	s_barrier
	ds_read_b128 v[2:5], v189 offset:32768
	ds_read_b128 v[6:9], v189 offset:33792
	ds_read_b128 v[192:195], v189 offset:34816
	ds_read_b128 v[196:199], v189 offset:35840
	ds_read_b128 v[200:203], v189 offset:49152
	ds_read_b128 v[204:207], v189 offset:50176
	ds_read_b128 v[208:211], v189 offset:51200
	ds_read_b128 v[212:215], v189 offset:52224
	s_add_u32 s50, s50, 0x80000
	s_addc_u32 s51, s51, 0
	s_mov_b32 m0, s52
	v_lshl_add_u64 v[186:187], s[50:51], 0, v[154:155]
	ds_read_b128 v[216:219], v190 offset:32768
	ds_read_b128 v[220:223], v190 offset:33792
	ds_read_b128 v[224:227], v190 offset:34816
	ds_read_b128 v[228:231], v190 offset:35840
	ds_read_b128 v[232:235], v190 offset:36864
	ds_read_b128 v[236:239], v190 offset:37888
	ds_read_b128 v[242:245], v190 offset:38912
	ds_read_b128 v[246:249], v190 offset:39936
	global_load_lds_dwordx4 v[186:187], off
	v_lshl_add_u64 v[186:187], s[50:51], 0, v[158:159]
	s_mov_b32 m0, s53
	s_nop 0
	global_load_lds_dwordx4 v[186:187], off
	s_waitcnt vmcnt(8)
	s_waitcnt lgkmcnt(0)
	s_barrier
	s_setprio 1
	s_waitcnt lgkmcnt(0)
	v_mfma_scale_f32_16x16x128_f8f6f4 v[134:137], v[2:9], v[216:223], v[134:137], v188, v188 op_sel_hi:[0,0,0]
	v_mfma_scale_f32_16x16x128_f8f6f4 v[130:133], v[192:199], v[216:223], v[130:133], v188, v188 op_sel_hi:[0,0,0]
	v_mfma_scale_f32_16x16x128_f8f6f4 v[122:125], v[192:199], v[224:231], v[122:125], v188, v188 op_sel_hi:[0,0,0]
	v_mfma_scale_f32_16x16x128_f8f6f4 v[126:129], v[2:9], v[224:231], v[126:129], v188, v188 op_sel_hi:[0,0,0]
	v_mfma_scale_f32_16x16x128_f8f6f4 v[118:121], v[2:9], v[232:239], v[118:121], v188, v188 op_sel_hi:[0,0,0]
	v_mfma_scale_f32_16x16x128_f8f6f4 v[114:117], v[192:199], v[232:239], v[114:117], v188, v188 op_sel_hi:[0,0,0]
	v_mfma_scale_f32_16x16x128_f8f6f4 v[106:109], v[192:199], v[242:249], v[106:109], v188, v188 op_sel_hi:[0,0,0]
	v_mfma_scale_f32_16x16x128_f8f6f4 v[110:113], v[2:9], v[242:249], v[110:113], v188, v188 op_sel_hi:[0,0,0]
	s_setprio 0
	s_setprio 1
	v_mfma_scale_f32_16x16x128_f8f6f4 v[78:81], v[200:207], v[242:249], v[78:81], v188, v188 op_sel_hi:[0,0,0]
	v_mfma_scale_f32_16x16x128_f8f6f4 v[74:77], v[208:215], v[242:249], v[74:77], v188, v188 op_sel_hi:[0,0,0]
	v_mfma_scale_f32_16x16x128_f8f6f4 v[82:85], v[208:215], v[232:239], v[82:85], v188, v188 op_sel_hi:[0,0,0]
	v_mfma_scale_f32_16x16x128_f8f6f4 v[86:89], v[200:207], v[232:239], v[86:89], v188, v188 op_sel_hi:[0,0,0]
	v_mfma_scale_f32_16x16x128_f8f6f4 v[94:97], v[200:207], v[224:231], v[94:97], v188, v188 op_sel_hi:[0,0,0]
	v_mfma_scale_f32_16x16x128_f8f6f4 v[90:93], v[208:215], v[224:231], v[90:93], v188, v188 op_sel_hi:[0,0,0]
	v_mfma_scale_f32_16x16x128_f8f6f4 v[98:101], v[208:215], v[216:223], v[98:101], v188, v188 op_sel_hi:[0,0,0]
	v_mfma_scale_f32_16x16x128_f8f6f4 v[102:105], v[200:207], v[216:223], v[102:105], v188, v188 op_sel_hi:[0,0,0]
	s_setprio 0
	s_barrier
	s_mov_b32 m0, s70
	v_lshl_add_u64 v[174:175], v[174:175], 0, s[18:19]
	s_add_u32 s48, s48, 0x80080
	ds_read_b128 v[216:219], v190 offset:49152
	ds_read_b128 v[220:223], v190 offset:50176
	ds_read_b128 v[224:227], v190 offset:51200
	ds_read_b128 v[228:231], v190 offset:52224
	ds_read_b128 v[232:235], v190 offset:53248
	ds_read_b128 v[236:239], v190 offset:54272
	ds_read_b128 v[242:245], v190 offset:55296
	ds_read_b128 v[246:249], v190 offset:56320
	global_load_lds_dwordx4 v[174:175], off
	v_lshl_add_u64 v[174:175], v[176:177], 0, s[18:19]
	s_mov_b32 m0, s71
	s_addc_u32 s49, s49, 0
	global_load_lds_dwordx4 v[174:175], off
	v_lshl_add_u64 v[174:175], s[48:49], 0, v[156:157]
	s_mov_b32 m0, s74
	s_nop 0
	global_load_lds_dwordx4 v[174:175], off
	v_lshl_add_u64 v[174:175], s[48:49], 0, v[160:161]
	s_mov_b32 m0, s75
	s_nop 0
	global_load_lds_dwordx4 v[174:175], off
	v_lshl_add_u64 v[174:175], v[182:183], 0, s[18:19]
	s_mov_b32 m0, s72
	s_nop 0
	global_load_lds_dwordx4 v[174:175], off
	v_lshl_add_u64 v[174:175], v[184:185], 0, s[18:19]
	s_mov_b32 m0, s73
	s_nop 0
	global_load_lds_dwordx4 v[174:175], off
	s_waitcnt vmcnt(8)
	s_waitcnt lgkmcnt(0)
	s_barrier
	s_setprio 1
	s_waitcnt lgkmcnt(0)
	v_mfma_scale_f32_16x16x128_f8f6f4 v[70:73], v[2:9], v[216:223], v[70:73], v188, v188 op_sel_hi:[0,0,0]
	v_mfma_scale_f32_16x16x128_f8f6f4 v[66:69], v[192:199], v[216:223], v[66:69], v188, v188 op_sel_hi:[0,0,0]
	v_mfma_scale_f32_16x16x128_f8f6f4 v[58:61], v[192:199], v[224:231], v[58:61], v188, v188 op_sel_hi:[0,0,0]
	v_mfma_scale_f32_16x16x128_f8f6f4 v[62:65], v[2:9], v[224:231], v[62:65], v188, v188 op_sel_hi:[0,0,0]
	v_mfma_scale_f32_16x16x128_f8f6f4 v[54:57], v[2:9], v[232:239], v[54:57], v188, v188 op_sel_hi:[0,0,0]
	v_mfma_scale_f32_16x16x128_f8f6f4 v[50:53], v[192:199], v[232:239], v[50:53], v188, v188 op_sel_hi:[0,0,0]
	v_mfma_scale_f32_16x16x128_f8f6f4 v[42:45], v[192:199], v[242:249], v[42:45], v188, v188 op_sel_hi:[0,0,0]
	v_mfma_scale_f32_16x16x128_f8f6f4 v[46:49], v[2:9], v[242:249], v[46:49], v188, v188 op_sel_hi:[0,0,0]
	s_setprio 0
	s_setprio 1
	v_mfma_scale_f32_16x16x128_f8f6f4 v[14:17], v[200:207], v[242:249], v[14:17], v188, v188 op_sel_hi:[0,0,0]
	v_mfma_scale_f32_16x16x128_f8f6f4 v[10:13], v[208:215], v[242:249], v[10:13], v188, v188 op_sel_hi:[0,0,0]
	v_mfma_scale_f32_16x16x128_f8f6f4 v[18:21], v[208:215], v[232:239], v[18:21], v188, v188 op_sel_hi:[0,0,0]
	v_mfma_scale_f32_16x16x128_f8f6f4 v[22:25], v[200:207], v[232:239], v[22:25], v188, v188 op_sel_hi:[0,0,0]
	v_mfma_scale_f32_16x16x128_f8f6f4 v[30:33], v[200:207], v[224:231], v[30:33], v188, v188 op_sel_hi:[0,0,0]
	v_mfma_scale_f32_16x16x128_f8f6f4 v[26:29], v[208:215], v[224:231], v[26:29], v188, v188 op_sel_hi:[0,0,0]
	v_mfma_scale_f32_16x16x128_f8f6f4 v[34:37], v[208:215], v[216:223], v[34:37], v188, v188 op_sel_hi:[0,0,0]
	v_mfma_scale_f32_16x16x128_f8f6f4 v[38:41], v[200:207], v[216:223], v[38:41], v188, v188 op_sel_hi:[0,0,0]
	s_setprio 0
	s_barrier
	s_cmp_lt_u32 s86, 3
	s_cbranch_scc1 .LBB0_796
	s_add_u32 s48, s55, s62
	s_addc_u32 s49, s61, s41
	s_add_u32 s46, s46, 0x80180
	s_addc_u32 s47, s47, 0
	s_add_u32 s41, s44, 0x200
	v_lshl_add_u64 v[174:175], v[172:173], 2, s[48:49]
	s_addc_u32 s50, s45, 0
	s_mov_b32 s51, 4
	s_cmp_eq_u32 s86, s51
	s_cselect_b64 s[44:45], -1, 0
	s_cmp_lg_u32 s86, s51
	s_cbranch_scc1 .LBB0_794

.LBB0_794:
	ds_read_b128 v[2:5], v189
	ds_read_b128 v[6:9], v189 offset:1024
	ds_read_b128 v[192:195], v189 offset:2048
	ds_read_b128 v[196:199], v189 offset:3072
	ds_read_b128 v[200:203], v189 offset:16384
	ds_read_b128 v[204:207], v189 offset:17408
	ds_read_b128 v[208:211], v189 offset:18432
	ds_read_b128 v[212:215], v189 offset:19456
	s_add_u32 s48, s46, 0xfff80080
	s_addc_u32 s49, s47, -1
	s_and_b64 s[44:45], s[44:45], exec
	s_cselect_b32 s44, s4, s41
	s_cselect_b32 s49, s1, s49
	s_cselect_b32 s48, s0, s48
	s_cselect_b32 s45, s5, s50
	s_mov_b32 m0, s37
	v_lshl_add_u64 v[176:177], s[46:47], 0, v[162:163]
	ds_read_b128 v[216:219], v190
	ds_read_b128 v[220:223], v190 offset:1024
	ds_read_b128 v[224:227], v190 offset:2048
	ds_read_b128 v[228:231], v190 offset:3072
	ds_read_b128 v[232:235], v190 offset:4096
	ds_read_b128 v[236:239], v190 offset:5120
	ds_read_b128 v[242:245], v190 offset:6144
	ds_read_b128 v[246:249], v190 offset:7168
	global_load_lds_dwordx4 v[176:177], off
	v_lshl_add_u64 v[176:177], s[46:47], 0, v[164:165]
	s_mov_b32 m0, s39
	s_nop 0
	global_load_lds_dwordx4 v[176:177], off
	s_waitcnt vmcnt(8)
	s_waitcnt lgkmcnt(0)
	s_barrier
	s_setprio 1
	s_waitcnt lgkmcnt(0)
	v_mfma_scale_f32_16x16x128_f8f6f4 v[134:137], v[2:9], v[216:223], v[134:137], v188, v188 op_sel_hi:[0,0,0]
	v_mfma_scale_f32_16x16x128_f8f6f4 v[130:133], v[192:199], v[216:223], v[130:133], v188, v188 op_sel_hi:[0,0,0]
	v_mfma_scale_f32_16x16x128_f8f6f4 v[122:125], v[192:199], v[224:231], v[122:125], v188, v188 op_sel_hi:[0,0,0]
	v_mfma_scale_f32_16x16x128_f8f6f4 v[126:129], v[2:9], v[224:231], v[126:129], v188, v188 op_sel_hi:[0,0,0]
	v_mfma_scale_f32_16x16x128_f8f6f4 v[118:121], v[2:9], v[232:239], v[118:121], v188, v188 op_sel_hi:[0,0,0]
	v_mfma_scale_f32_16x16x128_f8f6f4 v[114:117], v[192:199], v[232:239], v[114:117], v188, v188 op_sel_hi:[0,0,0]
	v_mfma_scale_f32_16x16x128_f8f6f4 v[106:109], v[192:199], v[242:249], v[106:109], v188, v188 op_sel_hi:[0,0,0]
	v_mfma_scale_f32_16x16x128_f8f6f4 v[110:113], v[2:9], v[242:249], v[110:113], v188, v188 op_sel_hi:[0,0,0]
	s_setprio 0
	s_setprio 1
	v_mfma_scale_f32_16x16x128_f8f6f4 v[78:81], v[200:207], v[242:249], v[78:81], v188, v188 op_sel_hi:[0,0,0]
	v_mfma_scale_f32_16x16x128_f8f6f4 v[74:77], v[208:215], v[242:249], v[74:77], v188, v188 op_sel_hi:[0,0,0]
	v_mfma_scale_f32_16x16x128_f8f6f4 v[82:85], v[208:215], v[232:239], v[82:85], v188, v188 op_sel_hi:[0,0,0]
	v_mfma_scale_f32_16x16x128_f8f6f4 v[86:89], v[200:207], v[232:239], v[86:89], v188, v188 op_sel_hi:[0,0,0]
	v_mfma_scale_f32_16x16x128_f8f6f4 v[94:97], v[200:207], v[224:231], v[94:97], v188, v188 op_sel_hi:[0,0,0]
	v_mfma_scale_f32_16x16x128_f8f6f4 v[90:93], v[208:215], v[224:231], v[90:93], v188, v188 op_sel_hi:[0,0,0]
	v_mfma_scale_f32_16x16x128_f8f6f4 v[98:101], v[208:215], v[216:223], v[98:101], v188, v188 op_sel_hi:[0,0,0]
	v_mfma_scale_f32_16x16x128_f8f6f4 v[102:105], v[200:207], v[216:223], v[102:105], v188, v188 op_sel_hi:[0,0,0]
	s_setprio 0
	s_barrier
	s_mov_b32 m0, s9
	v_lshl_add_u64 v[176:177], s[44:45], 0, v[156:157]
	s_add_u32 s62, s44, 0x80000
	ds_read_b128 v[216:219], v190 offset:16384
	ds_read_b128 v[220:223], v190 offset:17408
	ds_read_b128 v[224:227], v190 offset:18432
	ds_read_b128 v[228:231], v190 offset:19456
	ds_read_b128 v[232:235], v190 offset:20480
	ds_read_b128 v[236:239], v190 offset:21504
	ds_read_b128 v[242:245], v190 offset:22528
	ds_read_b128 v[246:249], v190 offset:23552
	global_load_lds_dwordx4 v[176:177], off
	v_lshl_add_u64 v[182:183], s[44:45], 0, v[160:161]
	s_mov_b32 m0, s27
	s_addc_u32 s63, s45, 0
	global_load_lds_dwordx4 v[182:183], off
	v_lshl_add_u64 v[184:185], s[62:63], 0, v[156:157]
	s_mov_b32 m0, s33
	v_lshl_add_u64 v[186:187], s[48:49], 0, v[158:159]
	global_load_lds_dwordx4 v[184:185], off
	v_lshl_add_u64 v[184:185], s[62:63], 0, v[160:161]
	s_mov_b32 m0, s35
	s_nop 0
	global_load_lds_dwordx4 v[184:185], off
	v_lshl_add_u64 v[184:185], s[48:49], 0, v[154:155]
	s_mov_b32 m0, s8
	s_nop 0
	global_load_lds_dwordx4 v[184:185], off
	s_mov_b32 m0, s43
	s_nop 0
	global_load_lds_dwordx4 v[186:187], off
	s_waitcnt vmcnt(8)
	s_waitcnt lgkmcnt(0)
	s_barrier
	s_setprio 1
	s_waitcnt lgkmcnt(0)
	v_mfma_scale_f32_16x16x128_f8f6f4 v[70:73], v[2:9], v[216:223], v[70:73], v188, v188 op_sel_hi:[0,0,0]
	v_mfma_scale_f32_16x16x128_f8f6f4 v[66:69], v[192:199], v[216:223], v[66:69], v188, v188 op_sel_hi:[0,0,0]
	v_mfma_scale_f32_16x16x128_f8f6f4 v[58:61], v[192:199], v[224:231], v[58:61], v188, v188 op_sel_hi:[0,0,0]
	v_mfma_scale_f32_16x16x128_f8f6f4 v[62:65], v[2:9], v[224:231], v[62:65], v188, v188 op_sel_hi:[0,0,0]
	v_mfma_scale_f32_16x16x128_f8f6f4 v[54:57], v[2:9], v[232:239], v[54:57], v188, v188 op_sel_hi:[0,0,0]
	v_mfma_scale_f32_16x16x128_f8f6f4 v[50:53], v[192:199], v[232:239], v[50:53], v188, v188 op_sel_hi:[0,0,0]
	v_mfma_scale_f32_16x16x128_f8f6f4 v[42:45], v[192:199], v[242:249], v[42:45], v188, v188 op_sel_hi:[0,0,0]
	v_mfma_scale_f32_16x16x128_f8f6f4 v[46:49], v[2:9], v[242:249], v[46:49], v188, v188 op_sel_hi:[0,0,0]
	s_setprio 0
	s_setprio 1
	v_mfma_scale_f32_16x16x128_f8f6f4 v[14:17], v[200:207], v[242:249], v[14:17], v188, v188 op_sel_hi:[0,0,0]
	v_mfma_scale_f32_16x16x128_f8f6f4 v[10:13], v[208:215], v[242:249], v[10:13], v188, v188 op_sel_hi:[0,0,0]
	v_mfma_scale_f32_16x16x128_f8f6f4 v[18:21], v[208:215], v[232:239], v[18:21], v188, v188 op_sel_hi:[0,0,0]
	v_mfma_scale_f32_16x16x128_f8f6f4 v[22:25], v[200:207], v[232:239], v[22:25], v188, v188 op_sel_hi:[0,0,0]
	v_mfma_scale_f32_16x16x128_f8f6f4 v[30:33], v[200:207], v[224:231], v[30:33], v188, v188 op_sel_hi:[0,0,0]
	v_mfma_scale_f32_16x16x128_f8f6f4 v[26:29], v[208:215], v[224:231], v[26:29], v188, v188 op_sel_hi:[0,0,0]
	v_mfma_scale_f32_16x16x128_f8f6f4 v[34:37], v[208:215], v[216:223], v[34:37], v188, v188 op_sel_hi:[0,0,0]
	v_mfma_scale_f32_16x16x128_f8f6f4 v[38:41], v[200:207], v[216:223], v[38:41], v188, v188 op_sel_hi:[0,0,0]
	s_setprio 0
	s_barrier
	ds_read_b128 v[192:195], v189 offset:32768
	ds_read_b128 v[196:199], v189 offset:33792
	ds_read_b128 v[200:203], v189 offset:34816
	ds_read_b128 v[204:207], v189 offset:35840
	ds_read_b128 v[2:5], v189 offset:49152
	ds_read_b128 v[6:9], v189 offset:50176
	ds_read_b128 v[208:211], v189 offset:51200
	ds_read_b128 v[212:215], v189 offset:52224
	s_add_u32 s48, s48, 0x80000
	s_addc_u32 s49, s49, 0
	s_mov_b32 m0, s52
	v_lshl_add_u64 v[252:253], s[48:49], 0, v[154:155]
	ds_read_b128 v[216:219], v190 offset:32768
	ds_read_b128 v[220:223], v190 offset:33792
	ds_read_b128 v[224:227], v190 offset:34816
	ds_read_b128 v[228:231], v190 offset:35840
	ds_read_b128 v[232:235], v190 offset:36864
	ds_read_b128 v[236:239], v190 offset:37888
	ds_read_b128 v[242:245], v190 offset:38912
	ds_read_b128 v[246:249], v190 offset:39936
	global_load_lds_dwordx4 v[252:253], off
	v_lshl_add_u64 v[252:253], s[48:49], 0, v[158:159]
	s_mov_b32 m0, s53
	s_nop 0
	global_load_lds_dwordx4 v[252:253], off
	s_waitcnt vmcnt(8)
	s_waitcnt lgkmcnt(0)
	s_barrier
	s_setprio 1
	s_waitcnt lgkmcnt(0)
	v_mfma_scale_f32_16x16x128_f8f6f4 v[134:137], v[192:199], v[216:223], v[134:137], v188, v188 op_sel_hi:[0,0,0]
	v_mfma_scale_f32_16x16x128_f8f6f4 v[130:133], v[200:207], v[216:223], v[130:133], v188, v188 op_sel_hi:[0,0,0]
	v_mfma_scale_f32_16x16x128_f8f6f4 v[122:125], v[200:207], v[224:231], v[122:125], v188, v188 op_sel_hi:[0,0,0]
	v_mfma_scale_f32_16x16x128_f8f6f4 v[126:129], v[192:199], v[224:231], v[126:129], v188, v188 op_sel_hi:[0,0,0]
	v_mfma_scale_f32_16x16x128_f8f6f4 v[118:121], v[192:199], v[232:239], v[118:121], v188, v188 op_sel_hi:[0,0,0]
	v_mfma_scale_f32_16x16x128_f8f6f4 v[114:117], v[200:207], v[232:239], v[114:117], v188, v188 op_sel_hi:[0,0,0]
	v_mfma_scale_f32_16x16x128_f8f6f4 v[106:109], v[200:207], v[242:249], v[106:109], v188, v188 op_sel_hi:[0,0,0]
	v_mfma_scale_f32_16x16x128_f8f6f4 v[110:113], v[192:199], v[242:249], v[110:113], v188, v188 op_sel_hi:[0,0,0]
	s_setprio 0
	s_setprio 1
	v_mfma_scale_f32_16x16x128_f8f6f4 v[78:81], v[2:9], v[242:249], v[78:81], v188, v188 op_sel_hi:[0,0,0]
	v_mfma_scale_f32_16x16x128_f8f6f4 v[74:77], v[208:215], v[242:249], v[74:77], v188, v188 op_sel_hi:[0,0,0]
	v_mfma_scale_f32_16x16x128_f8f6f4 v[82:85], v[208:215], v[232:239], v[82:85], v188, v188 op_sel_hi:[0,0,0]
	v_mfma_scale_f32_16x16x128_f8f6f4 v[86:89], v[2:9], v[232:239], v[86:89], v188, v188 op_sel_hi:[0,0,0]
	v_mfma_scale_f32_16x16x128_f8f6f4 v[94:97], v[2:9], v[224:231], v[94:97], v188, v188 op_sel_hi:[0,0,0]
	v_mfma_scale_f32_16x16x128_f8f6f4 v[90:93], v[208:215], v[224:231], v[90:93], v188, v188 op_sel_hi:[0,0,0]
	v_mfma_scale_f32_16x16x128_f8f6f4 v[98:101], v[208:215], v[216:223], v[98:101], v188, v188 op_sel_hi:[0,0,0]
	v_mfma_scale_f32_16x16x128_f8f6f4 v[102:105], v[2:9], v[216:223], v[102:105], v188, v188 op_sel_hi:[0,0,0]
	s_setprio 0
	s_barrier
	s_mov_b32 m0, s70
	v_lshl_add_u64 v[176:177], v[176:177], 0, s[18:19]
	s_add_u32 s44, s44, 0x80080
	ds_read_b128 v[216:219], v190 offset:49152
	ds_read_b128 v[220:223], v190 offset:50176
	ds_read_b128 v[224:227], v190 offset:51200
	ds_read_b128 v[228:231], v190 offset:52224
	ds_read_b128 v[232:235], v190 offset:53248
	ds_read_b128 v[236:239], v190 offset:54272
	ds_read_b128 v[242:245], v190 offset:55296
	ds_read_b128 v[246:249], v190 offset:56320
	global_load_lds_dwordx4 v[176:177], off
	v_lshl_add_u64 v[176:177], v[182:183], 0, s[18:19]
	s_mov_b32 m0, s71
	s_addc_u32 s45, s45, 0
	global_load_lds_dwordx4 v[176:177], off
	v_lshl_add_u64 v[176:177], s[44:45], 0, v[156:157]
	s_mov_b32 m0, s74
	s_nop 0
	global_load_lds_dwordx4 v[176:177], off
	v_lshl_add_u64 v[176:177], s[44:45], 0, v[160:161]
	s_mov_b32 m0, s75
	s_nop 0
	global_load_lds_dwordx4 v[176:177], off
	v_lshl_add_u64 v[176:177], v[184:185], 0, s[18:19]
	s_mov_b32 m0, s72
	s_nop 0
	global_load_lds_dwordx4 v[176:177], off
	v_lshl_add_u64 v[176:177], v[186:187], 0, s[18:19]
	s_mov_b32 m0, s73
	s_nop 0
	global_load_lds_dwordx4 v[176:177], off
	s_waitcnt vmcnt(8)
	s_waitcnt lgkmcnt(0)
	s_barrier
	s_setprio 1
	s_waitcnt lgkmcnt(0)
	v_mfma_scale_f32_16x16x128_f8f6f4 v[70:73], v[192:199], v[216:223], v[70:73], v188, v188 op_sel_hi:[0,0,0]
	v_mfma_scale_f32_16x16x128_f8f6f4 v[66:69], v[200:207], v[216:223], v[66:69], v188, v188 op_sel_hi:[0,0,0]
	v_mfma_scale_f32_16x16x128_f8f6f4 v[58:61], v[200:207], v[224:231], v[58:61], v188, v188 op_sel_hi:[0,0,0]
	v_mfma_scale_f32_16x16x128_f8f6f4 v[62:65], v[192:199], v[224:231], v[62:65], v188, v188 op_sel_hi:[0,0,0]
	v_mfma_scale_f32_16x16x128_f8f6f4 v[54:57], v[192:199], v[232:239], v[54:57], v188, v188 op_sel_hi:[0,0,0]
	v_mfma_scale_f32_16x16x128_f8f6f4 v[50:53], v[200:207], v[232:239], v[50:53], v188, v188 op_sel_hi:[0,0,0]
	v_mfma_scale_f32_16x16x128_f8f6f4 v[42:45], v[200:207], v[242:249], v[42:45], v188, v188 op_sel_hi:[0,0,0]
	v_mfma_scale_f32_16x16x128_f8f6f4 v[46:49], v[192:199], v[242:249], v[46:49], v188, v188 op_sel_hi:[0,0,0]
	s_setprio 0
	s_setprio 1
	v_mfma_scale_f32_16x16x128_f8f6f4 v[14:17], v[2:9], v[242:249], v[14:17], v188, v188 op_sel_hi:[0,0,0]
	v_mfma_scale_f32_16x16x128_f8f6f4 v[10:13], v[208:215], v[242:249], v[10:13], v188, v188 op_sel_hi:[0,0,0]
	v_mfma_scale_f32_16x16x128_f8f6f4 v[18:21], v[208:215], v[232:239], v[18:21], v188, v188 op_sel_hi:[0,0,0]
	v_mfma_scale_f32_16x16x128_f8f6f4 v[22:25], v[2:9], v[232:239], v[22:25], v188, v188 op_sel_hi:[0,0,0]
	v_mfma_scale_f32_16x16x128_f8f6f4 v[30:33], v[2:9], v[224:231], v[30:33], v188, v188 op_sel_hi:[0,0,0]
	v_mfma_scale_f32_16x16x128_f8f6f4 v[26:29], v[208:215], v[224:231], v[26:29], v188, v188 op_sel_hi:[0,0,0]
	v_mfma_scale_f32_16x16x128_f8f6f4 v[34:37], v[208:215], v[216:223], v[34:37], v188, v188 op_sel_hi:[0,0,0]
	v_mfma_scale_f32_16x16x128_f8f6f4 v[38:41], v[2:9], v[216:223], v[38:41], v188, v188 op_sel_hi:[0,0,0]
	s_setprio 0
	s_barrier
	s_add_i32 s44, s51, 2
	s_add_u32 s46, s46, 0x100
	s_addc_u32 s47, s47, 0
	s_add_u32 s41, s41, 0x100
	s_addc_u32 s50, s50, 0
	s_cmp_ge_i32 s51, s86
	s_cbranch_scc1 .LBB0_796
	s_mov_b32 s51, s44
	s_cmp_eq_u32 s86, s51
	s_cselect_b64 s[44:45], -1, 0
	s_cmp_lg_u32 s86, s51
	s_cbranch_scc0 .LBB0_793
	s_branch .LBB0_794

.LBB0_946:
	s_ashr_i32 s37, s36, 31
	ds_read_b128 v[18:21], v192
	ds_read_b128 v[22:25], v192 offset:1024
	ds_read_b128 v[26:29], v192 offset:2048
	ds_read_b128 v[30:33], v192 offset:3072
	ds_read_b128 v[2:5], v192 offset:16384
	ds_read_b128 v[6:9], v192 offset:17408
	ds_read_b128 v[10:13], v192 offset:18432
	ds_read_b128 v[14:17], v192 offset:19456
	s_lshl_b64 s[38:39], s[36:37], 20
	s_add_u32 s38, s22, s38
	s_addc_u32 s39, s23, s39
	s_and_b64 s[40:41], s[2:3], exec
	s_cselect_b32 s37, s39, s47
	s_cselect_b32 s84, s38, s46
	s_ashr_i32 s27, s26, 31
	s_lshl_b64 s[40:41], s[26:27], 20
	s_add_u32 s40, s25, s40
	s_addc_u32 s41, s35, s41
	s_and_b64 s[48:49], s[2:3], exec
	s_cselect_b32 s27, s41, s45
	s_cselect_b32 s85, s40, s44
	s_add_u32 s48, s46, 0x80080
	s_addc_u32 s49, s47, 0
	s_mov_b32 m0, s80
	v_lshl_add_u64 v[218:219], s[48:49], 0, v[164:165]
	ds_read_b128 v[184:187], v193
	ds_read_b128 v[188:191], v193 offset:1024
	ds_read_b128 v[194:197], v193 offset:2048
	ds_read_b128 v[198:201], v193 offset:3072
	ds_read_b128 v[202:205], v193 offset:4096
	ds_read_b128 v[206:209], v193 offset:5120
	ds_read_b128 v[210:213], v193 offset:6144
	ds_read_b128 v[214:217], v193 offset:7168
	global_load_lds_dwordx4 v[218:219], off
	v_lshl_add_u64 v[218:219], s[48:49], 0, v[168:169]
	s_mov_b32 m0, s81
	s_nop 0
	global_load_lds_dwordx4 v[218:219], off
	s_waitcnt vmcnt(8)
	s_waitcnt lgkmcnt(0)
	s_barrier
	s_setprio 1
	s_waitcnt lgkmcnt(0)
	v_mfma_scale_f32_16x16x128_f8f6f4 v[158:161], v[18:25], v[184:191], 0, v181, v181 op_sel_hi:[0,0,0]
	v_mfma_scale_f32_16x16x128_f8f6f4 v[154:157], v[26:33], v[184:191], 0, v181, v181 op_sel_hi:[0,0,0]
	v_mfma_scale_f32_16x16x128_f8f6f4 v[146:149], v[26:33], v[194:201], 0, v181, v181 op_sel_hi:[0,0,0]
	v_mfma_scale_f32_16x16x128_f8f6f4 v[150:153], v[18:25], v[194:201], 0, v181, v181 op_sel_hi:[0,0,0]
	v_mfma_scale_f32_16x16x128_f8f6f4 v[142:145], v[18:25], v[202:209], 0, v181, v181 op_sel_hi:[0,0,0]
	v_mfma_scale_f32_16x16x128_f8f6f4 v[138:141], v[26:33], v[202:209], 0, v181, v181 op_sel_hi:[0,0,0]
	v_mfma_scale_f32_16x16x128_f8f6f4 v[130:133], v[26:33], v[210:217], 0, v181, v181 op_sel_hi:[0,0,0]
	v_mfma_scale_f32_16x16x128_f8f6f4 v[134:137], v[18:25], v[210:217], 0, v181, v181 op_sel_hi:[0,0,0]
	s_setprio 0
	s_setprio 1
	v_mfma_scale_f32_16x16x128_f8f6f4 v[102:105], v[2:9], v[210:217], 0, v181, v181 op_sel_hi:[0,0,0]
	v_mfma_scale_f32_16x16x128_f8f6f4 v[98:101], v[10:17], v[210:217], 0, v181, v181 op_sel_hi:[0,0,0]
	v_mfma_scale_f32_16x16x128_f8f6f4 v[106:109], v[10:17], v[202:209], 0, v181, v181 op_sel_hi:[0,0,0]
	v_mfma_scale_f32_16x16x128_f8f6f4 v[110:113], v[2:9], v[202:209], 0, v181, v181 op_sel_hi:[0,0,0]
	v_mfma_scale_f32_16x16x128_f8f6f4 v[118:121], v[2:9], v[194:201], 0, v181, v181 op_sel_hi:[0,0,0]
	v_mfma_scale_f32_16x16x128_f8f6f4 v[114:117], v[10:17], v[194:201], 0, v181, v181 op_sel_hi:[0,0,0]
	v_mfma_scale_f32_16x16x128_f8f6f4 v[122:125], v[10:17], v[184:191], 0, v181, v181 op_sel_hi:[0,0,0]
	v_mfma_scale_f32_16x16x128_f8f6f4 v[126:129], v[2:9], v[184:191], 0, v181, v181 op_sel_hi:[0,0,0]
	s_setprio 0
	s_barrier
	v_lshl_add_u64 v[184:185], s[44:45], 0, v[166:167]
	s_mov_b32 m0, s52
	v_lshl_add_u64 v[186:187], v[184:185], 0, s[14:15]
	ds_read_b128 v[194:197], v193 offset:16384
	ds_read_b128 v[198:201], v193 offset:17408
	ds_read_b128 v[202:205], v193 offset:18432
	ds_read_b128 v[206:209], v193 offset:19456
	ds_read_b128 v[210:213], v193 offset:20480
	ds_read_b128 v[214:217], v193 offset:21504
	ds_read_b128 v[218:221], v193 offset:22528
	ds_read_b128 v[222:225], v193 offset:23552
	global_load_lds_dwordx4 v[186:187], off
	v_lshl_add_u64 v[186:187], s[44:45], 0, v[170:171]
	s_add_u32 s48, s44, 0x80100
	v_lshl_add_u64 v[188:189], v[186:187], 0, s[14:15]
	s_mov_b32 m0, s53
	s_addc_u32 s49, s45, 0
	global_load_lds_dwordx4 v[188:189], off
	v_lshl_add_u64 v[188:189], s[48:49], 0, v[166:167]
	s_mov_b32 m0, s54
	s_nop 0
	global_load_lds_dwordx4 v[188:189], off
	v_lshl_add_u64 v[188:189], s[48:49], 0, v[170:171]
	s_mov_b32 m0, s55
	s_nop 0
	global_load_lds_dwordx4 v[188:189], off
	v_lshl_add_u64 v[188:189], s[46:47], 0, v[164:165]
	v_lshl_add_u64 v[190:191], v[188:189], 0, s[14:15]
	s_mov_b32 m0, s43
	s_nop 0
	global_load_lds_dwordx4 v[190:191], off
	v_lshl_add_u64 v[190:191], s[46:47], 0, v[168:169]
	v_lshl_add_u64 v[226:227], v[190:191], 0, s[14:15]
	s_mov_b32 m0, s61
	s_nop 0
	global_load_lds_dwordx4 v[226:227], off
	s_waitcnt vmcnt(8)
	s_waitcnt lgkmcnt(0)
	s_barrier
	s_setprio 1
	s_waitcnt lgkmcnt(0)
	v_mfma_scale_f32_16x16x128_f8f6f4 v[94:97], v[18:25], v[194:201], 0, v181, v181 op_sel_hi:[0,0,0]
	v_mfma_scale_f32_16x16x128_f8f6f4 v[90:93], v[26:33], v[194:201], 0, v181, v181 op_sel_hi:[0,0,0]
	v_mfma_scale_f32_16x16x128_f8f6f4 v[82:85], v[26:33], v[202:209], 0, v181, v181 op_sel_hi:[0,0,0]
	v_mfma_scale_f32_16x16x128_f8f6f4 v[86:89], v[18:25], v[202:209], 0, v181, v181 op_sel_hi:[0,0,0]
	v_mfma_scale_f32_16x16x128_f8f6f4 v[78:81], v[18:25], v[210:217], 0, v181, v181 op_sel_hi:[0,0,0]
	v_mfma_scale_f32_16x16x128_f8f6f4 v[74:77], v[26:33], v[210:217], 0, v181, v181 op_sel_hi:[0,0,0]
	v_mfma_scale_f32_16x16x128_f8f6f4 v[66:69], v[26:33], v[218:225], 0, v181, v181 op_sel_hi:[0,0,0]
	v_mfma_scale_f32_16x16x128_f8f6f4 v[70:73], v[18:25], v[218:225], 0, v181, v181 op_sel_hi:[0,0,0]
	s_setprio 0
	s_setprio 1
	v_mfma_scale_f32_16x16x128_f8f6f4 v[38:41], v[2:9], v[218:225], 0, v181, v181 op_sel_hi:[0,0,0]
	v_mfma_scale_f32_16x16x128_f8f6f4 v[34:37], v[10:17], v[218:225], 0, v181, v181 op_sel_hi:[0,0,0]
	v_mfma_scale_f32_16x16x128_f8f6f4 v[42:45], v[10:17], v[210:217], 0, v181, v181 op_sel_hi:[0,0,0]
	v_mfma_scale_f32_16x16x128_f8f6f4 v[46:49], v[2:9], v[210:217], 0, v181, v181 op_sel_hi:[0,0,0]
	v_mfma_scale_f32_16x16x128_f8f6f4 v[54:57], v[2:9], v[202:209], 0, v181, v181 op_sel_hi:[0,0,0]
	v_mfma_scale_f32_16x16x128_f8f6f4 v[50:53], v[10:17], v[202:209], 0, v181, v181 op_sel_hi:[0,0,0]
	v_mfma_scale_f32_16x16x128_f8f6f4 v[58:61], v[10:17], v[194:201], 0, v181, v181 op_sel_hi:[0,0,0]
	v_mfma_scale_f32_16x16x128_f8f6f4 v[62:65], v[2:9], v[194:201], 0, v181, v181 op_sel_hi:[0,0,0]
	s_setprio 0
	s_barrier
	ds_read_b128 v[18:21], v192 offset:32768
	ds_read_b128 v[22:25], v192 offset:33792
	ds_read_b128 v[26:29], v192 offset:34816
	ds_read_b128 v[30:33], v192 offset:35840
	ds_read_b128 v[2:5], v192 offset:49152
	ds_read_b128 v[6:9], v192 offset:50176
	ds_read_b128 v[10:13], v192 offset:51200
	ds_read_b128 v[14:17], v192 offset:52224
	s_add_u32 s48, s46, 0x80100
	s_addc_u32 s49, s47, 0
	s_mov_b32 m0, s68
	v_lshl_add_u64 v[226:227], s[48:49], 0, v[164:165]
	ds_read_b128 v[194:197], v193 offset:32768
	ds_read_b128 v[198:201], v193 offset:33792
	ds_read_b128 v[202:205], v193 offset:34816
	ds_read_b128 v[206:209], v193 offset:35840
	ds_read_b128 v[210:213], v193 offset:36864
	ds_read_b128 v[214:217], v193 offset:37888
	ds_read_b128 v[218:221], v193 offset:38912
	ds_read_b128 v[222:225], v193 offset:39936
	global_load_lds_dwordx4 v[226:227], off
	v_lshl_add_u64 v[226:227], s[48:49], 0, v[168:169]
	s_mov_b32 m0, s69
	s_nop 0
	global_load_lds_dwordx4 v[226:227], off
	s_waitcnt vmcnt(8)
	s_waitcnt lgkmcnt(0)
	s_barrier
	s_setprio 1
	s_waitcnt lgkmcnt(0)
	v_mfma_scale_f32_16x16x128_f8f6f4 v[158:161], v[18:25], v[194:201], v[158:161], v181, v181 op_sel_hi:[0,0,0]
	v_mfma_scale_f32_16x16x128_f8f6f4 v[154:157], v[26:33], v[194:201], v[154:157], v181, v181 op_sel_hi:[0,0,0]
	v_mfma_scale_f32_16x16x128_f8f6f4 v[146:149], v[26:33], v[202:209], v[146:149], v181, v181 op_sel_hi:[0,0,0]
	v_mfma_scale_f32_16x16x128_f8f6f4 v[150:153], v[18:25], v[202:209], v[150:153], v181, v181 op_sel_hi:[0,0,0]
	v_mfma_scale_f32_16x16x128_f8f6f4 v[142:145], v[18:25], v[210:217], v[142:145], v181, v181 op_sel_hi:[0,0,0]
	v_mfma_scale_f32_16x16x128_f8f6f4 v[138:141], v[26:33], v[210:217], v[138:141], v181, v181 op_sel_hi:[0,0,0]
	v_mfma_scale_f32_16x16x128_f8f6f4 v[130:133], v[26:33], v[218:225], v[130:133], v181, v181 op_sel_hi:[0,0,0]
	v_mfma_scale_f32_16x16x128_f8f6f4 v[134:137], v[18:25], v[218:225], v[134:137], v181, v181 op_sel_hi:[0,0,0]
	s_setprio 0
	s_setprio 1
	v_mfma_scale_f32_16x16x128_f8f6f4 v[102:105], v[2:9], v[218:225], v[102:105], v181, v181 op_sel_hi:[0,0,0]
	v_mfma_scale_f32_16x16x128_f8f6f4 v[98:101], v[10:17], v[218:225], v[98:101], v181, v181 op_sel_hi:[0,0,0]
	v_mfma_scale_f32_16x16x128_f8f6f4 v[106:109], v[10:17], v[210:217], v[106:109], v181, v181 op_sel_hi:[0,0,0]
	v_mfma_scale_f32_16x16x128_f8f6f4 v[110:113], v[2:9], v[210:217], v[110:113], v181, v181 op_sel_hi:[0,0,0]
	v_mfma_scale_f32_16x16x128_f8f6f4 v[118:121], v[2:9], v[202:209], v[118:121], v181, v181 op_sel_hi:[0,0,0]
	v_mfma_scale_f32_16x16x128_f8f6f4 v[114:117], v[10:17], v[202:209], v[114:117], v181, v181 op_sel_hi:[0,0,0]
	v_mfma_scale_f32_16x16x128_f8f6f4 v[122:125], v[10:17], v[194:201], v[122:125], v181, v181 op_sel_hi:[0,0,0]
	v_mfma_scale_f32_16x16x128_f8f6f4 v[126:129], v[2:9], v[194:201], v[126:129], v181, v181 op_sel_hi:[0,0,0]
	s_setprio 0
	s_barrier
	s_mov_b32 m0, s74
	v_lshl_add_u64 v[184:185], v[184:185], 0, s[18:19]
	s_add_u32 s48, s44, 0x80180
	ds_read_b128 v[194:197], v193 offset:49152
	ds_read_b128 v[198:201], v193 offset:50176
	ds_read_b128 v[202:205], v193 offset:51200
	ds_read_b128 v[206:209], v193 offset:52224
	ds_read_b128 v[210:213], v193 offset:53248
	ds_read_b128 v[214:217], v193 offset:54272
	ds_read_b128 v[218:221], v193 offset:55296
	ds_read_b128 v[222:225], v193 offset:56320
	global_load_lds_dwordx4 v[184:185], off
	v_lshl_add_u64 v[184:185], v[186:187], 0, s[18:19]
	s_mov_b32 m0, s75
	s_addc_u32 s49, s45, 0
	global_load_lds_dwordx4 v[184:185], off
	v_lshl_add_u64 v[184:185], s[48:49], 0, v[166:167]
	s_mov_b32 m0, s78
	s_nop 0
	global_load_lds_dwordx4 v[184:185], off
	v_lshl_add_u64 v[184:185], s[48:49], 0, v[170:171]
	s_mov_b32 m0, s79
	s_nop 0
	global_load_lds_dwordx4 v[184:185], off
	v_lshl_add_u64 v[184:185], v[188:189], 0, s[18:19]
	s_mov_b32 m0, s76
	s_nop 0
	global_load_lds_dwordx4 v[184:185], off
	v_lshl_add_u64 v[184:185], v[190:191], 0, s[18:19]
	s_mov_b32 m0, s77
	s_nop 0
	global_load_lds_dwordx4 v[184:185], off
	s_waitcnt vmcnt(8)
	s_waitcnt lgkmcnt(0)
	s_barrier
	s_setprio 1
	s_waitcnt lgkmcnt(0)
	v_mfma_scale_f32_16x16x128_f8f6f4 v[94:97], v[18:25], v[194:201], v[94:97], v181, v181 op_sel_hi:[0,0,0]
	v_mfma_scale_f32_16x16x128_f8f6f4 v[90:93], v[26:33], v[194:201], v[90:93], v181, v181 op_sel_hi:[0,0,0]
	v_mfma_scale_f32_16x16x128_f8f6f4 v[82:85], v[26:33], v[202:209], v[82:85], v181, v181 op_sel_hi:[0,0,0]
	v_mfma_scale_f32_16x16x128_f8f6f4 v[86:89], v[18:25], v[202:209], v[86:89], v181, v181 op_sel_hi:[0,0,0]
	v_mfma_scale_f32_16x16x128_f8f6f4 v[78:81], v[18:25], v[210:217], v[78:81], v181, v181 op_sel_hi:[0,0,0]
	v_mfma_scale_f32_16x16x128_f8f6f4 v[74:77], v[26:33], v[210:217], v[74:77], v181, v181 op_sel_hi:[0,0,0]
	v_mfma_scale_f32_16x16x128_f8f6f4 v[66:69], v[26:33], v[218:225], v[66:69], v181, v181 op_sel_hi:[0,0,0]
	v_mfma_scale_f32_16x16x128_f8f6f4 v[70:73], v[18:25], v[218:225], v[70:73], v181, v181 op_sel_hi:[0,0,0]
	s_setprio 0
	s_setprio 1
	v_mfma_scale_f32_16x16x128_f8f6f4 v[38:41], v[2:9], v[218:225], v[38:41], v181, v181 op_sel_hi:[0,0,0]
	v_mfma_scale_f32_16x16x128_f8f6f4 v[34:37], v[10:17], v[218:225], v[34:37], v181, v181 op_sel_hi:[0,0,0]
	v_mfma_scale_f32_16x16x128_f8f6f4 v[42:45], v[10:17], v[210:217], v[42:45], v181, v181 op_sel_hi:[0,0,0]
	v_mfma_scale_f32_16x16x128_f8f6f4 v[46:49], v[2:9], v[210:217], v[46:49], v181, v181 op_sel_hi:[0,0,0]
	v_mfma_scale_f32_16x16x128_f8f6f4 v[54:57], v[2:9], v[202:209], v[54:57], v181, v181 op_sel_hi:[0,0,0]
	v_mfma_scale_f32_16x16x128_f8f6f4 v[50:53], v[10:17], v[202:209], v[50:53], v181, v181 op_sel_hi:[0,0,0]
	v_mfma_scale_f32_16x16x128_f8f6f4 v[58:61], v[10:17], v[194:201], v[58:61], v181, v181 op_sel_hi:[0,0,0]
	v_mfma_scale_f32_16x16x128_f8f6f4 v[62:65], v[2:9], v[194:201], v[62:65], v181, v181 op_sel_hi:[0,0,0]
	s_setprio 0
	s_barrier
	s_add_u32 s46, s46, 0x80180
	s_addc_u32 s47, s47, 0
	s_add_u32 s62, s44, 0x200
	s_addc_u32 s63, s45, 0
	s_mov_b32 s86, 0
.LBB0_947:
	ds_read_b128 v[2:5], v192
	ds_read_b128 v[6:9], v192 offset:1024
	ds_read_b128 v[18:21], v192 offset:2048
	ds_read_b128 v[22:25], v192 offset:3072
	ds_read_b128 v[26:29], v192 offset:16384
	ds_read_b128 v[30:33], v192 offset:17408
	ds_read_b128 v[184:187], v192 offset:18432
	ds_read_b128 v[188:191], v192 offset:19456
	s_add_u32 s44, s46, 0xfff80080
	s_addc_u32 s45, s47, -1
	s_cmp_eq_u32 s86, 28
	s_cselect_b32 s49, s37, s45
	s_cselect_b32 s48, s84, s44
	s_cselect_b32 s45, s27, s63
	s_cselect_b32 s44, s85, s62
	s_mov_b32 m0, s80
	v_lshl_add_u64 v[218:219], s[46:47], 0, v[172:173]
	ds_read_b128 v[10:13], v193
	ds_read_b128 v[14:17], v193 offset:1024
	ds_read_b128 v[194:197], v193 offset:2048
	ds_read_b128 v[198:201], v193 offset:3072
	ds_read_b128 v[202:205], v193 offset:4096
	ds_read_b128 v[206:209], v193 offset:5120
	ds_read_b128 v[210:213], v193 offset:6144
	ds_read_b128 v[214:217], v193 offset:7168
	global_load_lds_dwordx4 v[218:219], off
	v_lshl_add_u64 v[218:219], s[46:47], 0, v[174:175]
	s_mov_b32 m0, s81
	s_nop 0
	global_load_lds_dwordx4 v[218:219], off
	s_waitcnt vmcnt(8)
	s_waitcnt lgkmcnt(0)
	s_barrier
	s_setprio 1
	s_waitcnt lgkmcnt(0)
	v_mfma_scale_f32_16x16x128_f8f6f4 v[158:161], v[2:9], v[10:17], v[158:161], v181, v181 op_sel_hi:[0,0,0]
	v_mfma_scale_f32_16x16x128_f8f6f4 v[154:157], v[18:25], v[10:17], v[154:157], v181, v181 op_sel_hi:[0,0,0]
	v_mfma_scale_f32_16x16x128_f8f6f4 v[146:149], v[18:25], v[194:201], v[146:149], v181, v181 op_sel_hi:[0,0,0]
	v_mfma_scale_f32_16x16x128_f8f6f4 v[150:153], v[2:9], v[194:201], v[150:153], v181, v181 op_sel_hi:[0,0,0]
	v_mfma_scale_f32_16x16x128_f8f6f4 v[142:145], v[2:9], v[202:209], v[142:145], v181, v181 op_sel_hi:[0,0,0]
	v_mfma_scale_f32_16x16x128_f8f6f4 v[138:141], v[18:25], v[202:209], v[138:141], v181, v181 op_sel_hi:[0,0,0]
	v_mfma_scale_f32_16x16x128_f8f6f4 v[130:133], v[18:25], v[210:217], v[130:133], v181, v181 op_sel_hi:[0,0,0]
	v_mfma_scale_f32_16x16x128_f8f6f4 v[134:137], v[2:9], v[210:217], v[134:137], v181, v181 op_sel_hi:[0,0,0]
	s_setprio 0
	s_setprio 1
	v_mfma_scale_f32_16x16x128_f8f6f4 v[102:105], v[26:33], v[210:217], v[102:105], v181, v181 op_sel_hi:[0,0,0]
	v_mfma_scale_f32_16x16x128_f8f6f4 v[98:101], v[184:191], v[210:217], v[98:101], v181, v181 op_sel_hi:[0,0,0]
	v_mfma_scale_f32_16x16x128_f8f6f4 v[106:109], v[184:191], v[202:209], v[106:109], v181, v181 op_sel_hi:[0,0,0]
	v_mfma_scale_f32_16x16x128_f8f6f4 v[110:113], v[26:33], v[202:209], v[110:113], v181, v181 op_sel_hi:[0,0,0]
	v_mfma_scale_f32_16x16x128_f8f6f4 v[118:121], v[26:33], v[194:201], v[118:121], v181, v181 op_sel_hi:[0,0,0]
	v_mfma_scale_f32_16x16x128_f8f6f4 v[114:117], v[184:191], v[194:201], v[114:117], v181, v181 op_sel_hi:[0,0,0]
	v_mfma_scale_f32_16x16x128_f8f6f4 v[122:125], v[184:191], v[10:17], v[122:125], v181, v181 op_sel_hi:[0,0,0]
	v_mfma_scale_f32_16x16x128_f8f6f4 v[126:129], v[26:33], v[10:17], v[126:129], v181, v181 op_sel_hi:[0,0,0]
	s_setprio 0
	s_barrier
	s_mov_b32 m0, s52
	v_lshl_add_u64 v[10:11], s[44:45], 0, v[166:167]
	s_add_u32 s88, s44, 0x80000
	ds_read_b128 v[194:197], v193 offset:16384
	ds_read_b128 v[198:201], v193 offset:17408
	ds_read_b128 v[202:205], v193 offset:18432
	ds_read_b128 v[206:209], v193 offset:19456
	ds_read_b128 v[210:213], v193 offset:20480
	ds_read_b128 v[214:217], v193 offset:21504
	ds_read_b128 v[218:221], v193 offset:22528
	ds_read_b128 v[222:225], v193 offset:23552
	global_load_lds_dwordx4 v[10:11], off
	v_lshl_add_u64 v[12:13], s[44:45], 0, v[170:171]
	s_mov_b32 m0, s53
	s_addc_u32 s89, s45, 0
	global_load_lds_dwordx4 v[12:13], off
	v_lshl_add_u64 v[14:15], s[88:89], 0, v[166:167]
	s_mov_b32 m0, s54
	v_lshl_add_u64 v[16:17], s[48:49], 0, v[168:169]
	global_load_lds_dwordx4 v[14:15], off
	v_lshl_add_u64 v[14:15], s[88:89], 0, v[170:171]
	s_mov_b32 m0, s55
	s_nop 0
	global_load_lds_dwordx4 v[14:15], off
	v_lshl_add_u64 v[14:15], s[48:49], 0, v[164:165]
	s_mov_b32 m0, s43
	s_nop 0
	global_load_lds_dwordx4 v[14:15], off
	s_mov_b32 m0, s61
	s_nop 0
	global_load_lds_dwordx4 v[16:17], off
	s_waitcnt vmcnt(8)
	s_waitcnt lgkmcnt(0)
	s_barrier
	s_setprio 1
	s_waitcnt lgkmcnt(0)
	v_mfma_scale_f32_16x16x128_f8f6f4 v[94:97], v[2:9], v[194:201], v[94:97], v181, v181 op_sel_hi:[0,0,0]
	v_mfma_scale_f32_16x16x128_f8f6f4 v[90:93], v[18:25], v[194:201], v[90:93], v181, v181 op_sel_hi:[0,0,0]
	v_mfma_scale_f32_16x16x128_f8f6f4 v[82:85], v[18:25], v[202:209], v[82:85], v181, v181 op_sel_hi:[0,0,0]
	v_mfma_scale_f32_16x16x128_f8f6f4 v[86:89], v[2:9], v[202:209], v[86:89], v181, v181 op_sel_hi:[0,0,0]
	v_mfma_scale_f32_16x16x128_f8f6f4 v[78:81], v[2:9], v[210:217], v[78:81], v181, v181 op_sel_hi:[0,0,0]
	v_mfma_scale_f32_16x16x128_f8f6f4 v[74:77], v[18:25], v[210:217], v[74:77], v181, v181 op_sel_hi:[0,0,0]
	v_mfma_scale_f32_16x16x128_f8f6f4 v[66:69], v[18:25], v[218:225], v[66:69], v181, v181 op_sel_hi:[0,0,0]
	v_mfma_scale_f32_16x16x128_f8f6f4 v[70:73], v[2:9], v[218:225], v[70:73], v181, v181 op_sel_hi:[0,0,0]
	s_setprio 0
	s_setprio 1
	v_mfma_scale_f32_16x16x128_f8f6f4 v[38:41], v[26:33], v[218:225], v[38:41], v181, v181 op_sel_hi:[0,0,0]
	v_mfma_scale_f32_16x16x128_f8f6f4 v[34:37], v[184:191], v[218:225], v[34:37], v181, v181 op_sel_hi:[0,0,0]
	v_mfma_scale_f32_16x16x128_f8f6f4 v[42:45], v[184:191], v[210:217], v[42:45], v181, v181 op_sel_hi:[0,0,0]
	v_mfma_scale_f32_16x16x128_f8f6f4 v[46:49], v[26:33], v[210:217], v[46:49], v181, v181 op_sel_hi:[0,0,0]
	v_mfma_scale_f32_16x16x128_f8f6f4 v[54:57], v[26:33], v[202:209], v[54:57], v181, v181 op_sel_hi:[0,0,0]
	v_mfma_scale_f32_16x16x128_f8f6f4 v[50:53], v[184:191], v[202:209], v[50:53], v181, v181 op_sel_hi:[0,0,0]
	v_mfma_scale_f32_16x16x128_f8f6f4 v[58:61], v[184:191], v[194:201], v[58:61], v181, v181 op_sel_hi:[0,0,0]
	v_mfma_scale_f32_16x16x128_f8f6f4 v[62:65], v[26:33], v[194:201], v[62:65], v181, v181 op_sel_hi:[0,0,0]
	s_setprio 0
	s_barrier
	ds_read_b128 v[18:21], v192 offset:32768
	ds_read_b128 v[22:25], v192 offset:33792
	ds_read_b128 v[26:29], v192 offset:34816
	ds_read_b128 v[30:33], v192 offset:35840
	ds_read_b128 v[2:5], v192 offset:49152
	ds_read_b128 v[6:9], v192 offset:50176
	ds_read_b128 v[184:187], v192 offset:51200
	ds_read_b128 v[188:191], v192 offset:52224
	s_add_u32 s48, s48, 0x80000
	s_addc_u32 s49, s49, 0
	s_mov_b32 m0, s68
	v_lshl_add_u64 v[226:227], s[48:49], 0, v[164:165]
	ds_read_b128 v[194:197], v193 offset:32768
	ds_read_b128 v[198:201], v193 offset:33792
	ds_read_b128 v[202:205], v193 offset:34816
	ds_read_b128 v[206:209], v193 offset:35840
	ds_read_b128 v[210:213], v193 offset:36864
	ds_read_b128 v[214:217], v193 offset:37888
	ds_read_b128 v[218:221], v193 offset:38912
	ds_read_b128 v[222:225], v193 offset:39936
	global_load_lds_dwordx4 v[226:227], off
	v_lshl_add_u64 v[226:227], s[48:49], 0, v[168:169]
	s_mov_b32 m0, s69
	s_nop 0
	global_load_lds_dwordx4 v[226:227], off
	s_waitcnt vmcnt(8)
	s_waitcnt lgkmcnt(0)
	s_barrier
	s_setprio 1
	s_waitcnt lgkmcnt(0)
	v_mfma_scale_f32_16x16x128_f8f6f4 v[158:161], v[18:25], v[194:201], v[158:161], v181, v181 op_sel_hi:[0,0,0]
	v_mfma_scale_f32_16x16x128_f8f6f4 v[154:157], v[26:33], v[194:201], v[154:157], v181, v181 op_sel_hi:[0,0,0]
	v_mfma_scale_f32_16x16x128_f8f6f4 v[146:149], v[26:33], v[202:209], v[146:149], v181, v181 op_sel_hi:[0,0,0]
	v_mfma_scale_f32_16x16x128_f8f6f4 v[150:153], v[18:25], v[202:209], v[150:153], v181, v181 op_sel_hi:[0,0,0]
	v_mfma_scale_f32_16x16x128_f8f6f4 v[142:145], v[18:25], v[210:217], v[142:145], v181, v181 op_sel_hi:[0,0,0]
	v_mfma_scale_f32_16x16x128_f8f6f4 v[138:141], v[26:33], v[210:217], v[138:141], v181, v181 op_sel_hi:[0,0,0]
	v_mfma_scale_f32_16x16x128_f8f6f4 v[130:133], v[26:33], v[218:225], v[130:133], v181, v181 op_sel_hi:[0,0,0]
	v_mfma_scale_f32_16x16x128_f8f6f4 v[134:137], v[18:25], v[218:225], v[134:137], v181, v181 op_sel_hi:[0,0,0]
	s_setprio 0
	s_setprio 1
	v_mfma_scale_f32_16x16x128_f8f6f4 v[102:105], v[2:9], v[218:225], v[102:105], v181, v181 op_sel_hi:[0,0,0]
	v_mfma_scale_f32_16x16x128_f8f6f4 v[98:101], v[184:191], v[218:225], v[98:101], v181, v181 op_sel_hi:[0,0,0]
	v_mfma_scale_f32_16x16x128_f8f6f4 v[106:109], v[184:191], v[210:217], v[106:109], v181, v181 op_sel_hi:[0,0,0]
	v_mfma_scale_f32_16x16x128_f8f6f4 v[110:113], v[2:9], v[210:217], v[110:113], v181, v181 op_sel_hi:[0,0,0]
	v_mfma_scale_f32_16x16x128_f8f6f4 v[118:121], v[2:9], v[202:209], v[118:121], v181, v181 op_sel_hi:[0,0,0]
	v_mfma_scale_f32_16x16x128_f8f6f4 v[114:117], v[184:191], v[202:209], v[114:117], v181, v181 op_sel_hi:[0,0,0]
	v_mfma_scale_f32_16x16x128_f8f6f4 v[122:125], v[184:191], v[194:201], v[122:125], v181, v181 op_sel_hi:[0,0,0]
	v_mfma_scale_f32_16x16x128_f8f6f4 v[126:129], v[2:9], v[194:201], v[126:129], v181, v181 op_sel_hi:[0,0,0]
	s_setprio 0
	s_barrier
	s_mov_b32 m0, s74
	v_lshl_add_u64 v[10:11], v[10:11], 0, s[4:5]
	s_add_u32 s44, s44, 0x80080
	ds_read_b128 v[194:197], v193 offset:49152
	ds_read_b128 v[198:201], v193 offset:50176
	ds_read_b128 v[202:205], v193 offset:51200
	ds_read_b128 v[206:209], v193 offset:52224
	ds_read_b128 v[210:213], v193 offset:53248
	ds_read_b128 v[214:217], v193 offset:54272
	ds_read_b128 v[218:221], v193 offset:55296
	ds_read_b128 v[222:225], v193 offset:56320
	global_load_lds_dwordx4 v[10:11], off
	v_lshl_add_u64 v[10:11], v[12:13], 0, s[4:5]
	s_mov_b32 m0, s75
	s_addc_u32 s45, s45, 0
	global_load_lds_dwordx4 v[10:11], off
	v_lshl_add_u64 v[10:11], s[44:45], 0, v[166:167]
	s_mov_b32 m0, s78
	s_nop 0
	global_load_lds_dwordx4 v[10:11], off
	v_lshl_add_u64 v[10:11], s[44:45], 0, v[170:171]
	s_mov_b32 m0, s79
	s_nop 0
	global_load_lds_dwordx4 v[10:11], off
	v_lshl_add_u64 v[10:11], v[14:15], 0, s[4:5]
	s_mov_b32 m0, s76
	s_nop 0
	global_load_lds_dwordx4 v[10:11], off
	v_lshl_add_u64 v[10:11], v[16:17], 0, s[4:5]
	s_mov_b32 m0, s77
	s_nop 0
	global_load_lds_dwordx4 v[10:11], off
	s_waitcnt vmcnt(8)
	s_waitcnt lgkmcnt(0)
	s_barrier
	s_setprio 1
	s_waitcnt lgkmcnt(0)
	v_mfma_scale_f32_16x16x128_f8f6f4 v[94:97], v[18:25], v[194:201], v[94:97], v181, v181 op_sel_hi:[0,0,0]
	v_mfma_scale_f32_16x16x128_f8f6f4 v[90:93], v[26:33], v[194:201], v[90:93], v181, v181 op_sel_hi:[0,0,0]
	v_mfma_scale_f32_16x16x128_f8f6f4 v[82:85], v[26:33], v[202:209], v[82:85], v181, v181 op_sel_hi:[0,0,0]
	v_mfma_scale_f32_16x16x128_f8f6f4 v[86:89], v[18:25], v[202:209], v[86:89], v181, v181 op_sel_hi:[0,0,0]
	v_mfma_scale_f32_16x16x128_f8f6f4 v[78:81], v[18:25], v[210:217], v[78:81], v181, v181 op_sel_hi:[0,0,0]
	v_mfma_scale_f32_16x16x128_f8f6f4 v[74:77], v[26:33], v[210:217], v[74:77], v181, v181 op_sel_hi:[0,0,0]
	v_mfma_scale_f32_16x16x128_f8f6f4 v[66:69], v[26:33], v[218:225], v[66:69], v181, v181 op_sel_hi:[0,0,0]
	v_mfma_scale_f32_16x16x128_f8f6f4 v[70:73], v[18:25], v[218:225], v[70:73], v181, v181 op_sel_hi:[0,0,0]
	s_setprio 0
	s_setprio 1
	v_mfma_scale_f32_16x16x128_f8f6f4 v[38:41], v[2:9], v[218:225], v[38:41], v181, v181 op_sel_hi:[0,0,0]
	v_mfma_scale_f32_16x16x128_f8f6f4 v[34:37], v[184:191], v[218:225], v[34:37], v181, v181 op_sel_hi:[0,0,0]
	v_mfma_scale_f32_16x16x128_f8f6f4 v[42:45], v[184:191], v[210:217], v[42:45], v181, v181 op_sel_hi:[0,0,0]
	v_mfma_scale_f32_16x16x128_f8f6f4 v[46:49], v[2:9], v[210:217], v[46:49], v181, v181 op_sel_hi:[0,0,0]
	v_mfma_scale_f32_16x16x128_f8f6f4 v[54:57], v[2:9], v[202:209], v[54:57], v181, v181 op_sel_hi:[0,0,0]
	v_mfma_scale_f32_16x16x128_f8f6f4 v[50:53], v[184:191], v[202:209], v[50:53], v181, v181 op_sel_hi:[0,0,0]
	v_mfma_scale_f32_16x16x128_f8f6f4 v[58:61], v[184:191], v[194:201], v[58:61], v181, v181 op_sel_hi:[0,0,0]
	v_mfma_scale_f32_16x16x128_f8f6f4 v[62:65], v[2:9], v[194:201], v[62:65], v181, v181 op_sel_hi:[0,0,0]
	s_setprio 0
	s_barrier
	s_add_i32 s86, s86, 2
	s_add_u32 s46, s46, 0x100
	s_addc_u32 s47, s47, 0
	s_add_u32 s62, s62, 0x100
	s_addc_u32 s63, s63, 0
	s_cmp_gt_u32 s86, 29
	s_cbranch_scc0 .LBB0_947
	s_and_b64 vcc, exec, s[6:7]
	s_cbranch_vccz .LBB0_950
	s_barrier

.LBB0_957:
	s_ashr_i32 s2, s4, 31
	s_ashr_i32 s0, s4, 3
	s_lshr_b32 s2, s2, 27
	s_add_i32 s2, s0, s2
	s_and_b32 s25, s2, 0x1ffffe0
	s_lshl_b32 s2, s2, 3
	s_sub_i32 s0, s0, s25
	s_and_b32 s1, s18, 64
	s_and_b32 s3, s14, 0xc0
	s_and_b32 s2, s2, 0xffffff00
	s_lshl_b32 s25, s0, 7
	s_or_b32 s0, s2, s3
	s_or_b32 s2, s25, s1
	s_mul_i32 s1, s2, 0x2b00
	s_ashr_i32 s3, s1, 31
	s_add_u32 s25, s8, s1
	s_addc_u32 s33, s9, s3
	s_ashr_i32 s1, s0, 31
	s_lshl_b64 s[26:27], s[0:1], 14
	s_add_u32 s26, s5, s26
	s_addc_u32 s27, s6, s27
	s_ashr_i32 s3, s2, 31
	s_lshl_b64 s[2:3], s[2:3], 2
	s_add_u32 s2, s26, s2
	s_addc_u32 s3, s27, s3
	s_add_u32 s26, s2, 0x8000
	s_addc_u32 s27, s3, 0
	global_load_dword v31, v20, s[2:3] nt
	global_load_dword v72, v20, s[2:3] offset:128 nt
	global_load_dword v34, v20, s[26:27] nt
	global_load_dword v73, v20, s[26:27] offset:128 nt
	s_add_u32 s26, s2, 0x10000
	s_addc_u32 s27, s3, 0
	global_load_dword v35, v20, s[26:27] nt
	global_load_dword v74, v20, s[26:27] offset:128 nt
	s_add_u32 s26, s2, 0x18000
	s_addc_u32 s27, s3, 0
	global_load_dword v36, v20, s[26:27] nt
	global_load_dword v75, v20, s[26:27] offset:128 nt
	s_add_u32 s26, s2, 0x20000
	s_addc_u32 s27, s3, 0
	global_load_dword v37, v20, s[26:27] nt
	global_load_dword v76, v20, s[26:27] offset:128 nt
	s_add_u32 s26, s2, 0x28000
	s_addc_u32 s27, s3, 0
	global_load_dword v38, v20, s[26:27] nt
	global_load_dword v77, v20, s[26:27] offset:128 nt
	s_add_u32 s26, s2, 0x30000
	s_addc_u32 s27, s3, 0
	global_load_dword v39, v20, s[26:27] nt
	global_load_dword v78, v20, s[26:27] offset:128 nt
	s_add_u32 s26, s2, 0x38000
	s_addc_u32 s27, s3, 0
	global_load_dword v40, v20, s[26:27] nt
	global_load_dword v79, v20, s[26:27] offset:128 nt
	s_add_u32 s26, s2, 0x40000
	s_addc_u32 s27, s3, 0
	global_load_dword v32, v20, s[26:27] nt
	global_load_dword v80, v20, s[26:27] offset:128 nt
	s_add_u32 s26, s2, 0x48000
	s_addc_u32 s27, s3, 0
	global_load_dword v33, v20, s[26:27] nt
	global_load_dword v81, v20, s[26:27] offset:128 nt
	s_add_u32 s26, s2, 0x50000
	s_addc_u32 s27, s3, 0
	global_load_dword v41, v20, s[26:27] nt
	global_load_dword v82, v20, s[26:27] offset:128 nt
	s_add_u32 s26, s2, 0x58000
	s_addc_u32 s27, s3, 0
	global_load_dword v42, v20, s[26:27] nt
	global_load_dword v83, v20, s[26:27] offset:128 nt
	s_add_u32 s26, s2, 0x60000
	s_addc_u32 s27, s3, 0
	global_load_dword v43, v20, s[26:27] nt
	global_load_dword v84, v20, s[26:27] offset:128 nt
	s_add_u32 s26, s2, 0x68000
	s_addc_u32 s27, s3, 0
	global_load_dword v44, v20, s[26:27] nt
	global_load_dword v85, v20, s[26:27] offset:128 nt
	s_add_u32 s26, s2, 0x70000
	s_addc_u32 s27, s3, 0
	global_load_dword v45, v20, s[26:27] nt
	global_load_dword v86, v20, s[26:27] offset:128 nt
	s_add_u32 s26, s2, 0x78000
	s_addc_u32 s27, s3, 0
	global_load_dword v46, v20, s[26:27] nt
	global_load_dword v87, v20, s[26:27] offset:128 nt
	s_add_u32 s26, s2, 0x80000
	s_addc_u32 s27, s3, 0
	global_load_dword v47, v20, s[26:27] nt
	global_load_dword v88, v20, s[26:27] offset:128 nt
	s_add_u32 s26, s2, 0x88000
	s_addc_u32 s27, s3, 0
	global_load_dword v48, v20, s[26:27] nt
	global_load_dword v89, v20, s[26:27] offset:128 nt
	s_add_u32 s26, s2, 0x90000
	s_addc_u32 s27, s3, 0
	global_load_dword v49, v20, s[26:27] nt
	global_load_dword v90, v20, s[26:27] offset:128 nt
	s_add_u32 s26, s2, 0x98000
	s_addc_u32 s27, s3, 0
	global_load_dword v50, v20, s[26:27] nt
	global_load_dword v91, v20, s[26:27] offset:128 nt
	s_add_u32 s26, s2, 0xa0000
	s_addc_u32 s27, s3, 0
	global_load_dword v51, v20, s[26:27] nt
	global_load_dword v92, v20, s[26:27] offset:128 nt
	s_add_u32 s26, s2, 0xa8000
	s_addc_u32 s27, s3, 0
	global_load_dword v52, v20, s[26:27] nt
	global_load_dword v93, v20, s[26:27] offset:128 nt
	s_add_u32 s26, s2, 0xb0000
	s_addc_u32 s27, s3, 0
	global_load_dword v53, v20, s[26:27] nt
	global_load_dword v94, v20, s[26:27] offset:128 nt
	s_add_u32 s26, s2, 0xb8000
	s_addc_u32 s27, s3, 0
	global_load_dword v54, v20, s[26:27] nt
	global_load_dword v95, v20, s[26:27] offset:128 nt
	s_add_u32 s26, s2, 0xc0000
	s_addc_u32 s27, s3, 0
	global_load_dword v55, v20, s[26:27] nt
	global_load_dword v96, v20, s[26:27] offset:128 nt
	s_add_u32 s26, s2, 0xc8000
	s_addc_u32 s27, s3, 0
	global_load_dword v56, v20, s[26:27] nt
	global_load_dword v97, v20, s[26:27] offset:128 nt
	s_add_u32 s26, s2, 0xd0000
	s_addc_u32 s27, s3, 0
	global_load_dword v57, v20, s[26:27] nt
	global_load_dword v98, v20, s[26:27] offset:128 nt
	s_add_u32 s26, s2, 0xd8000
	s_addc_u32 s27, s3, 0
	global_load_dword v58, v20, s[26:27] nt
	global_load_dword v99, v20, s[26:27] offset:128 nt
	s_add_u32 s26, s2, 0xe0000
	s_addc_u32 s27, s3, 0
	global_load_dword v59, v20, s[26:27] nt
	global_load_dword v100, v20, s[26:27] offset:128 nt
	s_add_u32 s26, s2, 0xe8000
	s_addc_u32 s27, s3, 0
	global_load_dword v60, v20, s[26:27] nt
	global_load_dword v101, v20, s[26:27] offset:128 nt
	s_add_u32 s26, s2, 0xf0000
	s_addc_u32 s27, s3, 0
	s_add_u32 s2, s2, 0xf8000
	global_load_dword v61, v20, s[26:27] nt
	global_load_dword v102, v20, s[26:27] offset:128 nt
	s_addc_u32 s3, s3, 0
	global_load_dword v62, v20, s[2:3] nt
	global_load_dword v103, v20, s[2:3] offset:128 nt
	s_waitcnt vmcnt(0)
	s_add_u32 s0, s25, s0
	ds_write2_b32 v24, v32, v33 offset0:16 offset1:82
	ds_write2_b32 v24, v41, v42 offset0:148 offset1:214
	ds_write2_b32 v25, v43, v44 offset0:24 offset1:90
	ds_write2_b32 v25, v45, v46 offset0:156 offset1:222
	ds_write2_b32 v26, v47, v48 offset0:32 offset1:98
	ds_write2_b32 v26, v49, v50 offset0:164 offset1:230
	ds_write2_b32 v27, v51, v52 offset0:40 offset1:106
	ds_write2_b32 v27, v53, v54 offset0:172 offset1:238
	ds_write2_b32 v28, v55, v56 offset0:48 offset1:114
	ds_write2_b32 v28, v57, v58 offset0:180 offset1:246
	ds_write2_b32 v29, v59, v60 offset0:56 offset1:122
	ds_write2_b32 v29, v61, v62 offset0:188 offset1:254
	ds_write2_b32 v22, v31, v34 offset1:66
	ds_write2_b32 v22, v35, v36 offset0:132 offset1:198
	ds_write2_b32 v23, v37, v38 offset0:8 offset1:74
	ds_write2_b32 v23, v39, v40 offset0:140 offset1:206
	s_waitcnt lgkmcnt(0)
	ds_read2_b32 v[40:41], v21 offset1:16
	ds_read2_b32 v[42:43], v21 offset0:33 offset1:49
	ds_read2_b32 v[44:45], v21 offset0:66 offset1:82
	ds_read2_b32 v[46:47], v21 offset0:99 offset1:115
	ds_read2_b32 v[48:49], v21 offset0:132 offset1:148
	ds_read2_b32 v[50:51], v21 offset0:165 offset1:181
	ds_read2_b32 v[52:53], v21 offset0:198 offset1:214
	ds_read2_b32 v[54:55], v21 offset0:231 offset1:247
	ds_read2_b32 v[56:57], v30 offset0:8 offset1:24
	ds_read2_b32 v[58:59], v30 offset0:41 offset1:57
	ds_read2_b32 v[60:61], v30 offset0:74 offset1:90
	ds_read2_b32 v[62:63], v30 offset0:107 offset1:123
	ds_read2_b32 v[64:65], v30 offset0:140 offset1:156
	ds_read2_b32 v[66:67], v30 offset0:173 offset1:189
	ds_read2_b32 v[68:69], v30 offset0:206 offset1:222
	ds_read2_b32 v[70:71], v30 offset0:239 offset1:255
	s_addc_u32 s1, s33, s1
	v_mov_b32_e32 v2, 0
	v_mov_b32_e32 v3, 0
	v_mov_b32_e32 v4, 0
	v_mov_b32_e32 v5, 0
	v_lshl_add_u64 v[32:33], s[0:1], 0, v[162:163]
	v_mov_b32_e32 v10, 0
	v_mov_b32_e32 v11, 0
	v_mov_b32_e32 v12, 0
	v_mov_b32_e32 v13, 0
	v_lshl_add_u64 v[32:33], v[32:33], 0, v[18:19]
	s_waitcnt lgkmcnt(0)
	v_cvt_scalef32_pk_fp8_f32 v2, v40, v42, s22
	v_cvt_scalef32_pk_fp8_f32 v3, v48, v50, s22
	v_cvt_scalef32_pk_fp8_f32 v4, v56, v58, s22
	v_cvt_scalef32_pk_fp8_f32 v5, v64, v66, s22
	v_add_co_u32_e32 v34, vcc, s23, v32
	v_cvt_scalef32_pk_fp8_f32 v10, v41, v43, s22
	v_cvt_scalef32_pk_fp8_f32 v11, v49, v51, s22
	v_cvt_scalef32_pk_fp8_f32 v12, v57, v59, s22
	v_cvt_scalef32_pk_fp8_f32 v13, v65, v67, s22
	v_cvt_scalef32_pk_fp8_f32 v2, v44, v46, s22 op_sel:[0,0,0,1]
	v_cvt_scalef32_pk_fp8_f32 v3, v52, v54, s22 op_sel:[0,0,0,1]
	v_cvt_scalef32_pk_fp8_f32 v4, v60, v62, s22 op_sel:[0,0,0,1]
	v_cvt_scalef32_pk_fp8_f32 v5, v68, v70, s22 op_sel:[0,0,0,1]
	v_addc_co_u32_e32 v35, vcc, 0, v33, vcc
	v_cvt_scalef32_pk_fp8_f32 v10, v45, v47, s22 op_sel:[0,0,0,1]
	v_cvt_scalef32_pk_fp8_f32 v11, v53, v55, s22 op_sel:[0,0,0,1]
	v_cvt_scalef32_pk_fp8_f32 v12, v61, v63, s22 op_sel:[0,0,0,1]
	v_cvt_scalef32_pk_fp8_f32 v13, v69, v71, s22 op_sel:[0,0,0,1]
	global_store_dwordx4 v[32:33], v[2:5], off
	global_store_dwordx4 v[34:35], v[10:13], off
	s_waitcnt lgkmcnt(0)
	v_add_co_u32_e32 v36, vcc, s24, v32
	ds_write2_b32 v22, v72, v73 offset1:66
	ds_write2_b32 v22, v74, v75 offset0:132 offset1:198
	ds_write2_b32 v23, v76, v77 offset0:8 offset1:74
	ds_write2_b32 v23, v78, v79 offset0:140 offset1:206
	ds_write2_b32 v24, v80, v81 offset0:16 offset1:82
	ds_write2_b32 v24, v82, v83 offset0:148 offset1:214
	ds_write2_b32 v25, v84, v85 offset0:24 offset1:90
	ds_write2_b32 v25, v86, v87 offset0:156 offset1:222
	ds_write2_b32 v26, v88, v89 offset0:32 offset1:98
	ds_write2_b32 v26, v90, v91 offset0:164 offset1:230
	ds_write2_b32 v27, v92, v93 offset0:40 offset1:106
	ds_write2_b32 v27, v94, v95 offset0:172 offset1:238
	ds_write2_b32 v28, v96, v97 offset0:48 offset1:114
	ds_write2_b32 v28, v98, v99 offset0:180 offset1:246
	ds_write2_b32 v29, v100, v101 offset0:56 offset1:122
	ds_write2_b32 v29, v102, v103 offset0:188 offset1:254
	v_addc_co_u32_e32 v37, vcc, 0, v33, vcc
	s_waitcnt lgkmcnt(0)
	v_add_co_u32_e32 v38, vcc, 0x81000, v32
	v_mov_b32_e32 v6, 0
	s_nop 0
	v_addc_co_u32_e32 v39, vcc, 0, v33, vcc
	ds_read2_b32 v[2:3], v21 offset1:16
	ds_read2_b32 v[4:5], v21 offset0:33 offset1:49
	ds_read2_b32 v[10:11], v21 offset0:66 offset1:82
	ds_read2_b32 v[12:13], v21 offset0:99 offset1:115
	ds_read2_b32 v[32:33], v21 offset0:132 offset1:148
	ds_read2_b32 v[34:35], v21 offset0:165 offset1:181
	ds_read2_b32 v[40:41], v21 offset0:198 offset1:214
	ds_read2_b32 v[42:43], v21 offset0:231 offset1:247
	ds_read2_b32 v[44:45], v30 offset0:8 offset1:24
	ds_read2_b32 v[46:47], v30 offset0:41 offset1:57
	ds_read2_b32 v[48:49], v30 offset0:74 offset1:90
	ds_read2_b32 v[50:51], v30 offset0:107 offset1:123
	ds_read2_b32 v[52:53], v30 offset0:140 offset1:156
	ds_read2_b32 v[54:55], v30 offset0:173 offset1:189
	ds_read2_b32 v[56:57], v30 offset0:206 offset1:222
	ds_read2_b32 v[58:59], v30 offset0:239 offset1:255
	v_mov_b32_e32 v7, 0
	v_mov_b32_e32 v8, 0
	v_mov_b32_e32 v9, 0
	v_mov_b32_e32 v14, 0
	v_mov_b32_e32 v15, 0
	v_mov_b32_e32 v16, 0
	v_mov_b32_e32 v17, 0
	s_waitcnt lgkmcnt(0)
	v_cvt_scalef32_pk_fp8_f32 v6, v2, v4, s22
	v_cvt_scalef32_pk_fp8_f32 v7, v32, v34, s22
	v_cvt_scalef32_pk_fp8_f32 v8, v44, v46, s22
	v_cvt_scalef32_pk_fp8_f32 v9, v52, v54, s22
	v_cvt_scalef32_pk_fp8_f32 v14, v3, v5, s22
	v_cvt_scalef32_pk_fp8_f32 v15, v33, v35, s22
	v_cvt_scalef32_pk_fp8_f32 v16, v45, v47, s22
	v_cvt_scalef32_pk_fp8_f32 v17, v53, v55, s22
	v_cvt_scalef32_pk_fp8_f32 v6, v10, v12, s22 op_sel:[0,0,0,1]
	v_cvt_scalef32_pk_fp8_f32 v7, v40, v42, s22 op_sel:[0,0,0,1]
	v_cvt_scalef32_pk_fp8_f32 v8, v48, v50, s22 op_sel:[0,0,0,1]
	v_cvt_scalef32_pk_fp8_f32 v9, v56, v58, s22 op_sel:[0,0,0,1]
	v_cvt_scalef32_pk_fp8_f32 v14, v11, v13, s22 op_sel:[0,0,0,1]
	v_cvt_scalef32_pk_fp8_f32 v15, v41, v43, s22 op_sel:[0,0,0,1]
	v_cvt_scalef32_pk_fp8_f32 v16, v49, v51, s22 op_sel:[0,0,0,1]
	v_cvt_scalef32_pk_fp8_f32 v17, v57, v59, s22 op_sel:[0,0,0,1]
	global_store_dwordx4 v[36:37], v[6:9], off
	global_store_dwordx4 v[38:39], v[14:17], off
	s_waitcnt lgkmcnt(0)
	s_add_i32 s4, s4, s7
	s_add_i32 s14, s14, s15
	s_add_i32 s18, s18, s19
	s_cmpk_lt_i32 s4, 0x2b00
	s_cbranch_scc1 .LBB0_957

.LBB0_1031:
	ds_read_b128 v[2:5], v189
	ds_read_b128 v[6:9], v189 offset:1024
	ds_read_b128 v[192:195], v189 offset:2048
	ds_read_b128 v[196:199], v189 offset:3072
	ds_read_b128 v[200:203], v189 offset:16384
	ds_read_b128 v[204:207], v189 offset:17408
	ds_read_b128 v[208:211], v189 offset:18432
	ds_read_b128 v[212:215], v189 offset:19456
	s_add_u32 s25, s36, 0x100
	s_addc_u32 s83, s37, 0
	s_and_b64 s[40:41], s[38:39], exec
	s_cselect_b32 s41, s1, s83
	s_cselect_b32 s40, s0, s25
	s_add_u32 s25, s26, 0x100
	s_addc_u32 s83, s27, 0
	s_and_b64 s[38:39], s[38:39], exec
	s_cselect_b32 s39, s5, s83
	s_cselect_b32 s38, s4, s25
	s_add_u32 s84, s36, 0x158080
	s_addc_u32 s85, s37, 0
	s_add_i32 s25, s23, 0xc000
	v_lshl_add_u64 v[174:175], s[84:85], 0, v[154:155]
	s_mov_b32 m0, s25
	s_add_i32 s83, s23, 0xe000
	ds_read_b128 v[216:219], v190
	ds_read_b128 v[220:223], v190 offset:1024
	ds_read_b128 v[224:227], v190 offset:2048
	ds_read_b128 v[228:231], v190 offset:3072
	ds_read_b128 v[232:235], v190 offset:4096
	ds_read_b128 v[236:239], v190 offset:5120
	ds_read_b128 v[240:243], v190 offset:6144
	ds_read_b128 v[244:247], v190 offset:7168
	global_load_lds_dwordx4 v[174:175], off
	v_lshl_add_u64 v[174:175], s[84:85], 0, v[158:159]
	s_mov_b32 m0, s83
	s_nop 0
	global_load_lds_dwordx4 v[174:175], off
	s_waitcnt vmcnt(8)
	s_waitcnt lgkmcnt(0)
	s_barrier
	s_setprio 1
	s_waitcnt lgkmcnt(0)
	v_mfma_scale_f32_16x16x128_f8f6f4 v[134:137], v[2:9], v[216:223], 0, v188, v188 op_sel_hi:[0,0,0]
	v_mfma_scale_f32_16x16x128_f8f6f4 v[130:133], v[192:199], v[216:223], 0, v188, v188 op_sel_hi:[0,0,0]
	v_mfma_scale_f32_16x16x128_f8f6f4 v[122:125], v[192:199], v[224:231], 0, v188, v188 op_sel_hi:[0,0,0]
	v_mfma_scale_f32_16x16x128_f8f6f4 v[126:129], v[2:9], v[224:231], 0, v188, v188 op_sel_hi:[0,0,0]
	v_mfma_scale_f32_16x16x128_f8f6f4 v[118:121], v[2:9], v[232:239], 0, v188, v188 op_sel_hi:[0,0,0]
	v_mfma_scale_f32_16x16x128_f8f6f4 v[114:117], v[192:199], v[232:239], 0, v188, v188 op_sel_hi:[0,0,0]
	v_mfma_scale_f32_16x16x128_f8f6f4 v[106:109], v[192:199], v[240:247], 0, v188, v188 op_sel_hi:[0,0,0]
	v_mfma_scale_f32_16x16x128_f8f6f4 v[110:113], v[2:9], v[240:247], 0, v188, v188 op_sel_hi:[0,0,0]
	s_setprio 0
	s_setprio 1
	v_mfma_scale_f32_16x16x128_f8f6f4 v[78:81], v[200:207], v[240:247], 0, v188, v188 op_sel_hi:[0,0,0]
	v_mfma_scale_f32_16x16x128_f8f6f4 v[74:77], v[208:215], v[240:247], 0, v188, v188 op_sel_hi:[0,0,0]
	v_mfma_scale_f32_16x16x128_f8f6f4 v[82:85], v[208:215], v[232:239], 0, v188, v188 op_sel_hi:[0,0,0]
	v_mfma_scale_f32_16x16x128_f8f6f4 v[86:89], v[200:207], v[232:239], 0, v188, v188 op_sel_hi:[0,0,0]
	v_mfma_scale_f32_16x16x128_f8f6f4 v[94:97], v[200:207], v[224:231], 0, v188, v188 op_sel_hi:[0,0,0]
	v_mfma_scale_f32_16x16x128_f8f6f4 v[90:93], v[208:215], v[224:231], 0, v188, v188 op_sel_hi:[0,0,0]
	v_mfma_scale_f32_16x16x128_f8f6f4 v[98:101], v[208:215], v[216:223], 0, v188, v188 op_sel_hi:[0,0,0]
	v_mfma_scale_f32_16x16x128_f8f6f4 v[102:105], v[200:207], v[216:223], 0, v188, v188 op_sel_hi:[0,0,0]
	s_setprio 0
	s_barrier
	s_mov_b32 m0, s33
	v_lshl_add_u64 v[174:175], s[38:39], 0, v[156:157]
	s_add_u32 s84, s38, 0x158000
	ds_read_b128 v[216:219], v190 offset:16384
	ds_read_b128 v[220:223], v190 offset:17408
	ds_read_b128 v[224:227], v190 offset:18432
	ds_read_b128 v[228:231], v190 offset:19456
	ds_read_b128 v[232:235], v190 offset:20480
	ds_read_b128 v[236:239], v190 offset:21504
	ds_read_b128 v[240:243], v190 offset:22528
	ds_read_b128 v[244:247], v190 offset:23552
	global_load_lds_dwordx4 v[174:175], off
	v_lshl_add_u64 v[176:177], s[38:39], 0, v[160:161]
	s_mov_b32 m0, s35
	s_addc_u32 s85, s39, 0
	global_load_lds_dwordx4 v[176:177], off
	v_lshl_add_u64 v[182:183], s[84:85], 0, v[156:157]
	s_mov_b32 m0, s42
	v_lshl_add_u64 v[184:185], s[40:41], 0, v[158:159]
	global_load_lds_dwordx4 v[182:183], off
	v_lshl_add_u64 v[182:183], s[84:85], 0, v[160:161]
	s_mov_b32 m0, s43
	s_nop 0
	global_load_lds_dwordx4 v[182:183], off
	v_lshl_add_u64 v[182:183], s[40:41], 0, v[154:155]
	s_mov_b32 m0, s23
	s_nop 0
	global_load_lds_dwordx4 v[182:183], off
	s_mov_b32 m0, s44
	s_nop 0
	global_load_lds_dwordx4 v[184:185], off
	s_waitcnt vmcnt(8)
	s_waitcnt lgkmcnt(0)
	s_barrier
	s_setprio 1
	s_waitcnt lgkmcnt(0)
	v_mfma_scale_f32_16x16x128_f8f6f4 v[70:73], v[2:9], v[216:223], 0, v188, v188 op_sel_hi:[0,0,0]
	v_mfma_scale_f32_16x16x128_f8f6f4 v[66:69], v[192:199], v[216:223], 0, v188, v188 op_sel_hi:[0,0,0]
	v_mfma_scale_f32_16x16x128_f8f6f4 v[58:61], v[192:199], v[224:231], 0, v188, v188 op_sel_hi:[0,0,0]
	v_mfma_scale_f32_16x16x128_f8f6f4 v[62:65], v[2:9], v[224:231], 0, v188, v188 op_sel_hi:[0,0,0]
	v_mfma_scale_f32_16x16x128_f8f6f4 v[54:57], v[2:9], v[232:239], 0, v188, v188 op_sel_hi:[0,0,0]
	v_mfma_scale_f32_16x16x128_f8f6f4 v[50:53], v[192:199], v[232:239], 0, v188, v188 op_sel_hi:[0,0,0]
	v_mfma_scale_f32_16x16x128_f8f6f4 v[42:45], v[192:199], v[240:247], 0, v188, v188 op_sel_hi:[0,0,0]
	v_mfma_scale_f32_16x16x128_f8f6f4 v[46:49], v[2:9], v[240:247], 0, v188, v188 op_sel_hi:[0,0,0]
	s_setprio 0
	s_setprio 1
	v_mfma_scale_f32_16x16x128_f8f6f4 v[14:17], v[200:207], v[240:247], 0, v188, v188 op_sel_hi:[0,0,0]
	v_mfma_scale_f32_16x16x128_f8f6f4 v[10:13], v[208:215], v[240:247], 0, v188, v188 op_sel_hi:[0,0,0]
	v_mfma_scale_f32_16x16x128_f8f6f4 v[18:21], v[208:215], v[232:239], 0, v188, v188 op_sel_hi:[0,0,0]
	v_mfma_scale_f32_16x16x128_f8f6f4 v[22:25], v[200:207], v[232:239], 0, v188, v188 op_sel_hi:[0,0,0]
	v_mfma_scale_f32_16x16x128_f8f6f4 v[30:33], v[200:207], v[224:231], 0, v188, v188 op_sel_hi:[0,0,0]
	v_mfma_scale_f32_16x16x128_f8f6f4 v[26:29], v[208:215], v[224:231], 0, v188, v188 op_sel_hi:[0,0,0]
	v_mfma_scale_f32_16x16x128_f8f6f4 v[34:37], v[208:215], v[216:223], 0, v188, v188 op_sel_hi:[0,0,0]
	v_mfma_scale_f32_16x16x128_f8f6f4 v[38:41], v[200:207], v[216:223], 0, v188, v188 op_sel_hi:[0,0,0]
	s_setprio 0
	s_barrier
	ds_read_b128 v[2:5], v189 offset:32768
	ds_read_b128 v[6:9], v189 offset:33792
	ds_read_b128 v[192:195], v189 offset:34816
	ds_read_b128 v[196:199], v189 offset:35840
	ds_read_b128 v[200:203], v189 offset:49152
	ds_read_b128 v[204:207], v189 offset:50176
	ds_read_b128 v[208:211], v189 offset:51200
	ds_read_b128 v[212:215], v189 offset:52224
	s_add_u32 s40, s40, 0x158000
	s_addc_u32 s41, s41, 0
	s_mov_b32 m0, s45
	v_lshl_add_u64 v[186:187], s[40:41], 0, v[154:155]
	ds_read_b128 v[216:219], v190 offset:32768
	ds_read_b128 v[220:223], v190 offset:33792
	ds_read_b128 v[224:227], v190 offset:34816
	ds_read_b128 v[228:231], v190 offset:35840
	ds_read_b128 v[232:235], v190 offset:36864
	ds_read_b128 v[236:239], v190 offset:37888
	ds_read_b128 v[240:243], v190 offset:38912
	ds_read_b128 v[244:247], v190 offset:39936
	global_load_lds_dwordx4 v[186:187], off
	v_lshl_add_u64 v[186:187], s[40:41], 0, v[158:159]
	s_mov_b32 m0, s46
	s_nop 0
	global_load_lds_dwordx4 v[186:187], off
	s_waitcnt vmcnt(8)
	s_waitcnt lgkmcnt(0)
	s_barrier
	s_setprio 1
	s_waitcnt lgkmcnt(0)
	v_mfma_scale_f32_16x16x128_f8f6f4 v[134:137], v[2:9], v[216:223], v[134:137], v188, v188 op_sel_hi:[0,0,0]
	v_mfma_scale_f32_16x16x128_f8f6f4 v[130:133], v[192:199], v[216:223], v[130:133], v188, v188 op_sel_hi:[0,0,0]
	v_mfma_scale_f32_16x16x128_f8f6f4 v[122:125], v[192:199], v[224:231], v[122:125], v188, v188 op_sel_hi:[0,0,0]
	v_mfma_scale_f32_16x16x128_f8f6f4 v[126:129], v[2:9], v[224:231], v[126:129], v188, v188 op_sel_hi:[0,0,0]
	v_mfma_scale_f32_16x16x128_f8f6f4 v[118:121], v[2:9], v[232:239], v[118:121], v188, v188 op_sel_hi:[0,0,0]
	v_mfma_scale_f32_16x16x128_f8f6f4 v[114:117], v[192:199], v[232:239], v[114:117], v188, v188 op_sel_hi:[0,0,0]
	v_mfma_scale_f32_16x16x128_f8f6f4 v[106:109], v[192:199], v[240:247], v[106:109], v188, v188 op_sel_hi:[0,0,0]
	v_mfma_scale_f32_16x16x128_f8f6f4 v[110:113], v[2:9], v[240:247], v[110:113], v188, v188 op_sel_hi:[0,0,0]
	s_setprio 0
	s_setprio 1
	v_mfma_scale_f32_16x16x128_f8f6f4 v[78:81], v[200:207], v[240:247], v[78:81], v188, v188 op_sel_hi:[0,0,0]
	v_mfma_scale_f32_16x16x128_f8f6f4 v[74:77], v[208:215], v[240:247], v[74:77], v188, v188 op_sel_hi:[0,0,0]
	v_mfma_scale_f32_16x16x128_f8f6f4 v[82:85], v[208:215], v[232:239], v[82:85], v188, v188 op_sel_hi:[0,0,0]
	v_mfma_scale_f32_16x16x128_f8f6f4 v[86:89], v[200:207], v[232:239], v[86:89], v188, v188 op_sel_hi:[0,0,0]
	v_mfma_scale_f32_16x16x128_f8f6f4 v[94:97], v[200:207], v[224:231], v[94:97], v188, v188 op_sel_hi:[0,0,0]
	v_mfma_scale_f32_16x16x128_f8f6f4 v[90:93], v[208:215], v[224:231], v[90:93], v188, v188 op_sel_hi:[0,0,0]
	v_mfma_scale_f32_16x16x128_f8f6f4 v[98:101], v[208:215], v[216:223], v[98:101], v188, v188 op_sel_hi:[0,0,0]
	v_mfma_scale_f32_16x16x128_f8f6f4 v[102:105], v[200:207], v[216:223], v[102:105], v188, v188 op_sel_hi:[0,0,0]
	s_setprio 0
	s_barrier
	s_mov_b32 m0, s52
	v_lshl_add_u64 v[174:175], v[174:175], 0, s[14:15]
	s_add_u32 s38, s38, 0x158080
	ds_read_b128 v[216:219], v190 offset:49152
	ds_read_b128 v[220:223], v190 offset:50176
	ds_read_b128 v[224:227], v190 offset:51200
	ds_read_b128 v[228:231], v190 offset:52224
	ds_read_b128 v[232:235], v190 offset:53248
	ds_read_b128 v[236:239], v190 offset:54272
	ds_read_b128 v[240:243], v190 offset:55296
	ds_read_b128 v[244:247], v190 offset:56320
	global_load_lds_dwordx4 v[174:175], off
	v_lshl_add_u64 v[174:175], v[176:177], 0, s[14:15]
	s_mov_b32 m0, s53
	s_addc_u32 s39, s39, 0
	global_load_lds_dwordx4 v[174:175], off
	v_lshl_add_u64 v[174:175], s[38:39], 0, v[156:157]
	s_mov_b32 m0, s56
	s_nop 0
	global_load_lds_dwordx4 v[174:175], off
	v_lshl_add_u64 v[174:175], s[38:39], 0, v[160:161]
	s_mov_b32 m0, s57
	s_nop 0
	global_load_lds_dwordx4 v[174:175], off
	v_lshl_add_u64 v[174:175], v[182:183], 0, s[14:15]
	s_mov_b32 m0, s54
	s_nop 0
	global_load_lds_dwordx4 v[174:175], off
	v_lshl_add_u64 v[174:175], v[184:185], 0, s[14:15]
	s_mov_b32 m0, s55
	s_nop 0
	global_load_lds_dwordx4 v[174:175], off
	s_waitcnt vmcnt(8)
	s_waitcnt lgkmcnt(0)
	s_barrier
	s_setprio 1
	s_waitcnt lgkmcnt(0)
	v_mfma_scale_f32_16x16x128_f8f6f4 v[70:73], v[2:9], v[216:223], v[70:73], v188, v188 op_sel_hi:[0,0,0]
	v_mfma_scale_f32_16x16x128_f8f6f4 v[66:69], v[192:199], v[216:223], v[66:69], v188, v188 op_sel_hi:[0,0,0]
	v_mfma_scale_f32_16x16x128_f8f6f4 v[58:61], v[192:199], v[224:231], v[58:61], v188, v188 op_sel_hi:[0,0,0]
	v_mfma_scale_f32_16x16x128_f8f6f4 v[62:65], v[2:9], v[224:231], v[62:65], v188, v188 op_sel_hi:[0,0,0]
	v_mfma_scale_f32_16x16x128_f8f6f4 v[54:57], v[2:9], v[232:239], v[54:57], v188, v188 op_sel_hi:[0,0,0]
	v_mfma_scale_f32_16x16x128_f8f6f4 v[50:53], v[192:199], v[232:239], v[50:53], v188, v188 op_sel_hi:[0,0,0]
	v_mfma_scale_f32_16x16x128_f8f6f4 v[42:45], v[192:199], v[240:247], v[42:45], v188, v188 op_sel_hi:[0,0,0]
	v_mfma_scale_f32_16x16x128_f8f6f4 v[46:49], v[2:9], v[240:247], v[46:49], v188, v188 op_sel_hi:[0,0,0]
	s_setprio 0
	s_setprio 1
	v_mfma_scale_f32_16x16x128_f8f6f4 v[14:17], v[200:207], v[240:247], v[14:17], v188, v188 op_sel_hi:[0,0,0]
	v_mfma_scale_f32_16x16x128_f8f6f4 v[10:13], v[208:215], v[240:247], v[10:13], v188, v188 op_sel_hi:[0,0,0]
	v_mfma_scale_f32_16x16x128_f8f6f4 v[18:21], v[208:215], v[232:239], v[18:21], v188, v188 op_sel_hi:[0,0,0]
	v_mfma_scale_f32_16x16x128_f8f6f4 v[22:25], v[200:207], v[232:239], v[22:25], v188, v188 op_sel_hi:[0,0,0]
	v_mfma_scale_f32_16x16x128_f8f6f4 v[30:33], v[200:207], v[224:231], v[30:33], v188, v188 op_sel_hi:[0,0,0]
	v_mfma_scale_f32_16x16x128_f8f6f4 v[26:29], v[208:215], v[224:231], v[26:29], v188, v188 op_sel_hi:[0,0,0]
	v_mfma_scale_f32_16x16x128_f8f6f4 v[34:37], v[208:215], v[216:223], v[34:37], v188, v188 op_sel_hi:[0,0,0]
	v_mfma_scale_f32_16x16x128_f8f6f4 v[38:41], v[200:207], v[216:223], v[38:41], v188, v188 op_sel_hi:[0,0,0]
	s_setprio 0
	s_barrier
	s_cmp_lt_u32 s82, 3
	s_cbranch_scc1 .LBB0_1036
	s_add_u32 s38, s48, s63
	s_addc_u32 s39, s49, s62
	s_add_u32 s36, s36, 0x158180
	s_addc_u32 s37, s37, 0
	s_add_u32 s40, s26, 0x200
	v_lshl_add_u64 v[174:175], v[172:173], 2, s[38:39]
	s_addc_u32 s41, s27, 0
	s_mov_b32 s84, 4
	s_cmp_eq_u32 s82, s84
	s_cselect_b64 s[26:27], -1, 0
	s_cmp_lg_u32 s82, s84
	s_cbranch_scc1 .LBB0_1034

.LBB0_1034:
	ds_read_b128 v[2:5], v189
	ds_read_b128 v[6:9], v189 offset:1024
	ds_read_b128 v[192:195], v189 offset:2048
	ds_read_b128 v[196:199], v189 offset:3072
	ds_read_b128 v[200:203], v189 offset:16384
	ds_read_b128 v[204:207], v189 offset:17408
	ds_read_b128 v[208:211], v189 offset:18432
	ds_read_b128 v[212:215], v189 offset:19456
	s_add_u32 s38, s36, 0xffea8080
	s_addc_u32 s39, s37, -1
	s_and_b64 s[26:27], s[26:27], exec
	s_cselect_b32 s26, s4, s40
	s_cselect_b32 s39, s1, s39
	s_cselect_b32 s38, s0, s38
	s_cselect_b32 s27, s5, s41
	s_mov_b32 m0, s25
	v_lshl_add_u64 v[176:177], s[36:37], 0, v[162:163]
	ds_read_b128 v[216:219], v190
	ds_read_b128 v[220:223], v190 offset:1024
	ds_read_b128 v[224:227], v190 offset:2048
	ds_read_b128 v[228:231], v190 offset:3072
	ds_read_b128 v[232:235], v190 offset:4096
	ds_read_b128 v[236:239], v190 offset:5120
	ds_read_b128 v[240:243], v190 offset:6144
	ds_read_b128 v[244:247], v190 offset:7168
	global_load_lds_dwordx4 v[176:177], off
	v_lshl_add_u64 v[176:177], s[36:37], 0, v[164:165]
	s_mov_b32 m0, s83
	s_nop 0
	global_load_lds_dwordx4 v[176:177], off
	s_waitcnt vmcnt(8)
	s_waitcnt lgkmcnt(0)
	s_barrier
	s_setprio 1
	s_waitcnt lgkmcnt(0)
	v_mfma_scale_f32_16x16x128_f8f6f4 v[134:137], v[2:9], v[216:223], v[134:137], v188, v188 op_sel_hi:[0,0,0]
	v_mfma_scale_f32_16x16x128_f8f6f4 v[130:133], v[192:199], v[216:223], v[130:133], v188, v188 op_sel_hi:[0,0,0]
	v_mfma_scale_f32_16x16x128_f8f6f4 v[122:125], v[192:199], v[224:231], v[122:125], v188, v188 op_sel_hi:[0,0,0]
	v_mfma_scale_f32_16x16x128_f8f6f4 v[126:129], v[2:9], v[224:231], v[126:129], v188, v188 op_sel_hi:[0,0,0]
	v_mfma_scale_f32_16x16x128_f8f6f4 v[118:121], v[2:9], v[232:239], v[118:121], v188, v188 op_sel_hi:[0,0,0]
	v_mfma_scale_f32_16x16x128_f8f6f4 v[114:117], v[192:199], v[232:239], v[114:117], v188, v188 op_sel_hi:[0,0,0]
	v_mfma_scale_f32_16x16x128_f8f6f4 v[106:109], v[192:199], v[240:247], v[106:109], v188, v188 op_sel_hi:[0,0,0]
	v_mfma_scale_f32_16x16x128_f8f6f4 v[110:113], v[2:9], v[240:247], v[110:113], v188, v188 op_sel_hi:[0,0,0]
	s_setprio 0
	s_setprio 1
	v_mfma_scale_f32_16x16x128_f8f6f4 v[78:81], v[200:207], v[240:247], v[78:81], v188, v188 op_sel_hi:[0,0,0]
	v_mfma_scale_f32_16x16x128_f8f6f4 v[74:77], v[208:215], v[240:247], v[74:77], v188, v188 op_sel_hi:[0,0,0]
	v_mfma_scale_f32_16x16x128_f8f6f4 v[82:85], v[208:215], v[232:239], v[82:85], v188, v188 op_sel_hi:[0,0,0]
	v_mfma_scale_f32_16x16x128_f8f6f4 v[86:89], v[200:207], v[232:239], v[86:89], v188, v188 op_sel_hi:[0,0,0]
	v_mfma_scale_f32_16x16x128_f8f6f4 v[94:97], v[200:207], v[224:231], v[94:97], v188, v188 op_sel_hi:[0,0,0]
	v_mfma_scale_f32_16x16x128_f8f6f4 v[90:93], v[208:215], v[224:231], v[90:93], v188, v188 op_sel_hi:[0,0,0]
	v_mfma_scale_f32_16x16x128_f8f6f4 v[98:101], v[208:215], v[216:223], v[98:101], v188, v188 op_sel_hi:[0,0,0]
	v_mfma_scale_f32_16x16x128_f8f6f4 v[102:105], v[200:207], v[216:223], v[102:105], v188, v188 op_sel_hi:[0,0,0]
	s_setprio 0
	s_barrier
	s_mov_b32 m0, s33
	v_lshl_add_u64 v[176:177], s[26:27], 0, v[156:157]
	s_add_u32 s62, s26, 0x158000
	ds_read_b128 v[216:219], v190 offset:16384
	ds_read_b128 v[220:223], v190 offset:17408
	ds_read_b128 v[224:227], v190 offset:18432
	ds_read_b128 v[228:231], v190 offset:19456
	ds_read_b128 v[232:235], v190 offset:20480
	ds_read_b128 v[236:239], v190 offset:21504
	ds_read_b128 v[240:243], v190 offset:22528
	ds_read_b128 v[244:247], v190 offset:23552
	global_load_lds_dwordx4 v[176:177], off
	v_lshl_add_u64 v[182:183], s[26:27], 0, v[160:161]
	s_mov_b32 m0, s35
	s_addc_u32 s63, s27, 0
	global_load_lds_dwordx4 v[182:183], off
	v_lshl_add_u64 v[184:185], s[62:63], 0, v[156:157]
	s_mov_b32 m0, s42
	v_lshl_add_u64 v[186:187], s[38:39], 0, v[158:159]
	global_load_lds_dwordx4 v[184:185], off
	v_lshl_add_u64 v[184:185], s[62:63], 0, v[160:161]
	s_mov_b32 m0, s43
	s_nop 0
	global_load_lds_dwordx4 v[184:185], off
	v_lshl_add_u64 v[184:185], s[38:39], 0, v[154:155]
	s_mov_b32 m0, s23
	s_nop 0
	global_load_lds_dwordx4 v[184:185], off
	s_mov_b32 m0, s44
	s_nop 0
	global_load_lds_dwordx4 v[186:187], off
	s_waitcnt vmcnt(8)
	s_waitcnt lgkmcnt(0)
	s_barrier
	s_setprio 1
	s_waitcnt lgkmcnt(0)
	v_mfma_scale_f32_16x16x128_f8f6f4 v[70:73], v[2:9], v[216:223], v[70:73], v188, v188 op_sel_hi:[0,0,0]
	v_mfma_scale_f32_16x16x128_f8f6f4 v[66:69], v[192:199], v[216:223], v[66:69], v188, v188 op_sel_hi:[0,0,0]
	v_mfma_scale_f32_16x16x128_f8f6f4 v[58:61], v[192:199], v[224:231], v[58:61], v188, v188 op_sel_hi:[0,0,0]
	v_mfma_scale_f32_16x16x128_f8f6f4 v[62:65], v[2:9], v[224:231], v[62:65], v188, v188 op_sel_hi:[0,0,0]
	v_mfma_scale_f32_16x16x128_f8f6f4 v[54:57], v[2:9], v[232:239], v[54:57], v188, v188 op_sel_hi:[0,0,0]
	v_mfma_scale_f32_16x16x128_f8f6f4 v[50:53], v[192:199], v[232:239], v[50:53], v188, v188 op_sel_hi:[0,0,0]
	v_mfma_scale_f32_16x16x128_f8f6f4 v[42:45], v[192:199], v[240:247], v[42:45], v188, v188 op_sel_hi:[0,0,0]
	v_mfma_scale_f32_16x16x128_f8f6f4 v[46:49], v[2:9], v[240:247], v[46:49], v188, v188 op_sel_hi:[0,0,0]
	s_setprio 0
	s_setprio 1
	v_mfma_scale_f32_16x16x128_f8f6f4 v[14:17], v[200:207], v[240:247], v[14:17], v188, v188 op_sel_hi:[0,0,0]
	v_mfma_scale_f32_16x16x128_f8f6f4 v[10:13], v[208:215], v[240:247], v[10:13], v188, v188 op_sel_hi:[0,0,0]
	v_mfma_scale_f32_16x16x128_f8f6f4 v[18:21], v[208:215], v[232:239], v[18:21], v188, v188 op_sel_hi:[0,0,0]
	v_mfma_scale_f32_16x16x128_f8f6f4 v[22:25], v[200:207], v[232:239], v[22:25], v188, v188 op_sel_hi:[0,0,0]
	v_mfma_scale_f32_16x16x128_f8f6f4 v[30:33], v[200:207], v[224:231], v[30:33], v188, v188 op_sel_hi:[0,0,0]
	v_mfma_scale_f32_16x16x128_f8f6f4 v[26:29], v[208:215], v[224:231], v[26:29], v188, v188 op_sel_hi:[0,0,0]
	v_mfma_scale_f32_16x16x128_f8f6f4 v[34:37], v[208:215], v[216:223], v[34:37], v188, v188 op_sel_hi:[0,0,0]
	v_mfma_scale_f32_16x16x128_f8f6f4 v[38:41], v[200:207], v[216:223], v[38:41], v188, v188 op_sel_hi:[0,0,0]
	s_setprio 0
	s_barrier
	ds_read_b128 v[192:195], v189 offset:32768
	ds_read_b128 v[196:199], v189 offset:33792
	ds_read_b128 v[200:203], v189 offset:34816
	ds_read_b128 v[204:207], v189 offset:35840
	ds_read_b128 v[2:5], v189 offset:49152
	ds_read_b128 v[6:9], v189 offset:50176
	ds_read_b128 v[208:211], v189 offset:51200
	ds_read_b128 v[212:215], v189 offset:52224
	s_add_u32 s38, s38, 0x158000
	s_addc_u32 s39, s39, 0
	s_mov_b32 m0, s45
	v_lshl_add_u64 v[248:249], s[38:39], 0, v[154:155]
	ds_read_b128 v[216:219], v190 offset:32768
	ds_read_b128 v[220:223], v190 offset:33792
	ds_read_b128 v[224:227], v190 offset:34816
	ds_read_b128 v[228:231], v190 offset:35840
	ds_read_b128 v[232:235], v190 offset:36864
	ds_read_b128 v[236:239], v190 offset:37888
	ds_read_b128 v[240:243], v190 offset:38912
	ds_read_b128 v[244:247], v190 offset:39936
	global_load_lds_dwordx4 v[248:249], off
	v_lshl_add_u64 v[248:249], s[38:39], 0, v[158:159]
	s_mov_b32 m0, s46
	s_nop 0
	global_load_lds_dwordx4 v[248:249], off
	s_waitcnt vmcnt(8)
	s_waitcnt lgkmcnt(0)
	s_barrier
	s_setprio 1
	s_waitcnt lgkmcnt(0)
	v_mfma_scale_f32_16x16x128_f8f6f4 v[134:137], v[192:199], v[216:223], v[134:137], v188, v188 op_sel_hi:[0,0,0]
	v_mfma_scale_f32_16x16x128_f8f6f4 v[130:133], v[200:207], v[216:223], v[130:133], v188, v188 op_sel_hi:[0,0,0]
	v_mfma_scale_f32_16x16x128_f8f6f4 v[122:125], v[200:207], v[224:231], v[122:125], v188, v188 op_sel_hi:[0,0,0]
	v_mfma_scale_f32_16x16x128_f8f6f4 v[126:129], v[192:199], v[224:231], v[126:129], v188, v188 op_sel_hi:[0,0,0]
	v_mfma_scale_f32_16x16x128_f8f6f4 v[118:121], v[192:199], v[232:239], v[118:121], v188, v188 op_sel_hi:[0,0,0]
	v_mfma_scale_f32_16x16x128_f8f6f4 v[114:117], v[200:207], v[232:239], v[114:117], v188, v188 op_sel_hi:[0,0,0]
	v_mfma_scale_f32_16x16x128_f8f6f4 v[106:109], v[200:207], v[240:247], v[106:109], v188, v188 op_sel_hi:[0,0,0]
	v_mfma_scale_f32_16x16x128_f8f6f4 v[110:113], v[192:199], v[240:247], v[110:113], v188, v188 op_sel_hi:[0,0,0]
	s_setprio 0
	s_setprio 1
	v_mfma_scale_f32_16x16x128_f8f6f4 v[78:81], v[2:9], v[240:247], v[78:81], v188, v188 op_sel_hi:[0,0,0]
	v_mfma_scale_f32_16x16x128_f8f6f4 v[74:77], v[208:215], v[240:247], v[74:77], v188, v188 op_sel_hi:[0,0,0]
	v_mfma_scale_f32_16x16x128_f8f6f4 v[82:85], v[208:215], v[232:239], v[82:85], v188, v188 op_sel_hi:[0,0,0]
	v_mfma_scale_f32_16x16x128_f8f6f4 v[86:89], v[2:9], v[232:239], v[86:89], v188, v188 op_sel_hi:[0,0,0]
	v_mfma_scale_f32_16x16x128_f8f6f4 v[94:97], v[2:9], v[224:231], v[94:97], v188, v188 op_sel_hi:[0,0,0]
	v_mfma_scale_f32_16x16x128_f8f6f4 v[90:93], v[208:215], v[224:231], v[90:93], v188, v188 op_sel_hi:[0,0,0]
	v_mfma_scale_f32_16x16x128_f8f6f4 v[98:101], v[208:215], v[216:223], v[98:101], v188, v188 op_sel_hi:[0,0,0]
	v_mfma_scale_f32_16x16x128_f8f6f4 v[102:105], v[2:9], v[216:223], v[102:105], v188, v188 op_sel_hi:[0,0,0]
	s_setprio 0
	s_barrier
	s_mov_b32 m0, s52
	v_lshl_add_u64 v[176:177], v[176:177], 0, s[14:15]
	s_add_u32 s26, s26, 0x158080
	ds_read_b128 v[216:219], v190 offset:49152
	ds_read_b128 v[220:223], v190 offset:50176
	ds_read_b128 v[224:227], v190 offset:51200
	ds_read_b128 v[228:231], v190 offset:52224
	ds_read_b128 v[232:235], v190 offset:53248
	ds_read_b128 v[236:239], v190 offset:54272
	ds_read_b128 v[240:243], v190 offset:55296
	ds_read_b128 v[244:247], v190 offset:56320
	global_load_lds_dwordx4 v[176:177], off
	v_lshl_add_u64 v[176:177], v[182:183], 0, s[14:15]
	s_mov_b32 m0, s53
	s_addc_u32 s27, s27, 0
	global_load_lds_dwordx4 v[176:177], off
	v_lshl_add_u64 v[176:177], s[26:27], 0, v[156:157]
	s_mov_b32 m0, s56
	s_nop 0
	global_load_lds_dwordx4 v[176:177], off
	v_lshl_add_u64 v[176:177], s[26:27], 0, v[160:161]
	s_mov_b32 m0, s57
	s_nop 0
	global_load_lds_dwordx4 v[176:177], off
	v_lshl_add_u64 v[176:177], v[184:185], 0, s[14:15]
	s_mov_b32 m0, s54
	s_nop 0
	global_load_lds_dwordx4 v[176:177], off
	v_lshl_add_u64 v[176:177], v[186:187], 0, s[14:15]
	s_mov_b32 m0, s55
	s_nop 0
	global_load_lds_dwordx4 v[176:177], off
	s_waitcnt vmcnt(8)
	s_waitcnt lgkmcnt(0)
	s_barrier
	s_setprio 1
	s_waitcnt lgkmcnt(0)
	v_mfma_scale_f32_16x16x128_f8f6f4 v[70:73], v[192:199], v[216:223], v[70:73], v188, v188 op_sel_hi:[0,0,0]
	v_mfma_scale_f32_16x16x128_f8f6f4 v[66:69], v[200:207], v[216:223], v[66:69], v188, v188 op_sel_hi:[0,0,0]
	v_mfma_scale_f32_16x16x128_f8f6f4 v[58:61], v[200:207], v[224:231], v[58:61], v188, v188 op_sel_hi:[0,0,0]
	v_mfma_scale_f32_16x16x128_f8f6f4 v[62:65], v[192:199], v[224:231], v[62:65], v188, v188 op_sel_hi:[0,0,0]
	v_mfma_scale_f32_16x16x128_f8f6f4 v[54:57], v[192:199], v[232:239], v[54:57], v188, v188 op_sel_hi:[0,0,0]
	v_mfma_scale_f32_16x16x128_f8f6f4 v[50:53], v[200:207], v[232:239], v[50:53], v188, v188 op_sel_hi:[0,0,0]
	v_mfma_scale_f32_16x16x128_f8f6f4 v[42:45], v[200:207], v[240:247], v[42:45], v188, v188 op_sel_hi:[0,0,0]
	v_mfma_scale_f32_16x16x128_f8f6f4 v[46:49], v[192:199], v[240:247], v[46:49], v188, v188 op_sel_hi:[0,0,0]
	s_setprio 0
	s_setprio 1
	v_mfma_scale_f32_16x16x128_f8f6f4 v[14:17], v[2:9], v[240:247], v[14:17], v188, v188 op_sel_hi:[0,0,0]
	v_mfma_scale_f32_16x16x128_f8f6f4 v[10:13], v[208:215], v[240:247], v[10:13], v188, v188 op_sel_hi:[0,0,0]
	v_mfma_scale_f32_16x16x128_f8f6f4 v[18:21], v[208:215], v[232:239], v[18:21], v188, v188 op_sel_hi:[0,0,0]
	v_mfma_scale_f32_16x16x128_f8f6f4 v[22:25], v[2:9], v[232:239], v[22:25], v188, v188 op_sel_hi:[0,0,0]
	v_mfma_scale_f32_16x16x128_f8f6f4 v[30:33], v[2:9], v[224:231], v[30:33], v188, v188 op_sel_hi:[0,0,0]
	v_mfma_scale_f32_16x16x128_f8f6f4 v[26:29], v[208:215], v[224:231], v[26:29], v188, v188 op_sel_hi:[0,0,0]
	v_mfma_scale_f32_16x16x128_f8f6f4 v[34:37], v[208:215], v[216:223], v[34:37], v188, v188 op_sel_hi:[0,0,0]
	v_mfma_scale_f32_16x16x128_f8f6f4 v[38:41], v[2:9], v[216:223], v[38:41], v188, v188 op_sel_hi:[0,0,0]
	s_setprio 0
	s_barrier
	s_add_i32 s26, s84, 2
	s_add_u32 s36, s36, 0x100
	s_addc_u32 s37, s37, 0
	s_add_u32 s40, s40, 0x100
	s_addc_u32 s41, s41, 0
	s_cmp_ge_i32 s84, s82
	s_cbranch_scc1 .LBB0_1036
	s_mov_b32 s84, s26
	s_cmp_eq_u32 s82, s84
	s_cselect_b64 s[26:27], -1, 0
	s_cmp_lg_u32 s82, s84
	s_cbranch_scc0 .LBB0_1033
	s_branch .LBB0_1034

	.amdhsa_kernel _Z6mk_fwd4Args
		.amdhsa_group_segment_fixed_size 0
		.amdhsa_private_segment_fixed_size 0
		.amdhsa_kernarg_size 448
		.amdhsa_user_sgpr_count 2
		.amdhsa_user_sgpr_dispatch_ptr 0
		.amdhsa_user_sgpr_queue_ptr 0
		.amdhsa_user_sgpr_kernarg_segment_ptr 1
		.amdhsa_user_sgpr_dispatch_id 0
		.amdhsa_user_sgpr_kernarg_preload_length 0
		.amdhsa_user_sgpr_kernarg_preload_offset 0
		.amdhsa_user_sgpr_private_segment_size 0
		.amdhsa_uses_dynamic_stack 0
		.amdhsa_enable_private_segment 0
		.amdhsa_system_sgpr_workgroup_id_x 1
		.amdhsa_system_sgpr_workgroup_id_y 0
		.amdhsa_system_sgpr_workgroup_id_z 0
		.amdhsa_system_sgpr_workgroup_info 0
		.amdhsa_system_vgpr_workitem_id 0
		.amdhsa_next_free_vgpr 255
		.amdhsa_next_free_sgpr 98
		.amdhsa_accum_offset 256
		.amdhsa_reserve_vcc 1
		.amdhsa_float_round_mode_32 0
		.amdhsa_float_round_mode_16_64 0
		.amdhsa_float_denorm_mode_32 3
		.amdhsa_float_denorm_mode_16_64 3
		.amdhsa_dx10_clamp 1
		.amdhsa_ieee_mode 1
		.amdhsa_fp16_overflow 0
		.amdhsa_tg_split 0
		.amdhsa_exception_fp_ieee_invalid_op 0
		.amdhsa_exception_fp_denorm_src 0
		.amdhsa_exception_fp_ieee_div_zero 0
		.amdhsa_exception_fp_ieee_overflow 0
		.amdhsa_exception_fp_ieee_underflow 0
		.amdhsa_exception_fp_ieee_inexact 0
		.amdhsa_exception_int_div_zero 0
	.end_amdhsa_kernel

amdhsa.kernels:
  - .agpr_count:     0
    .args:
      - .offset:         0
        .size:           192
        .value_kind:     by_value
      - .offset:         192
        .size:           4
        .value_kind:     hidden_block_count_x
      - .offset:         196
        .size:           4
        .value_kind:     hidden_block_count_y
      - .offset:         200
        .size:           4
        .value_kind:     hidden_block_count_z
      - .offset:         204
        .size:           2
        .value_kind:     hidden_group_size_x
      - .offset:         206
        .size:           2
        .value_kind:     hidden_group_size_y
      - .offset:         208
        .size:           2
        .value_kind:     hidden_group_size_z
      - .offset:         210
        .size:           2
        .value_kind:     hidden_remainder_x
      - .offset:         212
        .size:           2
        .value_kind:     hidden_remainder_y
      - .offset:         214
        .size:           2
        .value_kind:     hidden_remainder_z
      - .offset:         232
        .size:           8
        .value_kind:     hidden_global_offset_x
      - .offset:         240
        .size:           8
        .value_kind:     hidden_global_offset_y
      - .offset:         248
        .size:           8
        .value_kind:     hidden_global_offset_z
      - .offset:         256
        .size:           2
        .value_kind:     hidden_grid_dims
      - .offset:         312
        .size:           4
        .value_kind:     hidden_dynamic_lds_size
    .group_segment_fixed_size: 0
    .kernarg_segment_align: 8
    .kernarg_segment_size: 448
    .language:       OpenCL C
    .language_version:
      - 2
      - 0
    .max_flat_workgroup_size: 512
    .name:           _Z6mk_fwd4Args
    .private_segment_fixed_size: 0
    .sgpr_count:     104
    .sgpr_spill_count: 20
    .symbol:         _Z6mk_fwd4Args.kd
    .uniform_work_group_size: 1
    .uses_dynamic_stack: false
    .vgpr_count:     255
    .vgpr_spill_count: 0
    .wavefront_size: 64
